# v9: P7 sample-attention score reduction rewritten with packed f32 FMAs and a DPP/permlane-swap transposing tree (no LDS shuffles)
# speedup vs baseline: 1.0164x; 1.0164x over previous
; DI void attn_sample_item(const Params& p, int item, ldsp lds, int tid_) {
;     ...
;   for (int t = 0; t < 4; ++t) { f32x4 a = {0.f, 0.f, 0.f, 0.f}; const float* pp = (const float*)(p.ws + B_PART) + (size_t)(b * 4 + t) * 1024 + h * 256 + lane * 4;
; #pragma unroll
;     for (int kp = 0; kp < 4; ++kp) a += *(const f32x4*)(pp + (size_t)kp * 512 * 1024);
;     q[t][0] = a[0] * 0.0625f; q[t][1] = a[1] * 0.0625f; q[t][2] = a[2] * 0.0625f; q[t][3] = a[3] * 0.0625f; }
;   const bool b0 = lane & 1, b1 = lane & 2;
;   f32x4 kvA[16], kvB[16];
; #pragma unroll
;   for (int j = 0; j < 16; ++j) kvA[j] = __builtin_nontemporal_load((const f32x4*)(ck + (size_t)(wid * 32 + j) * 1024 + lane * 4));
.LBB0_1604:
	s_ashr_i32 s4, s40, 2
	s_ashr_i32 s5, s4, 31
	s_lshl_b64 s[4:5], s[4:5], 18
	s_and_b32 s26, s0, 0x300
	v_mov_b32_e32 v222, v212
	s_or_b32 s4, s4, s26
	s_and_b32 s28, s40, -4
	s_lshl_b32 s6, s26, 2
	s_add_u32 s6, s36, s6
	v_and_b32_e32 v223, 63, v222
	s_addc_u32 s7, s37, 0
	v_lshlrev_b32_e32 v144, 4, v223
	s_ashr_i32 s29, s28, 31
	v_lshl_add_u64 v[48:49], s[6:7], 0, v[144:145]
	s_lshl_b64 s[6:7], s[28:29], 12
	v_lshl_add_u64 v[8:9], v[48:49], 0, s[6:7]
	v_add_co_u32_e32 v4, vcc, s3, v8
	s_or_b32 s6, s28, 1
	s_nop 0
	v_addc_co_u32_e32 v5, vcc, 0, v9, vcc
	v_add_co_u32_e32 v10, vcc, s33, v8
	s_ashr_i32 s7, s6, 31
	s_nop 0
	v_addc_co_u32_e32 v11, vcc, 0, v9, vcc
	v_add_co_u32_e32 v12, vcc, s38, v8
	s_lshl_b64 s[6:7], s[6:7], 12
	s_nop 0
	v_addc_co_u32_e32 v13, vcc, 0, v9, vcc
	v_lshl_add_u64 v[24:25], v[48:49], 0, s[6:7]
	v_add_co_u32_e32 v20, vcc, s3, v24
	s_or_b32 s6, s28, 2
	s_nop 0
	v_addc_co_u32_e32 v21, vcc, 0, v25, vcc
	v_add_co_u32_e32 v26, vcc, s33, v24
	s_ashr_i32 s7, s6, 31
	s_nop 0
	v_addc_co_u32_e32 v27, vcc, 0, v25, vcc
	v_add_co_u32_e32 v28, vcc, s38, v24
	s_lshl_b64 s[6:7], s[6:7], 12
	global_load_dwordx4 v[0:3], v[8:9], off
	s_nop 0
	global_load_dwordx4 v[4:7], v[4:5], off
	v_addc_co_u32_e32 v29, vcc, 0, v25, vcc
	v_lshl_add_u64 v[44:45], v[48:49], 0, s[6:7]
	global_load_dwordx4 v[8:11], v[10:11], off
	s_nop 0
	global_load_dwordx4 v[12:15], v[12:13], off
	s_nop 0
	global_load_dwordx4 v[16:19], v[24:25], off
	s_nop 0
	global_load_dwordx4 v[20:23], v[20:21], off
	v_add_co_u32_e32 v36, vcc, s3, v44
	global_load_dwordx4 v[24:27], v[26:27], off
	s_nop 0
	global_load_dwordx4 v[28:31], v[28:29], off
	v_addc_co_u32_e32 v37, vcc, 0, v45, vcc
	v_add_co_u32_e32 v40, vcc, s33, v44
	global_load_dwordx4 v[32:35], v[44:45], off
	s_nop 0
	global_load_dwordx4 v[36:39], v[36:37], off
	v_addc_co_u32_e32 v41, vcc, 0, v45, vcc
	v_add_co_u32_e32 v44, vcc, s38, v44
	global_load_dwordx4 v[40:43], v[40:41], off
	s_nop 0
	v_addc_co_u32_e32 v45, vcc, 0, v45, vcc
	global_load_dwordx4 v[44:47], v[44:45], off
	s_or_b32 s6, s40, 3
	s_ashr_i32 s7, s6, 31
	s_lshl_b64 s[6:7], s[6:7], 12
	s_lshl_b64 s[30:31], s[4:5], 2
	s_add_u32 s4, s12, s30
	s_addc_u32 s5, s13, s31
	s_waitcnt vmcnt(11)
	v_pk_add_f32 v[2:3], v[2:3], 0 op_sel_hi:[1,0]
	v_pk_add_f32 v[0:1], v[0:1], 0 op_sel_hi:[1,0]
	s_waitcnt vmcnt(10)
	v_pk_add_f32 v[2:3], v[2:3], v[6:7]
	v_pk_add_f32 v[0:1], v[0:1], v[4:5]
	s_waitcnt vmcnt(9)
	v_pk_add_f32 v[2:3], v[2:3], v[10:11]
	s_waitcnt vmcnt(7)
	v_pk_add_f32 v[4:5], v[18:19], 0 op_sel_hi:[1,0]
	v_pk_add_f32 v[6:7], v[16:17], 0 op_sel_hi:[1,0]
	v_pk_add_f32 v[0:1], v[0:1], v[8:9]
	s_waitcnt vmcnt(6)
	v_pk_add_f32 v[4:5], v[4:5], v[22:23]
	v_pk_add_f32 v[6:7], v[6:7], v[20:21]
	v_pk_add_f32 v[2:3], v[2:3], v[14:15]
	v_pk_add_f32 v[0:1], v[0:1], v[12:13]
	s_waitcnt vmcnt(5)
	v_pk_add_f32 v[4:5], v[4:5], v[26:27]
	v_pk_add_f32 v[6:7], v[6:7], v[24:25]
	v_mul_f32_e32 v228, 0x3d800000, v0
	v_mul_f32_e32 v231, 0x3d800000, v1
	v_mul_f32_e32 v229, 0x3d800000, v2
	v_mul_f32_e32 v225, 0x3d800000, v3
	s_waitcnt vmcnt(4)
	v_pk_add_f32 v[0:1], v[4:5], v[30:31]
	v_pk_add_f32 v[2:3], v[6:7], v[28:29]
	v_mul_f32_e32 v227, 0x3d800000, v0
	v_mul_f32_e32 v226, 0x3d800000, v2
	v_mul_f32_e32 v230, 0x3d800000, v3
	v_mul_f32_e32 v224, 0x3d800000, v1
	s_waitcnt vmcnt(3)
	v_pk_add_f32 v[0:1], v[34:35], 0 op_sel_hi:[1,0]
	v_pk_add_f32 v[2:3], v[32:33], 0 op_sel_hi:[1,0]
	s_waitcnt vmcnt(2)
	v_pk_add_f32 v[0:1], v[0:1], v[38:39]
	v_pk_add_f32 v[2:3], v[2:3], v[36:37]
	s_waitcnt vmcnt(1)
	v_pk_add_f32 v[0:1], v[0:1], v[42:43]
	v_pk_add_f32 v[2:3], v[2:3], v[40:41]
	s_waitcnt vmcnt(0)
	v_pk_add_f32 v[210:211], v[0:1], v[46:47]
	v_pk_add_f32 v[0:1], v[2:3], v[44:45]
	v_mul_f32_e32 v233, 0x3d800000, v210
	v_mul_f32_e32 v232, 0x3d800000, v0
	v_mul_f32_e32 v234, 0x3d800000, v1
	v_lshl_add_u64 v[0:1], v[48:49], 0, s[6:7]
	v_add_co_u32_e32 v2, vcc, s3, v0
	v_ashrrev_i32_e32 v210, 6, v222
	s_nop 0
	v_addc_co_u32_e32 v3, vcc, 0, v1, vcc
	global_load_dwordx4 v[128:131], v[0:1], off
	global_load_dwordx4 v[132:135], v[2:3], off
	v_add_co_u32_e32 v2, vcc, s33, v0
	v_mul_f32_e32 v211, 0x3d800000, v211
	s_nop 0
	v_addc_co_u32_e32 v3, vcc, 0, v1, vcc
	v_add_co_u32_e32 v0, vcc, s38, v0
	v_cmp_lt_i32_e64 s[6:7], v218, v216
	s_nop 0
	v_addc_co_u32_e32 v1, vcc, 0, v1, vcc
	global_load_dwordx4 v[136:139], v[2:3], off
	global_load_dwordx4 v[140:143], v[0:1], off
	v_lshlrev_b32_e32 v0, 5, v210
	v_ashrrev_i32_e32 v1, 31, v0
	v_or_b32_e32 v6, 1, v0
	v_lshl_add_u64 v[2:3], s[4:5], 0, v[144:145]
	v_lshlrev_b64 v[162:163], 12, v[0:1]
	v_ashrrev_i32_e32 v7, 31, v6
	v_lshl_add_u64 v[4:5], v[2:3], 0, v[162:163]
	v_lshlrev_b64 v[166:167], 12, v[6:7]
	v_lshl_add_u64 v[6:7], v[2:3], 0, v[166:167]
	global_load_dwordx4 v[124:127], v[4:5], off nt
	global_load_dwordx4 v[120:123], v[6:7], off nt
	v_or_b32_e32 v4, 2, v0
	v_ashrrev_i32_e32 v5, 31, v4
	v_or_b32_e32 v6, 3, v0
	v_lshlrev_b64 v[168:169], 12, v[4:5]
	v_ashrrev_i32_e32 v7, 31, v6
	v_lshl_add_u64 v[4:5], v[2:3], 0, v[168:169]
	v_lshlrev_b64 v[172:173], 12, v[6:7]
	v_lshl_add_u64 v[6:7], v[2:3], 0, v[172:173]
	global_load_dwordx4 v[116:119], v[4:5], off nt
	global_load_dwordx4 v[112:115], v[6:7], off nt
	v_or_b32_e32 v4, 4, v0
	v_ashrrev_i32_e32 v5, 31, v4
	v_or_b32_e32 v6, 5, v0
	v_lshlrev_b64 v[176:177], 12, v[4:5]
	v_ashrrev_i32_e32 v7, 31, v6
	v_lshl_add_u64 v[4:5], v[2:3], 0, v[176:177]
	v_lshlrev_b64 v[180:181], 12, v[6:7]
	v_lshl_add_u64 v[6:7], v[2:3], 0, v[180:181]
	global_load_dwordx4 v[108:111], v[4:5], off nt
	global_load_dwordx4 v[104:107], v[6:7], off nt
	v_or_b32_e32 v4, 6, v0
	v_ashrrev_i32_e32 v5, 31, v4
	v_or_b32_e32 v6, 7, v0
; DI void attn_sample_item(const Params& p, int item, ldsp lds, int tid_) {
;     ...
;   for (int t = 0; t < 4; ++t) { f32x4 a = {0.f, 0.f, 0.f, 0.f}; const float* pp = (const float*)(p.ws + B_PART) + (size_t)(b * 4 + t) * 1024 + h * 256 + lane * 4;
; #pragma unroll
;     for (int kp = 0; kp < 4; ++kp) a += *(const f32x4*)(pp + (size_t)kp * 512 * 1024);
;     q[t][0] = a[0] * 0.0625f; q[t][1] = a[1] * 0.0625f; q[t][2] = a[2] * 0.0625f; q[t][3] = a[3] * 0.0625f; }
;     ...
;   for (int j = 0; j < 16; ++j) kvA[j] = __builtin_nontemporal_load((const f32x4*)(ck + (size_t)(wid * 32 + j) * 1024 + lane * 4));
; #pragma unroll
;   for (int j = 0; j < 16; ++j) kvB[j] = __builtin_nontemporal_load((const f32x4*)(ck + (size_t)(wid * 32 + 16 + j) * 1024 + lane * 4));
	v_lshlrev_b64 v[182:183], 12, v[4:5]
	v_ashrrev_i32_e32 v7, 31, v6
	v_lshl_add_u64 v[4:5], v[2:3], 0, v[182:183]
	v_lshlrev_b64 v[186:187], 12, v[6:7]
	v_lshl_add_u64 v[6:7], v[2:3], 0, v[186:187]
	global_load_dwordx4 v[100:103], v[4:5], off nt
	global_load_dwordx4 v[96:99], v[6:7], off nt
	v_or_b32_e32 v4, 8, v0
	v_ashrrev_i32_e32 v5, 31, v4
	v_or_b32_e32 v6, 9, v0
	v_lshlrev_b64 v[190:191], 12, v[4:5]
	v_ashrrev_i32_e32 v7, 31, v6
	v_lshl_add_u64 v[4:5], v[2:3], 0, v[190:191]
	v_lshlrev_b64 v[194:195], 12, v[6:7]
	v_lshl_add_u64 v[6:7], v[2:3], 0, v[194:195]
	global_load_dwordx4 v[92:95], v[4:5], off nt
	global_load_dwordx4 v[88:91], v[6:7], off nt
	v_or_b32_e32 v4, 10, v0
	v_ashrrev_i32_e32 v5, 31, v4
	v_or_b32_e32 v6, 11, v0
	v_lshlrev_b64 v[198:199], 12, v[4:5]
	v_ashrrev_i32_e32 v7, 31, v6
	v_lshl_add_u64 v[4:5], v[2:3], 0, v[198:199]
	v_lshlrev_b64 v[200:201], 12, v[6:7]
	v_lshl_add_u64 v[6:7], v[2:3], 0, v[200:201]
	global_load_dwordx4 v[84:87], v[4:5], off nt
	global_load_dwordx4 v[80:83], v[6:7], off nt
	v_or_b32_e32 v4, 12, v0
	v_ashrrev_i32_e32 v5, 31, v4
	v_or_b32_e32 v6, 13, v0
	v_lshlrev_b64 v[202:203], 12, v[4:5]
	v_ashrrev_i32_e32 v7, 31, v6
	v_lshl_add_u64 v[4:5], v[2:3], 0, v[202:203]
	v_lshlrev_b64 v[204:205], 12, v[6:7]
	v_lshl_add_u64 v[6:7], v[2:3], 0, v[204:205]
	global_load_dwordx4 v[76:79], v[4:5], off nt
	global_load_dwordx4 v[72:75], v[6:7], off nt
	v_or_b32_e32 v4, 14, v0
	v_ashrrev_i32_e32 v5, 31, v4
	v_or_b32_e32 v6, 15, v0
	v_lshlrev_b64 v[206:207], 12, v[4:5]
	v_ashrrev_i32_e32 v7, 31, v6
	v_lshl_add_u64 v[4:5], v[2:3], 0, v[206:207]
	v_lshlrev_b64 v[208:209], 12, v[6:7]
	v_lshl_add_u64 v[6:7], v[2:3], 0, v[208:209]
	global_load_dwordx4 v[68:71], v[4:5], off nt
	global_load_dwordx4 v[64:67], v[6:7], off nt
	v_or_b32_e32 v4, 16, v0
	v_ashrrev_i32_e32 v5, 31, v4
	v_or_b32_e32 v6, 17, v0
	v_lshlrev_b64 v[146:147], 12, v[4:5]
	v_ashrrev_i32_e32 v7, 31, v6
	v_lshl_add_u64 v[4:5], v[2:3], 0, v[146:147]
	v_lshlrev_b64 v[148:149], 12, v[6:7]
	v_lshl_add_u64 v[6:7], v[2:3], 0, v[148:149]
	global_load_dwordx4 v[60:63], v[4:5], off nt
	global_load_dwordx4 v[56:59], v[6:7], off nt
	v_or_b32_e32 v4, 18, v0
	v_ashrrev_i32_e32 v5, 31, v4
	v_or_b32_e32 v6, 19, v0
	v_lshlrev_b64 v[150:151], 12, v[4:5]
	v_ashrrev_i32_e32 v7, 31, v6
	v_lshl_add_u64 v[4:5], v[2:3], 0, v[150:151]
	v_lshlrev_b64 v[152:153], 12, v[6:7]
	v_lshl_add_u64 v[6:7], v[2:3], 0, v[152:153]
	global_load_dwordx4 v[52:55], v[4:5], off nt
	global_load_dwordx4 v[48:51], v[6:7], off nt
	v_or_b32_e32 v4, 20, v0
	v_ashrrev_i32_e32 v5, 31, v4
	v_or_b32_e32 v6, 21, v0
	v_lshlrev_b64 v[154:155], 12, v[4:5]
	v_ashrrev_i32_e32 v7, 31, v6
	v_lshl_add_u64 v[4:5], v[2:3], 0, v[154:155]
	v_lshlrev_b64 v[156:157], 12, v[6:7]
	v_lshl_add_u64 v[6:7], v[2:3], 0, v[156:157]
	global_load_dwordx4 v[44:47], v[4:5], off nt
	global_load_dwordx4 v[40:43], v[6:7], off nt
	v_or_b32_e32 v4, 22, v0
	v_ashrrev_i32_e32 v5, 31, v4
	v_or_b32_e32 v6, 23, v0
	v_lshlrev_b64 v[158:159], 12, v[4:5]
	v_ashrrev_i32_e32 v7, 31, v6
	v_lshl_add_u64 v[4:5], v[2:3], 0, v[158:159]
	v_lshlrev_b64 v[160:161], 12, v[6:7]
	v_lshl_add_u64 v[6:7], v[2:3], 0, v[160:161]
	global_load_dwordx4 v[36:39], v[4:5], off nt
	global_load_dwordx4 v[32:35], v[6:7], off nt
	v_or_b32_e32 v4, 24, v0
	v_ashrrev_i32_e32 v5, 31, v4
	v_or_b32_e32 v6, 25, v0
	v_lshlrev_b64 v[164:165], 12, v[4:5]
	v_ashrrev_i32_e32 v7, 31, v6
	v_lshl_add_u64 v[4:5], v[2:3], 0, v[164:165]
	v_lshlrev_b64 v[170:171], 12, v[6:7]
	v_lshl_add_u64 v[6:7], v[2:3], 0, v[170:171]
	global_load_dwordx4 v[28:31], v[4:5], off nt
	global_load_dwordx4 v[24:27], v[6:7], off nt
	v_or_b32_e32 v4, 26, v0
	v_ashrrev_i32_e32 v5, 31, v4
	v_or_b32_e32 v6, 27, v0
	v_lshlrev_b64 v[174:175], 12, v[4:5]
	v_ashrrev_i32_e32 v7, 31, v6
	v_lshl_add_u64 v[4:5], v[2:3], 0, v[174:175]
	v_lshlrev_b64 v[178:179], 12, v[6:7]
	v_lshl_add_u64 v[6:7], v[2:3], 0, v[178:179]
	global_load_dwordx4 v[20:23], v[4:5], off nt
	global_load_dwordx4 v[16:19], v[6:7], off nt
	v_or_b32_e32 v4, 28, v0
	v_ashrrev_i32_e32 v5, 31, v4
	v_or_b32_e32 v6, 29, v0
	v_lshlrev_b64 v[184:185], 12, v[4:5]
	v_ashrrev_i32_e32 v7, 31, v6
	v_lshl_add_u64 v[4:5], v[2:3], 0, v[184:185]
	v_lshlrev_b64 v[188:189], 12, v[6:7]
	v_lshl_add_u64 v[6:7], v[2:3], 0, v[188:189]
	global_load_dwordx4 v[12:15], v[4:5], off nt
	global_load_dwordx4 v[8:11], v[6:7], off nt
	v_or_b32_e32 v4, 30, v0
	v_or_b32_e32 v0, 31, v0
	v_ashrrev_i32_e32 v5, 31, v4
	v_ashrrev_i32_e32 v1, 31, v0
	v_lshlrev_b64 v[192:193], 12, v[4:5]
	v_lshlrev_b64 v[196:197], 12, v[0:1]
	v_lshl_add_u64 v[4:5], v[2:3], 0, v[192:193]
	v_lshl_add_u64 v[0:1], v[2:3], 0, v[196:197]
	global_load_dwordx4 v[4:7], v[4:5], off nt
	s_nop 0
	global_load_dwordx4 v[0:3], v[0:1], off nt
	s_waitcnt vmcnt(35)
	v_pk_add_f32 v[128:129], v[128:129], 0 op_sel_hi:[1,0]
	v_pk_add_f32 v[130:131], v[130:131], 0 op_sel_hi:[1,0]
	s_waitcnt vmcnt(34)
	v_pk_add_f32 v[128:129], v[128:129], v[132:133]
	v_pk_add_f32 v[130:131], v[130:131], v[134:135]
	s_waitcnt vmcnt(33)
	v_pk_add_f32 v[128:129], v[128:129], v[136:137]
	v_pk_add_f32 v[130:131], v[130:131], v[138:139]
	s_waitcnt vmcnt(32)
; DI void attn_sample_item(const Params& p, int item, ldsp lds, int tid_) {
;     ...
;   const bool b0 = lane & 1, b1 = lane & 2;
	v_pk_add_f32 v[128:129], v[128:129], v[140:141]
	v_pk_add_f32 v[130:131], v[130:131], v[142:143]
	v_mul_f32_e32 v138, 0x3d800000, v129
	v_mul_f32_e32 v135, 0x3d800000, v128
	v_mul_f32_e32 v134, 0x3d800000, v131
	v_mul_f32_e32 v137, 0x3d800000, v130
	v_lshlrev_b32_e32 v128, 2, v215
	v_lshlrev_b32_e32 v129, 2, v217
	v_lshlrev_b32_e32 v130, 2, v218
	v_lshlrev_b32_e32 v131, 2, v219
	v_lshlrev_b32_e32 v132, 2, v220
	v_lshlrev_b32_e32 v133, 2, v221
	v_lshl_add_u32 v136, v210, 7, 16
	v_and_b32_e32 v139, 3, v223
	v_bfrev_b32_e32 v139, v139
	v_lshrrev_b32_e32 v139, 20, v139
	v_and_b32_e32 v235, -4, v223
	v_add3_u32 v235, v136, v139, v235
	v_mov_b32_e32 v236, v228
	v_mov_b32_e32 v237, v226
	v_mov_b32_e32 v238, v231
	v_mov_b32_e32 v239, v230
	v_mov_b32_e32 v240, v229
	v_mov_b32_e32 v241, v227
	v_mov_b32_e32 v242, v225
	v_mov_b32_e32 v243, v224
	v_mov_b32_e32 v244, v232
	v_mov_b32_e32 v245, v135
	v_mov_b32_e32 v246, v234
	v_mov_b32_e32 v247, v138
	v_mov_b32_e32 v248, v233
	v_mov_b32_e32 v249, v137
	v_mov_b32_e32 v250, v211
	v_mov_b32_e32 v251, v134
	s_mov_b32 vcc_lo, 0x55555555
	s_mov_b32 vcc_hi, 0x55555555
	s_mov_b32 s4, 0x33333333
	s_mov_b32 s5, 0x33333333
	s_mov_b32 s6, 0x0f0f0f0f
	s_mov_b32 s7, 0x0f0f0f0f
	s_mov_b32 s64, 0x00ff00ff
	s_mov_b32 s65, 0x00ff00ff
	s_waitcnt vmcnt(31)
	v_pk_mul_f32 v[252:253], v[236:237], v[124:125] op_sel_hi:[1,0]
	v_pk_mul_f32 v[254:255], v[244:245], v[124:125] op_sel_hi:[1,0]
	v_pk_fma_f32 v[252:253], v[238:239], v[124:125], v[252:253] op_sel:[0,1,0]
	v_pk_fma_f32 v[254:255], v[246:247], v[124:125], v[254:255] op_sel:[0,1,0]
	v_pk_fma_f32 v[252:253], v[240:241], v[126:127], v[252:253] op_sel_hi:[1,0,1]
	v_pk_fma_f32 v[254:255], v[248:249], v[126:127], v[254:255] op_sel_hi:[1,0,1]
	v_pk_fma_f32 v[252:253], v[242:243], v[126:127], v[252:253] op_sel:[0,1,0]
	v_pk_fma_f32 v[254:255], v[250:251], v[126:127], v[254:255] op_sel:[0,1,0]
	s_waitcnt vmcnt(30)
	v_pk_mul_f32 v[140:141], v[236:237], v[120:121] op_sel_hi:[1,0]
	v_pk_mul_f32 v[142:143], v[244:245], v[120:121] op_sel_hi:[1,0]
	v_pk_fma_f32 v[140:141], v[238:239], v[120:121], v[140:141] op_sel:[0,1,0]
	v_pk_fma_f32 v[142:143], v[246:247], v[120:121], v[142:143] op_sel:[0,1,0]
	v_pk_fma_f32 v[140:141], v[240:241], v[122:123], v[140:141] op_sel_hi:[1,0,1]
	v_pk_fma_f32 v[142:143], v[248:249], v[122:123], v[142:143] op_sel_hi:[1,0,1]
	v_pk_fma_f32 v[140:141], v[242:243], v[122:123], v[140:141] op_sel:[0,1,0]
	v_pk_fma_f32 v[142:143], v[250:251], v[122:123], v[142:143] op_sel:[0,1,0]
	v_add_f32_dpp v124, v252, v252 quad_perm:[1,0,3,2] row_mask:0xf bank_mask:0xf
	v_add_f32_dpp v125, v253, v253 quad_perm:[1,0,3,2] row_mask:0xf bank_mask:0xf
	v_add_f32_dpp v126, v254, v254 quad_perm:[1,0,3,2] row_mask:0xf bank_mask:0xf
	v_add_f32_dpp v127, v255, v255 quad_perm:[1,0,3,2] row_mask:0xf bank_mask:0xf
	v_cndmask_b32_e32 v124, v126, v124, vcc
	v_cndmask_b32_e32 v125, v127, v125, vcc
	s_waitcnt vmcnt(29)
	v_pk_mul_f32 v[252:253], v[236:237], v[116:117] op_sel_hi:[1,0]
	v_pk_mul_f32 v[254:255], v[244:245], v[116:117] op_sel_hi:[1,0]
	v_pk_fma_f32 v[252:253], v[238:239], v[116:117], v[252:253] op_sel:[0,1,0]
	v_pk_fma_f32 v[254:255], v[246:247], v[116:117], v[254:255] op_sel:[0,1,0]
	v_pk_fma_f32 v[252:253], v[240:241], v[118:119], v[252:253] op_sel_hi:[1,0,1]
	v_pk_fma_f32 v[254:255], v[248:249], v[118:119], v[254:255] op_sel_hi:[1,0,1]
	v_pk_fma_f32 v[252:253], v[242:243], v[118:119], v[252:253] op_sel:[0,1,0]
	v_pk_fma_f32 v[254:255], v[250:251], v[118:119], v[254:255] op_sel:[0,1,0]
	v_add_f32_dpp v120, v140, v140 quad_perm:[1,0,3,2] row_mask:0xf bank_mask:0xf
	v_add_f32_dpp v121, v141, v141 quad_perm:[1,0,3,2] row_mask:0xf bank_mask:0xf
	v_add_f32_dpp v122, v142, v142 quad_perm:[1,0,3,2] row_mask:0xf bank_mask:0xf
	v_add_f32_dpp v123, v143, v143 quad_perm:[1,0,3,2] row_mask:0xf bank_mask:0xf
	v_cndmask_b32_e32 v120, v122, v120, vcc
	v_cndmask_b32_e32 v121, v123, v121, vcc
	v_add_f32_dpp v126, v124, v124 quad_perm:[2,3,0,1] row_mask:0xf bank_mask:0xf
	v_add_f32_dpp v127, v125, v125 quad_perm:[2,3,0,1] row_mask:0xf bank_mask:0xf
	v_cndmask_b32_e64 v124, v127, v126, s[4:5]
	s_waitcnt vmcnt(28)
	v_pk_mul_f32 v[140:141], v[236:237], v[112:113] op_sel_hi:[1,0]
	v_pk_mul_f32 v[142:143], v[244:245], v[112:113] op_sel_hi:[1,0]
	v_pk_fma_f32 v[140:141], v[238:239], v[112:113], v[140:141] op_sel:[0,1,0]
	v_pk_fma_f32 v[142:143], v[246:247], v[112:113], v[142:143] op_sel:[0,1,0]
	v_pk_fma_f32 v[140:141], v[240:241], v[114:115], v[140:141] op_sel_hi:[1,0,1]
	v_pk_fma_f32 v[142:143], v[248:249], v[114:115], v[142:143] op_sel_hi:[1,0,1]
	v_pk_fma_f32 v[140:141], v[242:243], v[114:115], v[140:141] op_sel:[0,1,0]
	v_pk_fma_f32 v[142:143], v[250:251], v[114:115], v[142:143] op_sel:[0,1,0]
	v_add_f32_dpp v116, v252, v252 quad_perm:[1,0,3,2] row_mask:0xf bank_mask:0xf
	v_add_f32_dpp v117, v253, v253 quad_perm:[1,0,3,2] row_mask:0xf bank_mask:0xf
	v_add_f32_dpp v118, v254, v254 quad_perm:[1,0,3,2] row_mask:0xf bank_mask:0xf
	v_add_f32_dpp v119, v255, v255 quad_perm:[1,0,3,2] row_mask:0xf bank_mask:0xf
	v_cndmask_b32_e32 v116, v118, v116, vcc
	v_cndmask_b32_e32 v117, v119, v117, vcc
	v_add_f32_dpp v122, v120, v120 quad_perm:[2,3,0,1] row_mask:0xf bank_mask:0xf
	v_add_f32_dpp v123, v121, v121 quad_perm:[2,3,0,1] row_mask:0xf bank_mask:0xf
	v_cndmask_b32_e64 v120, v123, v122, s[4:5]
	v_cndmask_b32_e64 v125, v120, v124, s[6:7]
	v_cndmask_b32_e64 v126, v124, v120, s[6:7]
	s_waitcnt vmcnt(27)
	v_pk_mul_f32 v[252:253], v[236:237], v[108:109] op_sel_hi:[1,0]
	v_pk_mul_f32 v[254:255], v[244:245], v[108:109] op_sel_hi:[1,0]
	v_pk_fma_f32 v[252:253], v[238:239], v[108:109], v[252:253] op_sel:[0,1,0]
	v_pk_fma_f32 v[254:255], v[246:247], v[108:109], v[254:255] op_sel:[0,1,0]
	v_pk_fma_f32 v[252:253], v[240:241], v[110:111], v[252:253] op_sel_hi:[1,0,1]
	v_pk_fma_f32 v[254:255], v[248:249], v[110:111], v[254:255] op_sel_hi:[1,0,1]
	v_pk_fma_f32 v[252:253], v[242:243], v[110:111], v[252:253] op_sel:[0,1,0]
	v_pk_fma_f32 v[254:255], v[250:251], v[110:111], v[254:255] op_sel:[0,1,0]
	v_add_f32_dpp v124, v126, v125 row_ror:4 row_mask:0xf bank_mask:0xf
	v_add_f32_dpp v112, v140, v140 quad_perm:[1,0,3,2] row_mask:0xf bank_mask:0xf
	v_add_f32_dpp v113, v141, v141 quad_perm:[1,0,3,2] row_mask:0xf bank_mask:0xf
	v_add_f32_dpp v114, v142, v142 quad_perm:[1,0,3,2] row_mask:0xf bank_mask:0xf
	v_add_f32_dpp v115, v143, v143 quad_perm:[1,0,3,2] row_mask:0xf bank_mask:0xf
	v_cndmask_b32_e32 v112, v114, v112, vcc
	v_cndmask_b32_e32 v113, v115, v113, vcc
	v_add_f32_dpp v118, v116, v116 quad_perm:[2,3,0,1] row_mask:0xf bank_mask:0xf
	v_add_f32_dpp v119, v117, v117 quad_perm:[2,3,0,1] row_mask:0xf bank_mask:0xf
	v_cndmask_b32_e64 v116, v119, v118, s[4:5]
	s_waitcnt vmcnt(26)
	v_pk_mul_f32 v[140:141], v[236:237], v[104:105] op_sel_hi:[1,0]
	v_pk_mul_f32 v[142:143], v[244:245], v[104:105] op_sel_hi:[1,0]
	v_pk_fma_f32 v[140:141], v[238:239], v[104:105], v[140:141] op_sel:[0,1,0]
	v_pk_fma_f32 v[142:143], v[246:247], v[104:105], v[142:143] op_sel:[0,1,0]
	v_pk_fma_f32 v[140:141], v[240:241], v[106:107], v[140:141] op_sel_hi:[1,0,1]
	v_pk_fma_f32 v[142:143], v[248:249], v[106:107], v[142:143] op_sel_hi:[1,0,1]
	v_pk_fma_f32 v[140:141], v[242:243], v[106:107], v[140:141] op_sel:[0,1,0]
	v_pk_fma_f32 v[142:143], v[250:251], v[106:107], v[142:143] op_sel:[0,1,0]
	v_add_f32_dpp v108, v252, v252 quad_perm:[1,0,3,2] row_mask:0xf bank_mask:0xf
	v_add_f32_dpp v109, v253, v253 quad_perm:[1,0,3,2] row_mask:0xf bank_mask:0xf
	v_add_f32_dpp v110, v254, v254 quad_perm:[1,0,3,2] row_mask:0xf bank_mask:0xf
	v_add_f32_dpp v111, v255, v255 quad_perm:[1,0,3,2] row_mask:0xf bank_mask:0xf
	v_cndmask_b32_e32 v108, v110, v108, vcc
	v_cndmask_b32_e32 v109, v111, v109, vcc
	v_add_f32_dpp v114, v112, v112 quad_perm:[2,3,0,1] row_mask:0xf bank_mask:0xf
	v_add_f32_dpp v115, v113, v113 quad_perm:[2,3,0,1] row_mask:0xf bank_mask:0xf
	v_cndmask_b32_e64 v112, v115, v114, s[4:5]
	v_cndmask_b32_e64 v117, v112, v116, s[6:7]
	v_cndmask_b32_e64 v118, v116, v112, s[6:7]
	s_waitcnt vmcnt(25)
	v_pk_mul_f32 v[252:253], v[236:237], v[100:101] op_sel_hi:[1,0]
	v_pk_mul_f32 v[254:255], v[244:245], v[100:101] op_sel_hi:[1,0]
	v_pk_fma_f32 v[252:253], v[238:239], v[100:101], v[252:253] op_sel:[0,1,0]
	v_pk_fma_f32 v[254:255], v[246:247], v[100:101], v[254:255] op_sel:[0,1,0]
	v_pk_fma_f32 v[252:253], v[240:241], v[102:103], v[252:253] op_sel_hi:[1,0,1]
	v_pk_fma_f32 v[254:255], v[248:249], v[102:103], v[254:255] op_sel_hi:[1,0,1]
	v_pk_fma_f32 v[252:253], v[242:243], v[102:103], v[252:253] op_sel:[0,1,0]
	v_pk_fma_f32 v[254:255], v[250:251], v[102:103], v[254:255] op_sel:[0,1,0]
	v_add_f32_dpp v116, v118, v117 row_ror:4 row_mask:0xf bank_mask:0xf
	v_cndmask_b32_e64 v125, v116, v124, s[64:65]
	v_cndmask_b32_e64 v126, v124, v116, s[64:65]
	v_add_f32_dpp v104, v140, v140 quad_perm:[1,0,3,2] row_mask:0xf bank_mask:0xf
	v_add_f32_dpp v105, v141, v141 quad_perm:[1,0,3,2] row_mask:0xf bank_mask:0xf
	v_add_f32_dpp v106, v142, v142 quad_perm:[1,0,3,2] row_mask:0xf bank_mask:0xf
	v_add_f32_dpp v107, v143, v143 quad_perm:[1,0,3,2] row_mask:0xf bank_mask:0xf
	v_cndmask_b32_e32 v104, v106, v104, vcc
	v_cndmask_b32_e32 v105, v107, v105, vcc
	v_add_f32_dpp v110, v108, v108 quad_perm:[2,3,0,1] row_mask:0xf bank_mask:0xf
	v_add_f32_dpp v111, v109, v109 quad_perm:[2,3,0,1] row_mask:0xf bank_mask:0xf
	v_cndmask_b32_e64 v108, v111, v110, s[4:5]
	s_waitcnt vmcnt(24)
	v_pk_mul_f32 v[140:141], v[236:237], v[96:97] op_sel_hi:[1,0]
	v_pk_mul_f32 v[142:143], v[244:245], v[96:97] op_sel_hi:[1,0]
	v_pk_fma_f32 v[140:141], v[238:239], v[96:97], v[140:141] op_sel:[0,1,0]
	v_pk_fma_f32 v[142:143], v[246:247], v[96:97], v[142:143] op_sel:[0,1,0]
	v_pk_fma_f32 v[140:141], v[240:241], v[98:99], v[140:141] op_sel_hi:[1,0,1]
	v_pk_fma_f32 v[142:143], v[248:249], v[98:99], v[142:143] op_sel_hi:[1,0,1]
	v_pk_fma_f32 v[140:141], v[242:243], v[98:99], v[140:141] op_sel:[0,1,0]
	v_pk_fma_f32 v[142:143], v[250:251], v[98:99], v[142:143] op_sel:[0,1,0]
	v_add_f32_dpp v124, v126, v125 row_ror:8 row_mask:0xf bank_mask:0xf
	v_add_f32_dpp v100, v252, v252 quad_perm:[1,0,3,2] row_mask:0xf bank_mask:0xf
	v_add_f32_dpp v101, v253, v253 quad_perm:[1,0,3,2] row_mask:0xf bank_mask:0xf
	v_add_f32_dpp v102, v254, v254 quad_perm:[1,0,3,2] row_mask:0xf bank_mask:0xf
	v_add_f32_dpp v103, v255, v255 quad_perm:[1,0,3,2] row_mask:0xf bank_mask:0xf
	v_cndmask_b32_e32 v100, v102, v100, vcc
	v_cndmask_b32_e32 v101, v103, v101, vcc
	v_add_f32_dpp v106, v104, v104 quad_perm:[2,3,0,1] row_mask:0xf bank_mask:0xf
	v_add_f32_dpp v107, v105, v105 quad_perm:[2,3,0,1] row_mask:0xf bank_mask:0xf
	v_cndmask_b32_e64 v104, v107, v106, s[4:5]
	v_cndmask_b32_e64 v109, v104, v108, s[6:7]
	v_cndmask_b32_e64 v110, v108, v104, s[6:7]
	s_waitcnt vmcnt(23)
	v_pk_mul_f32 v[252:253], v[236:237], v[92:93] op_sel_hi:[1,0]
	v_pk_mul_f32 v[254:255], v[244:245], v[92:93] op_sel_hi:[1,0]
	v_pk_fma_f32 v[252:253], v[238:239], v[92:93], v[252:253] op_sel:[0,1,0]
	v_pk_fma_f32 v[254:255], v[246:247], v[92:93], v[254:255] op_sel:[0,1,0]
	v_pk_fma_f32 v[252:253], v[240:241], v[94:95], v[252:253] op_sel_hi:[1,0,1]
	v_pk_fma_f32 v[254:255], v[248:249], v[94:95], v[254:255] op_sel_hi:[1,0,1]
	v_pk_fma_f32 v[252:253], v[242:243], v[94:95], v[252:253] op_sel:[0,1,0]
	v_pk_fma_f32 v[254:255], v[250:251], v[94:95], v[254:255] op_sel:[0,1,0]
	v_add_f32_dpp v108, v110, v109 row_ror:4 row_mask:0xf bank_mask:0xf
	v_add_f32_dpp v96, v140, v140 quad_perm:[1,0,3,2] row_mask:0xf bank_mask:0xf
	v_add_f32_dpp v97, v141, v141 quad_perm:[1,0,3,2] row_mask:0xf bank_mask:0xf
	v_add_f32_dpp v98, v142, v142 quad_perm:[1,0,3,2] row_mask:0xf bank_mask:0xf
	v_add_f32_dpp v99, v143, v143 quad_perm:[1,0,3,2] row_mask:0xf bank_mask:0xf
	v_cndmask_b32_e32 v96, v98, v96, vcc
	v_cndmask_b32_e32 v97, v99, v97, vcc
	v_add_f32_dpp v102, v100, v100 quad_perm:[2,3,0,1] row_mask:0xf bank_mask:0xf
	v_add_f32_dpp v103, v101, v101 quad_perm:[2,3,0,1] row_mask:0xf bank_mask:0xf
	v_cndmask_b32_e64 v100, v103, v102, s[4:5]
	s_waitcnt vmcnt(22)
	v_pk_mul_f32 v[140:141], v[236:237], v[88:89] op_sel_hi:[1,0]
	v_pk_mul_f32 v[142:143], v[244:245], v[88:89] op_sel_hi:[1,0]
	v_pk_fma_f32 v[140:141], v[238:239], v[88:89], v[140:141] op_sel:[0,1,0]
	v_pk_fma_f32 v[142:143], v[246:247], v[88:89], v[142:143] op_sel:[0,1,0]
	v_pk_fma_f32 v[140:141], v[240:241], v[90:91], v[140:141] op_sel_hi:[1,0,1]
	v_pk_fma_f32 v[142:143], v[248:249], v[90:91], v[142:143] op_sel_hi:[1,0,1]
	v_pk_fma_f32 v[140:141], v[242:243], v[90:91], v[140:141] op_sel:[0,1,0]
	v_pk_fma_f32 v[142:143], v[250:251], v[90:91], v[142:143] op_sel:[0,1,0]
	v_add_f32_dpp v92, v252, v252 quad_perm:[1,0,3,2] row_mask:0xf bank_mask:0xf
	v_add_f32_dpp v93, v253, v253 quad_perm:[1,0,3,2] row_mask:0xf bank_mask:0xf
	v_add_f32_dpp v94, v254, v254 quad_perm:[1,0,3,2] row_mask:0xf bank_mask:0xf
	v_add_f32_dpp v95, v255, v255 quad_perm:[1,0,3,2] row_mask:0xf bank_mask:0xf
	v_cndmask_b32_e32 v92, v94, v92, vcc
	v_cndmask_b32_e32 v93, v95, v93, vcc
	v_add_f32_dpp v98, v96, v96 quad_perm:[2,3,0,1] row_mask:0xf bank_mask:0xf
	v_add_f32_dpp v99, v97, v97 quad_perm:[2,3,0,1] row_mask:0xf bank_mask:0xf
	v_cndmask_b32_e64 v96, v99, v98, s[4:5]
	v_cndmask_b32_e64 v101, v96, v100, s[6:7]
	v_cndmask_b32_e64 v102, v100, v96, s[6:7]
	s_waitcnt vmcnt(21)
	v_pk_mul_f32 v[252:253], v[236:237], v[84:85] op_sel_hi:[1,0]
	v_pk_mul_f32 v[254:255], v[244:245], v[84:85] op_sel_hi:[1,0]
	v_pk_fma_f32 v[252:253], v[238:239], v[84:85], v[252:253] op_sel:[0,1,0]
	v_pk_fma_f32 v[254:255], v[246:247], v[84:85], v[254:255] op_sel:[0,1,0]
	v_pk_fma_f32 v[252:253], v[240:241], v[86:87], v[252:253] op_sel_hi:[1,0,1]
	v_pk_fma_f32 v[254:255], v[248:249], v[86:87], v[254:255] op_sel_hi:[1,0,1]
	v_pk_fma_f32 v[252:253], v[242:243], v[86:87], v[252:253] op_sel:[0,1,0]
	v_pk_fma_f32 v[254:255], v[250:251], v[86:87], v[254:255] op_sel:[0,1,0]
	v_add_f32_dpp v100, v102, v101 row_ror:4 row_mask:0xf bank_mask:0xf
	v_cndmask_b32_e64 v109, v100, v108, s[64:65]
	v_cndmask_b32_e64 v110, v108, v100, s[64:65]
	v_add_f32_dpp v88, v140, v140 quad_perm:[1,0,3,2] row_mask:0xf bank_mask:0xf
	v_add_f32_dpp v89, v141, v141 quad_perm:[1,0,3,2] row_mask:0xf bank_mask:0xf
	v_add_f32_dpp v90, v142, v142 quad_perm:[1,0,3,2] row_mask:0xf bank_mask:0xf
	v_add_f32_dpp v91, v143, v143 quad_perm:[1,0,3,2] row_mask:0xf bank_mask:0xf
	v_cndmask_b32_e32 v88, v90, v88, vcc
	v_cndmask_b32_e32 v89, v91, v89, vcc
	v_add_f32_dpp v94, v92, v92 quad_perm:[2,3,0,1] row_mask:0xf bank_mask:0xf
	v_add_f32_dpp v95, v93, v93 quad_perm:[2,3,0,1] row_mask:0xf bank_mask:0xf
	v_cndmask_b32_e64 v92, v95, v94, s[4:5]
	s_waitcnt vmcnt(20)
	v_pk_mul_f32 v[140:141], v[236:237], v[80:81] op_sel_hi:[1,0]
	v_pk_mul_f32 v[142:143], v[244:245], v[80:81] op_sel_hi:[1,0]
	v_pk_fma_f32 v[140:141], v[238:239], v[80:81], v[140:141] op_sel:[0,1,0]
	v_pk_fma_f32 v[142:143], v[246:247], v[80:81], v[142:143] op_sel:[0,1,0]
	v_pk_fma_f32 v[140:141], v[240:241], v[82:83], v[140:141] op_sel_hi:[1,0,1]
	v_pk_fma_f32 v[142:143], v[248:249], v[82:83], v[142:143] op_sel_hi:[1,0,1]
	v_pk_fma_f32 v[140:141], v[242:243], v[82:83], v[140:141] op_sel:[0,1,0]
	v_pk_fma_f32 v[142:143], v[250:251], v[82:83], v[142:143] op_sel:[0,1,0]
	v_add_f32_dpp v108, v110, v109 row_ror:8 row_mask:0xf bank_mask:0xf
	v_add_f32_dpp v84, v252, v252 quad_perm:[1,0,3,2] row_mask:0xf bank_mask:0xf
	v_add_f32_dpp v85, v253, v253 quad_perm:[1,0,3,2] row_mask:0xf bank_mask:0xf
	v_add_f32_dpp v86, v254, v254 quad_perm:[1,0,3,2] row_mask:0xf bank_mask:0xf
	v_add_f32_dpp v87, v255, v255 quad_perm:[1,0,3,2] row_mask:0xf bank_mask:0xf
	v_cndmask_b32_e32 v84, v86, v84, vcc
	v_cndmask_b32_e32 v85, v87, v85, vcc
	v_add_f32_dpp v90, v88, v88 quad_perm:[2,3,0,1] row_mask:0xf bank_mask:0xf
	v_add_f32_dpp v91, v89, v89 quad_perm:[2,3,0,1] row_mask:0xf bank_mask:0xf
	v_cndmask_b32_e64 v88, v91, v90, s[4:5]
	v_cndmask_b32_e64 v93, v88, v92, s[6:7]
	v_cndmask_b32_e64 v94, v92, v88, s[6:7]
	s_waitcnt vmcnt(19)
	v_pk_mul_f32 v[252:253], v[236:237], v[76:77] op_sel_hi:[1,0]
	v_pk_mul_f32 v[254:255], v[244:245], v[76:77] op_sel_hi:[1,0]
	v_pk_fma_f32 v[252:253], v[238:239], v[76:77], v[252:253] op_sel:[0,1,0]
	v_pk_fma_f32 v[254:255], v[246:247], v[76:77], v[254:255] op_sel:[0,1,0]
	v_pk_fma_f32 v[252:253], v[240:241], v[78:79], v[252:253] op_sel_hi:[1,0,1]
	v_pk_fma_f32 v[254:255], v[248:249], v[78:79], v[254:255] op_sel_hi:[1,0,1]
	v_pk_fma_f32 v[252:253], v[242:243], v[78:79], v[252:253] op_sel:[0,1,0]
	v_pk_fma_f32 v[254:255], v[250:251], v[78:79], v[254:255] op_sel:[0,1,0]
	v_permlane16_swap_b32_e32 v124, v108
	v_add_f32_e32 v124, v124, v108
	v_add_f32_dpp v92, v94, v93 row_ror:4 row_mask:0xf bank_mask:0xf
	v_add_f32_dpp v80, v140, v140 quad_perm:[1,0,3,2] row_mask:0xf bank_mask:0xf
	v_add_f32_dpp v81, v141, v141 quad_perm:[1,0,3,2] row_mask:0xf bank_mask:0xf
	v_add_f32_dpp v82, v142, v142 quad_perm:[1,0,3,2] row_mask:0xf bank_mask:0xf
	v_add_f32_dpp v83, v143, v143 quad_perm:[1,0,3,2] row_mask:0xf bank_mask:0xf
	v_cndmask_b32_e32 v80, v82, v80, vcc
	v_cndmask_b32_e32 v81, v83, v81, vcc
	v_add_f32_dpp v86, v84, v84 quad_perm:[2,3,0,1] row_mask:0xf bank_mask:0xf
	v_add_f32_dpp v87, v85, v85 quad_perm:[2,3,0,1] row_mask:0xf bank_mask:0xf
	v_cndmask_b32_e64 v84, v87, v86, s[4:5]
	s_waitcnt vmcnt(18)
	v_pk_mul_f32 v[140:141], v[236:237], v[72:73] op_sel_hi:[1,0]
	v_pk_mul_f32 v[142:143], v[244:245], v[72:73] op_sel_hi:[1,0]
	v_pk_fma_f32 v[140:141], v[238:239], v[72:73], v[140:141] op_sel:[0,1,0]
	v_pk_fma_f32 v[142:143], v[246:247], v[72:73], v[142:143] op_sel:[0,1,0]
	v_pk_fma_f32 v[140:141], v[240:241], v[74:75], v[140:141] op_sel_hi:[1,0,1]
	v_pk_fma_f32 v[142:143], v[248:249], v[74:75], v[142:143] op_sel_hi:[1,0,1]
	v_pk_fma_f32 v[140:141], v[242:243], v[74:75], v[140:141] op_sel:[0,1,0]
	v_pk_fma_f32 v[142:143], v[250:251], v[74:75], v[142:143] op_sel:[0,1,0]
	v_add_f32_dpp v76, v252, v252 quad_perm:[1,0,3,2] row_mask:0xf bank_mask:0xf
	v_add_f32_dpp v77, v253, v253 quad_perm:[1,0,3,2] row_mask:0xf bank_mask:0xf
	v_add_f32_dpp v78, v254, v254 quad_perm:[1,0,3,2] row_mask:0xf bank_mask:0xf
	v_add_f32_dpp v79, v255, v255 quad_perm:[1,0,3,2] row_mask:0xf bank_mask:0xf
	v_cndmask_b32_e32 v76, v78, v76, vcc
	v_cndmask_b32_e32 v77, v79, v77, vcc
	v_add_f32_dpp v82, v80, v80 quad_perm:[2,3,0,1] row_mask:0xf bank_mask:0xf
	v_add_f32_dpp v83, v81, v81 quad_perm:[2,3,0,1] row_mask:0xf bank_mask:0xf
	v_cndmask_b32_e64 v80, v83, v82, s[4:5]
	v_cndmask_b32_e64 v85, v80, v84, s[6:7]
	v_cndmask_b32_e64 v86, v84, v80, s[6:7]
	s_waitcnt vmcnt(17)
	v_pk_mul_f32 v[252:253], v[236:237], v[68:69] op_sel_hi:[1,0]
	v_pk_mul_f32 v[254:255], v[244:245], v[68:69] op_sel_hi:[1,0]
	v_pk_fma_f32 v[252:253], v[238:239], v[68:69], v[252:253] op_sel:[0,1,0]
	v_pk_fma_f32 v[254:255], v[246:247], v[68:69], v[254:255] op_sel:[0,1,0]
	v_pk_fma_f32 v[252:253], v[240:241], v[70:71], v[252:253] op_sel_hi:[1,0,1]
	v_pk_fma_f32 v[254:255], v[248:249], v[70:71], v[254:255] op_sel_hi:[1,0,1]
	v_pk_fma_f32 v[252:253], v[242:243], v[70:71], v[252:253] op_sel:[0,1,0]
	v_pk_fma_f32 v[254:255], v[250:251], v[70:71], v[254:255] op_sel:[0,1,0]
	v_add_f32_dpp v84, v86, v85 row_ror:4 row_mask:0xf bank_mask:0xf
	v_cndmask_b32_e64 v93, v84, v92, s[64:65]
	v_cndmask_b32_e64 v94, v92, v84, s[64:65]
	v_add_f32_dpp v72, v140, v140 quad_perm:[1,0,3,2] row_mask:0xf bank_mask:0xf
	v_add_f32_dpp v73, v141, v141 quad_perm:[1,0,3,2] row_mask:0xf bank_mask:0xf
	v_add_f32_dpp v74, v142, v142 quad_perm:[1,0,3,2] row_mask:0xf bank_mask:0xf
	v_add_f32_dpp v75, v143, v143 quad_perm:[1,0,3,2] row_mask:0xf bank_mask:0xf
	v_cndmask_b32_e32 v72, v74, v72, vcc
	v_cndmask_b32_e32 v73, v75, v73, vcc
	v_add_f32_dpp v78, v76, v76 quad_perm:[2,3,0,1] row_mask:0xf bank_mask:0xf
	v_add_f32_dpp v79, v77, v77 quad_perm:[2,3,0,1] row_mask:0xf bank_mask:0xf
	v_cndmask_b32_e64 v76, v79, v78, s[4:5]
	s_waitcnt vmcnt(16)
	v_pk_mul_f32 v[140:141], v[236:237], v[64:65] op_sel_hi:[1,0]
	v_pk_mul_f32 v[142:143], v[244:245], v[64:65] op_sel_hi:[1,0]
	v_pk_fma_f32 v[140:141], v[238:239], v[64:65], v[140:141] op_sel:[0,1,0]
	v_pk_fma_f32 v[142:143], v[246:247], v[64:65], v[142:143] op_sel:[0,1,0]
	v_pk_fma_f32 v[140:141], v[240:241], v[66:67], v[140:141] op_sel_hi:[1,0,1]
	v_pk_fma_f32 v[142:143], v[248:249], v[66:67], v[142:143] op_sel_hi:[1,0,1]
	v_pk_fma_f32 v[140:141], v[242:243], v[66:67], v[140:141] op_sel:[0,1,0]
	v_pk_fma_f32 v[142:143], v[250:251], v[66:67], v[142:143] op_sel:[0,1,0]
	v_add_f32_dpp v92, v94, v93 row_ror:8 row_mask:0xf bank_mask:0xf
	v_add_f32_dpp v68, v252, v252 quad_perm:[1,0,3,2] row_mask:0xf bank_mask:0xf
	v_add_f32_dpp v69, v253, v253 quad_perm:[1,0,3,2] row_mask:0xf bank_mask:0xf
	v_add_f32_dpp v70, v254, v254 quad_perm:[1,0,3,2] row_mask:0xf bank_mask:0xf
	v_add_f32_dpp v71, v255, v255 quad_perm:[1,0,3,2] row_mask:0xf bank_mask:0xf
	v_cndmask_b32_e32 v68, v70, v68, vcc
	v_cndmask_b32_e32 v69, v71, v69, vcc
	v_add_f32_dpp v74, v72, v72 quad_perm:[2,3,0,1] row_mask:0xf bank_mask:0xf
	v_add_f32_dpp v75, v73, v73 quad_perm:[2,3,0,1] row_mask:0xf bank_mask:0xf
	v_cndmask_b32_e64 v72, v75, v74, s[4:5]
	v_cndmask_b32_e64 v77, v72, v76, s[6:7]
	v_cndmask_b32_e64 v78, v76, v72, s[6:7]
	s_waitcnt vmcnt(15)
	v_pk_mul_f32 v[252:253], v[236:237], v[60:61] op_sel_hi:[1,0]
	v_pk_mul_f32 v[254:255], v[244:245], v[60:61] op_sel_hi:[1,0]
	v_pk_fma_f32 v[252:253], v[238:239], v[60:61], v[252:253] op_sel:[0,1,0]
	v_pk_fma_f32 v[254:255], v[246:247], v[60:61], v[254:255] op_sel:[0,1,0]
	v_pk_fma_f32 v[252:253], v[240:241], v[62:63], v[252:253] op_sel_hi:[1,0,1]
	v_pk_fma_f32 v[254:255], v[248:249], v[62:63], v[254:255] op_sel_hi:[1,0,1]
	v_pk_fma_f32 v[252:253], v[242:243], v[62:63], v[252:253] op_sel:[0,1,0]
	v_pk_fma_f32 v[254:255], v[250:251], v[62:63], v[254:255] op_sel:[0,1,0]
	v_add_f32_dpp v76, v78, v77 row_ror:4 row_mask:0xf bank_mask:0xf
	v_add_f32_dpp v64, v140, v140 quad_perm:[1,0,3,2] row_mask:0xf bank_mask:0xf
	v_add_f32_dpp v65, v141, v141 quad_perm:[1,0,3,2] row_mask:0xf bank_mask:0xf
	v_add_f32_dpp v66, v142, v142 quad_perm:[1,0,3,2] row_mask:0xf bank_mask:0xf
	v_add_f32_dpp v67, v143, v143 quad_perm:[1,0,3,2] row_mask:0xf bank_mask:0xf
	v_cndmask_b32_e32 v64, v66, v64, vcc
	v_cndmask_b32_e32 v65, v67, v65, vcc
	v_add_f32_dpp v70, v68, v68 quad_perm:[2,3,0,1] row_mask:0xf bank_mask:0xf
	v_add_f32_dpp v71, v69, v69 quad_perm:[2,3,0,1] row_mask:0xf bank_mask:0xf
	v_cndmask_b32_e64 v68, v71, v70, s[4:5]
	s_waitcnt vmcnt(14)
	v_pk_mul_f32 v[140:141], v[236:237], v[56:57] op_sel_hi:[1,0]
	v_pk_mul_f32 v[142:143], v[244:245], v[56:57] op_sel_hi:[1,0]
	v_pk_fma_f32 v[140:141], v[238:239], v[56:57], v[140:141] op_sel:[0,1,0]
	v_pk_fma_f32 v[142:143], v[246:247], v[56:57], v[142:143] op_sel:[0,1,0]
	v_pk_fma_f32 v[140:141], v[240:241], v[58:59], v[140:141] op_sel_hi:[1,0,1]
	v_pk_fma_f32 v[142:143], v[248:249], v[58:59], v[142:143] op_sel_hi:[1,0,1]
	v_pk_fma_f32 v[140:141], v[242:243], v[58:59], v[140:141] op_sel:[0,1,0]
	v_pk_fma_f32 v[142:143], v[250:251], v[58:59], v[142:143] op_sel:[0,1,0]
	v_add_f32_dpp v60, v252, v252 quad_perm:[1,0,3,2] row_mask:0xf bank_mask:0xf
	v_add_f32_dpp v61, v253, v253 quad_perm:[1,0,3,2] row_mask:0xf bank_mask:0xf
	v_add_f32_dpp v62, v254, v254 quad_perm:[1,0,3,2] row_mask:0xf bank_mask:0xf
	v_add_f32_dpp v63, v255, v255 quad_perm:[1,0,3,2] row_mask:0xf bank_mask:0xf
	v_cndmask_b32_e32 v60, v62, v60, vcc
	v_cndmask_b32_e32 v61, v63, v61, vcc
	v_add_f32_dpp v66, v64, v64 quad_perm:[2,3,0,1] row_mask:0xf bank_mask:0xf
	v_add_f32_dpp v67, v65, v65 quad_perm:[2,3,0,1] row_mask:0xf bank_mask:0xf
	v_cndmask_b32_e64 v64, v67, v66, s[4:5]
	v_cndmask_b32_e64 v69, v64, v68, s[6:7]
	v_cndmask_b32_e64 v70, v68, v64, s[6:7]
	s_waitcnt vmcnt(13)
	v_pk_mul_f32 v[252:253], v[236:237], v[52:53] op_sel_hi:[1,0]
	v_pk_mul_f32 v[254:255], v[244:245], v[52:53] op_sel_hi:[1,0]
	v_pk_fma_f32 v[252:253], v[238:239], v[52:53], v[252:253] op_sel:[0,1,0]
	v_pk_fma_f32 v[254:255], v[246:247], v[52:53], v[254:255] op_sel:[0,1,0]
	v_pk_fma_f32 v[252:253], v[240:241], v[54:55], v[252:253] op_sel_hi:[1,0,1]
	v_pk_fma_f32 v[254:255], v[248:249], v[54:55], v[254:255] op_sel_hi:[1,0,1]
	v_pk_fma_f32 v[252:253], v[242:243], v[54:55], v[252:253] op_sel:[0,1,0]
	v_pk_fma_f32 v[254:255], v[250:251], v[54:55], v[254:255] op_sel:[0,1,0]
	v_add_f32_dpp v68, v70, v69 row_ror:4 row_mask:0xf bank_mask:0xf
	v_cndmask_b32_e64 v77, v68, v76, s[64:65]
	v_cndmask_b32_e64 v78, v76, v68, s[64:65]
	v_add_f32_dpp v56, v140, v140 quad_perm:[1,0,3,2] row_mask:0xf bank_mask:0xf
	v_add_f32_dpp v57, v141, v141 quad_perm:[1,0,3,2] row_mask:0xf bank_mask:0xf
	v_add_f32_dpp v58, v142, v142 quad_perm:[1,0,3,2] row_mask:0xf bank_mask:0xf
	v_add_f32_dpp v59, v143, v143 quad_perm:[1,0,3,2] row_mask:0xf bank_mask:0xf
	v_cndmask_b32_e32 v56, v58, v56, vcc
	v_cndmask_b32_e32 v57, v59, v57, vcc
	v_add_f32_dpp v62, v60, v60 quad_perm:[2,3,0,1] row_mask:0xf bank_mask:0xf
	v_add_f32_dpp v63, v61, v61 quad_perm:[2,3,0,1] row_mask:0xf bank_mask:0xf
	v_cndmask_b32_e64 v60, v63, v62, s[4:5]
	s_waitcnt vmcnt(12)
	v_pk_mul_f32 v[140:141], v[236:237], v[48:49] op_sel_hi:[1,0]
	v_pk_mul_f32 v[142:143], v[244:245], v[48:49] op_sel_hi:[1,0]
	v_pk_fma_f32 v[140:141], v[238:239], v[48:49], v[140:141] op_sel:[0,1,0]
	v_pk_fma_f32 v[142:143], v[246:247], v[48:49], v[142:143] op_sel:[0,1,0]
	v_pk_fma_f32 v[140:141], v[240:241], v[50:51], v[140:141] op_sel_hi:[1,0,1]
	v_pk_fma_f32 v[142:143], v[248:249], v[50:51], v[142:143] op_sel_hi:[1,0,1]
	v_pk_fma_f32 v[140:141], v[242:243], v[50:51], v[140:141] op_sel:[0,1,0]
	v_pk_fma_f32 v[142:143], v[250:251], v[50:51], v[142:143] op_sel:[0,1,0]
	v_add_f32_dpp v76, v78, v77 row_ror:8 row_mask:0xf bank_mask:0xf
	v_add_f32_dpp v52, v252, v252 quad_perm:[1,0,3,2] row_mask:0xf bank_mask:0xf
	v_add_f32_dpp v53, v253, v253 quad_perm:[1,0,3,2] row_mask:0xf bank_mask:0xf
	v_add_f32_dpp v54, v254, v254 quad_perm:[1,0,3,2] row_mask:0xf bank_mask:0xf
	v_add_f32_dpp v55, v255, v255 quad_perm:[1,0,3,2] row_mask:0xf bank_mask:0xf
	v_cndmask_b32_e32 v52, v54, v52, vcc
	v_cndmask_b32_e32 v53, v55, v53, vcc
	v_add_f32_dpp v58, v56, v56 quad_perm:[2,3,0,1] row_mask:0xf bank_mask:0xf
	v_add_f32_dpp v59, v57, v57 quad_perm:[2,3,0,1] row_mask:0xf bank_mask:0xf
	v_cndmask_b32_e64 v56, v59, v58, s[4:5]
	v_cndmask_b32_e64 v61, v56, v60, s[6:7]
	v_cndmask_b32_e64 v62, v60, v56, s[6:7]
	s_waitcnt vmcnt(11)
	v_pk_mul_f32 v[252:253], v[236:237], v[44:45] op_sel_hi:[1,0]
	v_pk_mul_f32 v[254:255], v[244:245], v[44:45] op_sel_hi:[1,0]
	v_pk_fma_f32 v[252:253], v[238:239], v[44:45], v[252:253] op_sel:[0,1,0]
	v_pk_fma_f32 v[254:255], v[246:247], v[44:45], v[254:255] op_sel:[0,1,0]
	v_pk_fma_f32 v[252:253], v[240:241], v[46:47], v[252:253] op_sel_hi:[1,0,1]
	v_pk_fma_f32 v[254:255], v[248:249], v[46:47], v[254:255] op_sel_hi:[1,0,1]
	v_pk_fma_f32 v[252:253], v[242:243], v[46:47], v[252:253] op_sel:[0,1,0]
	v_pk_fma_f32 v[254:255], v[250:251], v[46:47], v[254:255] op_sel:[0,1,0]
	v_permlane16_swap_b32_e32 v92, v76
	v_add_f32_e32 v92, v92, v76
	v_add_f32_dpp v60, v62, v61 row_ror:4 row_mask:0xf bank_mask:0xf
	v_add_f32_dpp v48, v140, v140 quad_perm:[1,0,3,2] row_mask:0xf bank_mask:0xf
	v_add_f32_dpp v49, v141, v141 quad_perm:[1,0,3,2] row_mask:0xf bank_mask:0xf
	v_add_f32_dpp v50, v142, v142 quad_perm:[1,0,3,2] row_mask:0xf bank_mask:0xf
	v_add_f32_dpp v51, v143, v143 quad_perm:[1,0,3,2] row_mask:0xf bank_mask:0xf
	v_cndmask_b32_e32 v48, v50, v48, vcc
	v_cndmask_b32_e32 v49, v51, v49, vcc
	v_add_f32_dpp v54, v52, v52 quad_perm:[2,3,0,1] row_mask:0xf bank_mask:0xf
	v_add_f32_dpp v55, v53, v53 quad_perm:[2,3,0,1] row_mask:0xf bank_mask:0xf
	v_cndmask_b32_e64 v52, v55, v54, s[4:5]
	s_waitcnt vmcnt(10)
	v_pk_mul_f32 v[140:141], v[236:237], v[40:41] op_sel_hi:[1,0]
	v_pk_mul_f32 v[142:143], v[244:245], v[40:41] op_sel_hi:[1,0]
	v_pk_fma_f32 v[140:141], v[238:239], v[40:41], v[140:141] op_sel:[0,1,0]
	v_pk_fma_f32 v[142:143], v[246:247], v[40:41], v[142:143] op_sel:[0,1,0]
	v_pk_fma_f32 v[140:141], v[240:241], v[42:43], v[140:141] op_sel_hi:[1,0,1]
	v_pk_fma_f32 v[142:143], v[248:249], v[42:43], v[142:143] op_sel_hi:[1,0,1]
	v_pk_fma_f32 v[140:141], v[242:243], v[42:43], v[140:141] op_sel:[0,1,0]
	v_pk_fma_f32 v[142:143], v[250:251], v[42:43], v[142:143] op_sel:[0,1,0]
	v_permlane32_swap_b32_e32 v124, v92
	v_add_f32_e32 v124, v124, v92
	ds_write_b32 v235, v124
	v_add_f32_dpp v44, v252, v252 quad_perm:[1,0,3,2] row_mask:0xf bank_mask:0xf
	v_add_f32_dpp v45, v253, v253 quad_perm:[1,0,3,2] row_mask:0xf bank_mask:0xf
	v_add_f32_dpp v46, v254, v254 quad_perm:[1,0,3,2] row_mask:0xf bank_mask:0xf
	v_add_f32_dpp v47, v255, v255 quad_perm:[1,0,3,2] row_mask:0xf bank_mask:0xf
	v_cndmask_b32_e32 v44, v46, v44, vcc
	v_cndmask_b32_e32 v45, v47, v45, vcc
	v_add_f32_dpp v50, v48, v48 quad_perm:[2,3,0,1] row_mask:0xf bank_mask:0xf
	v_add_f32_dpp v51, v49, v49 quad_perm:[2,3,0,1] row_mask:0xf bank_mask:0xf
	v_cndmask_b32_e64 v48, v51, v50, s[4:5]
	v_cndmask_b32_e64 v53, v48, v52, s[6:7]
	v_cndmask_b32_e64 v54, v52, v48, s[6:7]
	s_waitcnt vmcnt(9)
	v_pk_mul_f32 v[252:253], v[236:237], v[36:37] op_sel_hi:[1,0]
	v_pk_mul_f32 v[254:255], v[244:245], v[36:37] op_sel_hi:[1,0]
	v_pk_fma_f32 v[252:253], v[238:239], v[36:37], v[252:253] op_sel:[0,1,0]
	v_pk_fma_f32 v[254:255], v[246:247], v[36:37], v[254:255] op_sel:[0,1,0]
	v_pk_fma_f32 v[252:253], v[240:241], v[38:39], v[252:253] op_sel_hi:[1,0,1]
	v_pk_fma_f32 v[254:255], v[248:249], v[38:39], v[254:255] op_sel_hi:[1,0,1]
	v_pk_fma_f32 v[252:253], v[242:243], v[38:39], v[252:253] op_sel:[0,1,0]
	v_pk_fma_f32 v[254:255], v[250:251], v[38:39], v[254:255] op_sel:[0,1,0]
	v_add_f32_dpp v52, v54, v53 row_ror:4 row_mask:0xf bank_mask:0xf
	v_cndmask_b32_e64 v61, v52, v60, s[64:65]
	v_cndmask_b32_e64 v62, v60, v52, s[64:65]
	v_add_f32_dpp v40, v140, v140 quad_perm:[1,0,3,2] row_mask:0xf bank_mask:0xf
	v_add_f32_dpp v41, v141, v141 quad_perm:[1,0,3,2] row_mask:0xf bank_mask:0xf
	v_add_f32_dpp v42, v142, v142 quad_perm:[1,0,3,2] row_mask:0xf bank_mask:0xf
	v_add_f32_dpp v43, v143, v143 quad_perm:[1,0,3,2] row_mask:0xf bank_mask:0xf
	v_cndmask_b32_e32 v40, v42, v40, vcc
	v_cndmask_b32_e32 v41, v43, v41, vcc
	v_add_f32_dpp v46, v44, v44 quad_perm:[2,3,0,1] row_mask:0xf bank_mask:0xf
	v_add_f32_dpp v47, v45, v45 quad_perm:[2,3,0,1] row_mask:0xf bank_mask:0xf
	v_cndmask_b32_e64 v44, v47, v46, s[4:5]
	s_waitcnt vmcnt(8)
	v_pk_mul_f32 v[140:141], v[236:237], v[32:33] op_sel_hi:[1,0]
	v_pk_mul_f32 v[142:143], v[244:245], v[32:33] op_sel_hi:[1,0]
	v_pk_fma_f32 v[140:141], v[238:239], v[32:33], v[140:141] op_sel:[0,1,0]
	v_pk_fma_f32 v[142:143], v[246:247], v[32:33], v[142:143] op_sel:[0,1,0]
	v_pk_fma_f32 v[140:141], v[240:241], v[34:35], v[140:141] op_sel_hi:[1,0,1]
	v_pk_fma_f32 v[142:143], v[248:249], v[34:35], v[142:143] op_sel_hi:[1,0,1]
	v_pk_fma_f32 v[140:141], v[242:243], v[34:35], v[140:141] op_sel:[0,1,0]
	v_pk_fma_f32 v[142:143], v[250:251], v[34:35], v[142:143] op_sel:[0,1,0]
	v_add_f32_dpp v60, v62, v61 row_ror:8 row_mask:0xf bank_mask:0xf
	v_add_f32_dpp v36, v252, v252 quad_perm:[1,0,3,2] row_mask:0xf bank_mask:0xf
	v_add_f32_dpp v37, v253, v253 quad_perm:[1,0,3,2] row_mask:0xf bank_mask:0xf
	v_add_f32_dpp v38, v254, v254 quad_perm:[1,0,3,2] row_mask:0xf bank_mask:0xf
	v_add_f32_dpp v39, v255, v255 quad_perm:[1,0,3,2] row_mask:0xf bank_mask:0xf
	v_cndmask_b32_e32 v36, v38, v36, vcc
	v_cndmask_b32_e32 v37, v39, v37, vcc
	v_add_f32_dpp v42, v40, v40 quad_perm:[2,3,0,1] row_mask:0xf bank_mask:0xf
	v_add_f32_dpp v43, v41, v41 quad_perm:[2,3,0,1] row_mask:0xf bank_mask:0xf
	v_cndmask_b32_e64 v40, v43, v42, s[4:5]
	v_cndmask_b32_e64 v45, v40, v44, s[6:7]
	v_cndmask_b32_e64 v46, v44, v40, s[6:7]
	s_waitcnt vmcnt(7)
	v_pk_mul_f32 v[252:253], v[236:237], v[28:29] op_sel_hi:[1,0]
	v_pk_mul_f32 v[254:255], v[244:245], v[28:29] op_sel_hi:[1,0]
	v_pk_fma_f32 v[252:253], v[238:239], v[28:29], v[252:253] op_sel:[0,1,0]
	v_pk_fma_f32 v[254:255], v[246:247], v[28:29], v[254:255] op_sel:[0,1,0]
	v_pk_fma_f32 v[252:253], v[240:241], v[30:31], v[252:253] op_sel_hi:[1,0,1]
	v_pk_fma_f32 v[254:255], v[248:249], v[30:31], v[254:255] op_sel_hi:[1,0,1]
	v_pk_fma_f32 v[252:253], v[242:243], v[30:31], v[252:253] op_sel:[0,1,0]
	v_pk_fma_f32 v[254:255], v[250:251], v[30:31], v[254:255] op_sel:[0,1,0]
	v_add_f32_dpp v44, v46, v45 row_ror:4 row_mask:0xf bank_mask:0xf
	v_add_f32_dpp v32, v140, v140 quad_perm:[1,0,3,2] row_mask:0xf bank_mask:0xf
	v_add_f32_dpp v33, v141, v141 quad_perm:[1,0,3,2] row_mask:0xf bank_mask:0xf
	v_add_f32_dpp v34, v142, v142 quad_perm:[1,0,3,2] row_mask:0xf bank_mask:0xf
	v_add_f32_dpp v35, v143, v143 quad_perm:[1,0,3,2] row_mask:0xf bank_mask:0xf
	v_cndmask_b32_e32 v32, v34, v32, vcc
	v_cndmask_b32_e32 v33, v35, v33, vcc
	v_add_f32_dpp v38, v36, v36 quad_perm:[2,3,0,1] row_mask:0xf bank_mask:0xf
	v_add_f32_dpp v39, v37, v37 quad_perm:[2,3,0,1] row_mask:0xf bank_mask:0xf
	v_cndmask_b32_e64 v36, v39, v38, s[4:5]
	s_waitcnt vmcnt(6)
	v_pk_mul_f32 v[140:141], v[236:237], v[24:25] op_sel_hi:[1,0]
	v_pk_mul_f32 v[142:143], v[244:245], v[24:25] op_sel_hi:[1,0]
	v_pk_fma_f32 v[140:141], v[238:239], v[24:25], v[140:141] op_sel:[0,1,0]
	v_pk_fma_f32 v[142:143], v[246:247], v[24:25], v[142:143] op_sel:[0,1,0]
	v_pk_fma_f32 v[140:141], v[240:241], v[26:27], v[140:141] op_sel_hi:[1,0,1]
	v_pk_fma_f32 v[142:143], v[248:249], v[26:27], v[142:143] op_sel_hi:[1,0,1]
	v_pk_fma_f32 v[140:141], v[242:243], v[26:27], v[140:141] op_sel:[0,1,0]
	v_pk_fma_f32 v[142:143], v[250:251], v[26:27], v[142:143] op_sel:[0,1,0]
	v_add_f32_dpp v28, v252, v252 quad_perm:[1,0,3,2] row_mask:0xf bank_mask:0xf
	v_add_f32_dpp v29, v253, v253 quad_perm:[1,0,3,2] row_mask:0xf bank_mask:0xf
	v_add_f32_dpp v30, v254, v254 quad_perm:[1,0,3,2] row_mask:0xf bank_mask:0xf
	v_add_f32_dpp v31, v255, v255 quad_perm:[1,0,3,2] row_mask:0xf bank_mask:0xf
	v_cndmask_b32_e32 v28, v30, v28, vcc
	v_cndmask_b32_e32 v29, v31, v29, vcc
	v_add_f32_dpp v34, v32, v32 quad_perm:[2,3,0,1] row_mask:0xf bank_mask:0xf
	v_add_f32_dpp v35, v33, v33 quad_perm:[2,3,0,1] row_mask:0xf bank_mask:0xf
	v_cndmask_b32_e64 v32, v35, v34, s[4:5]
	v_cndmask_b32_e64 v37, v32, v36, s[6:7]
	v_cndmask_b32_e64 v38, v36, v32, s[6:7]
	s_waitcnt vmcnt(5)
	v_pk_mul_f32 v[252:253], v[236:237], v[20:21] op_sel_hi:[1,0]
	v_pk_mul_f32 v[254:255], v[244:245], v[20:21] op_sel_hi:[1,0]
	v_pk_fma_f32 v[252:253], v[238:239], v[20:21], v[252:253] op_sel:[0,1,0]
	v_pk_fma_f32 v[254:255], v[246:247], v[20:21], v[254:255] op_sel:[0,1,0]
	v_pk_fma_f32 v[252:253], v[240:241], v[22:23], v[252:253] op_sel_hi:[1,0,1]
	v_pk_fma_f32 v[254:255], v[248:249], v[22:23], v[254:255] op_sel_hi:[1,0,1]
	v_pk_fma_f32 v[252:253], v[242:243], v[22:23], v[252:253] op_sel:[0,1,0]
	v_pk_fma_f32 v[254:255], v[250:251], v[22:23], v[254:255] op_sel:[0,1,0]
	v_add_f32_dpp v36, v38, v37 row_ror:4 row_mask:0xf bank_mask:0xf
	v_cndmask_b32_e64 v45, v36, v44, s[64:65]
	v_cndmask_b32_e64 v46, v44, v36, s[64:65]
	v_add_f32_dpp v24, v140, v140 quad_perm:[1,0,3,2] row_mask:0xf bank_mask:0xf
	v_add_f32_dpp v25, v141, v141 quad_perm:[1,0,3,2] row_mask:0xf bank_mask:0xf
	v_add_f32_dpp v26, v142, v142 quad_perm:[1,0,3,2] row_mask:0xf bank_mask:0xf
	v_add_f32_dpp v27, v143, v143 quad_perm:[1,0,3,2] row_mask:0xf bank_mask:0xf
	v_cndmask_b32_e32 v24, v26, v24, vcc
	v_cndmask_b32_e32 v25, v27, v25, vcc
	v_add_f32_dpp v30, v28, v28 quad_perm:[2,3,0,1] row_mask:0xf bank_mask:0xf
	v_add_f32_dpp v31, v29, v29 quad_perm:[2,3,0,1] row_mask:0xf bank_mask:0xf
	v_cndmask_b32_e64 v28, v31, v30, s[4:5]
	s_waitcnt vmcnt(4)
	v_pk_mul_f32 v[140:141], v[236:237], v[16:17] op_sel_hi:[1,0]
	v_pk_mul_f32 v[142:143], v[244:245], v[16:17] op_sel_hi:[1,0]
	v_pk_fma_f32 v[140:141], v[238:239], v[16:17], v[140:141] op_sel:[0,1,0]
	v_pk_fma_f32 v[142:143], v[246:247], v[16:17], v[142:143] op_sel:[0,1,0]
	v_pk_fma_f32 v[140:141], v[240:241], v[18:19], v[140:141] op_sel_hi:[1,0,1]
	v_pk_fma_f32 v[142:143], v[248:249], v[18:19], v[142:143] op_sel_hi:[1,0,1]
	v_pk_fma_f32 v[140:141], v[242:243], v[18:19], v[140:141] op_sel:[0,1,0]
	v_pk_fma_f32 v[142:143], v[250:251], v[18:19], v[142:143] op_sel:[0,1,0]
	v_add_f32_dpp v44, v46, v45 row_ror:8 row_mask:0xf bank_mask:0xf
	v_add_f32_dpp v20, v252, v252 quad_perm:[1,0,3,2] row_mask:0xf bank_mask:0xf
	v_add_f32_dpp v21, v253, v253 quad_perm:[1,0,3,2] row_mask:0xf bank_mask:0xf
	v_add_f32_dpp v22, v254, v254 quad_perm:[1,0,3,2] row_mask:0xf bank_mask:0xf
	v_add_f32_dpp v23, v255, v255 quad_perm:[1,0,3,2] row_mask:0xf bank_mask:0xf
	v_cndmask_b32_e32 v20, v22, v20, vcc
	v_cndmask_b32_e32 v21, v23, v21, vcc
	v_add_f32_dpp v26, v24, v24 quad_perm:[2,3,0,1] row_mask:0xf bank_mask:0xf
	v_add_f32_dpp v27, v25, v25 quad_perm:[2,3,0,1] row_mask:0xf bank_mask:0xf
	v_cndmask_b32_e64 v24, v27, v26, s[4:5]
	v_cndmask_b32_e64 v29, v24, v28, s[6:7]
	v_cndmask_b32_e64 v30, v28, v24, s[6:7]
	s_waitcnt vmcnt(3)
; DI void attn_sample_item(const Params& p, int item, ldsp lds, int tid_) {
;     ...
;   SC_SCORE(kvA, 0)
;   SC_SCORE(kvB, 1)
;     ...
;   for (int j = 0; j < 16; ++j) vvA[j] = __builtin_nontemporal_load((const f32x4*)(cv + (size_t)(wid * 32 + j) * 1024 + lane * 4));
	v_pk_mul_f32 v[252:253], v[236:237], v[12:13] op_sel_hi:[1,0]
	v_pk_mul_f32 v[254:255], v[244:245], v[12:13] op_sel_hi:[1,0]
	v_pk_fma_f32 v[252:253], v[238:239], v[12:13], v[252:253] op_sel:[0,1,0]
	v_pk_fma_f32 v[254:255], v[246:247], v[12:13], v[254:255] op_sel:[0,1,0]
	v_pk_fma_f32 v[252:253], v[240:241], v[14:15], v[252:253] op_sel_hi:[1,0,1]
	v_pk_fma_f32 v[254:255], v[248:249], v[14:15], v[254:255] op_sel_hi:[1,0,1]
	v_pk_fma_f32 v[252:253], v[242:243], v[14:15], v[252:253] op_sel:[0,1,0]
	v_pk_fma_f32 v[254:255], v[250:251], v[14:15], v[254:255] op_sel:[0,1,0]
	v_permlane16_swap_b32_e32 v60, v44
	v_add_f32_e32 v60, v60, v44
	v_add_f32_dpp v28, v30, v29 row_ror:4 row_mask:0xf bank_mask:0xf
	v_add_f32_dpp v16, v140, v140 quad_perm:[1,0,3,2] row_mask:0xf bank_mask:0xf
	v_add_f32_dpp v17, v141, v141 quad_perm:[1,0,3,2] row_mask:0xf bank_mask:0xf
	v_add_f32_dpp v18, v142, v142 quad_perm:[1,0,3,2] row_mask:0xf bank_mask:0xf
	v_add_f32_dpp v19, v143, v143 quad_perm:[1,0,3,2] row_mask:0xf bank_mask:0xf
	v_cndmask_b32_e32 v16, v18, v16, vcc
	v_cndmask_b32_e32 v17, v19, v17, vcc
	v_add_f32_dpp v22, v20, v20 quad_perm:[2,3,0,1] row_mask:0xf bank_mask:0xf
	v_add_f32_dpp v23, v21, v21 quad_perm:[2,3,0,1] row_mask:0xf bank_mask:0xf
	v_cndmask_b32_e64 v20, v23, v22, s[4:5]
	s_waitcnt vmcnt(2)
	v_pk_mul_f32 v[140:141], v[236:237], v[8:9] op_sel_hi:[1,0]
	v_pk_mul_f32 v[142:143], v[244:245], v[8:9] op_sel_hi:[1,0]
	v_pk_fma_f32 v[140:141], v[238:239], v[8:9], v[140:141] op_sel:[0,1,0]
	v_pk_fma_f32 v[142:143], v[246:247], v[8:9], v[142:143] op_sel:[0,1,0]
	v_pk_fma_f32 v[140:141], v[240:241], v[10:11], v[140:141] op_sel_hi:[1,0,1]
	v_pk_fma_f32 v[142:143], v[248:249], v[10:11], v[142:143] op_sel_hi:[1,0,1]
	v_pk_fma_f32 v[140:141], v[242:243], v[10:11], v[140:141] op_sel:[0,1,0]
	v_pk_fma_f32 v[142:143], v[250:251], v[10:11], v[142:143] op_sel:[0,1,0]
	v_add_f32_dpp v12, v252, v252 quad_perm:[1,0,3,2] row_mask:0xf bank_mask:0xf
	v_add_f32_dpp v13, v253, v253 quad_perm:[1,0,3,2] row_mask:0xf bank_mask:0xf
	v_add_f32_dpp v14, v254, v254 quad_perm:[1,0,3,2] row_mask:0xf bank_mask:0xf
	v_add_f32_dpp v15, v255, v255 quad_perm:[1,0,3,2] row_mask:0xf bank_mask:0xf
	v_cndmask_b32_e32 v12, v14, v12, vcc
	v_cndmask_b32_e32 v13, v15, v13, vcc
	v_add_f32_dpp v18, v16, v16 quad_perm:[2,3,0,1] row_mask:0xf bank_mask:0xf
	v_add_f32_dpp v19, v17, v17 quad_perm:[2,3,0,1] row_mask:0xf bank_mask:0xf
	v_cndmask_b32_e64 v16, v19, v18, s[4:5]
	v_cndmask_b32_e64 v21, v16, v20, s[6:7]
	v_cndmask_b32_e64 v22, v20, v16, s[6:7]
	s_waitcnt vmcnt(1)
	v_pk_mul_f32 v[252:253], v[236:237], v[4:5] op_sel_hi:[1,0]
	v_pk_mul_f32 v[254:255], v[244:245], v[4:5] op_sel_hi:[1,0]
	v_pk_fma_f32 v[252:253], v[238:239], v[4:5], v[252:253] op_sel:[0,1,0]
	v_pk_fma_f32 v[254:255], v[246:247], v[4:5], v[254:255] op_sel:[0,1,0]
	v_pk_fma_f32 v[252:253], v[240:241], v[6:7], v[252:253] op_sel_hi:[1,0,1]
	v_pk_fma_f32 v[254:255], v[248:249], v[6:7], v[254:255] op_sel_hi:[1,0,1]
	v_pk_fma_f32 v[252:253], v[242:243], v[6:7], v[252:253] op_sel:[0,1,0]
	v_pk_fma_f32 v[254:255], v[250:251], v[6:7], v[254:255] op_sel:[0,1,0]
	v_add_f32_dpp v20, v22, v21 row_ror:4 row_mask:0xf bank_mask:0xf
	v_cndmask_b32_e64 v29, v20, v28, s[64:65]
	v_cndmask_b32_e64 v30, v28, v20, s[64:65]
	v_add_f32_dpp v8, v140, v140 quad_perm:[1,0,3,2] row_mask:0xf bank_mask:0xf
	v_add_f32_dpp v9, v141, v141 quad_perm:[1,0,3,2] row_mask:0xf bank_mask:0xf
	v_add_f32_dpp v10, v142, v142 quad_perm:[1,0,3,2] row_mask:0xf bank_mask:0xf
	v_add_f32_dpp v11, v143, v143 quad_perm:[1,0,3,2] row_mask:0xf bank_mask:0xf
	v_cndmask_b32_e32 v8, v10, v8, vcc
	v_cndmask_b32_e32 v9, v11, v9, vcc
	v_add_f32_dpp v14, v12, v12 quad_perm:[2,3,0,1] row_mask:0xf bank_mask:0xf
	v_add_f32_dpp v15, v13, v13 quad_perm:[2,3,0,1] row_mask:0xf bank_mask:0xf
	v_cndmask_b32_e64 v12, v15, v14, s[4:5]
	s_waitcnt vmcnt(0)
	v_pk_mul_f32 v[140:141], v[236:237], v[0:1] op_sel_hi:[1,0]
	v_pk_mul_f32 v[142:143], v[244:245], v[0:1] op_sel_hi:[1,0]
	v_pk_fma_f32 v[140:141], v[238:239], v[0:1], v[140:141] op_sel:[0,1,0]
	v_pk_fma_f32 v[142:143], v[246:247], v[0:1], v[142:143] op_sel:[0,1,0]
	v_pk_fma_f32 v[140:141], v[240:241], v[2:3], v[140:141] op_sel_hi:[1,0,1]
	v_pk_fma_f32 v[142:143], v[248:249], v[2:3], v[142:143] op_sel_hi:[1,0,1]
	v_pk_fma_f32 v[140:141], v[242:243], v[2:3], v[140:141] op_sel:[0,1,0]
	v_pk_fma_f32 v[142:143], v[250:251], v[2:3], v[142:143] op_sel:[0,1,0]
	v_add_f32_dpp v28, v30, v29 row_ror:8 row_mask:0xf bank_mask:0xf
	v_add_f32_dpp v4, v252, v252 quad_perm:[1,0,3,2] row_mask:0xf bank_mask:0xf
	v_add_f32_dpp v5, v253, v253 quad_perm:[1,0,3,2] row_mask:0xf bank_mask:0xf
	v_add_f32_dpp v6, v254, v254 quad_perm:[1,0,3,2] row_mask:0xf bank_mask:0xf
	v_add_f32_dpp v7, v255, v255 quad_perm:[1,0,3,2] row_mask:0xf bank_mask:0xf
	v_cndmask_b32_e32 v4, v6, v4, vcc
	v_cndmask_b32_e32 v5, v7, v5, vcc
	v_add_f32_dpp v10, v8, v8 quad_perm:[2,3,0,1] row_mask:0xf bank_mask:0xf
	v_add_f32_dpp v11, v9, v9 quad_perm:[2,3,0,1] row_mask:0xf bank_mask:0xf
	v_cndmask_b32_e64 v8, v11, v10, s[4:5]
	v_cndmask_b32_e64 v13, v8, v12, s[6:7]
	v_cndmask_b32_e64 v14, v12, v8, s[6:7]
	s_nop 1
	v_add_f32_dpp v12, v14, v13 row_ror:4 row_mask:0xf bank_mask:0xf
	v_add_f32_dpp v0, v140, v140 quad_perm:[1,0,3,2] row_mask:0xf bank_mask:0xf
	v_add_f32_dpp v1, v141, v141 quad_perm:[1,0,3,2] row_mask:0xf bank_mask:0xf
	v_add_f32_dpp v2, v142, v142 quad_perm:[1,0,3,2] row_mask:0xf bank_mask:0xf
	v_add_f32_dpp v3, v143, v143 quad_perm:[1,0,3,2] row_mask:0xf bank_mask:0xf
	v_cndmask_b32_e32 v0, v2, v0, vcc
	v_cndmask_b32_e32 v1, v3, v1, vcc
	v_add_f32_dpp v6, v4, v4 quad_perm:[2,3,0,1] row_mask:0xf bank_mask:0xf
	v_add_f32_dpp v7, v5, v5 quad_perm:[2,3,0,1] row_mask:0xf bank_mask:0xf
	v_cndmask_b32_e64 v4, v7, v6, s[4:5]
	v_add_f32_dpp v2, v0, v0 quad_perm:[2,3,0,1] row_mask:0xf bank_mask:0xf
	v_add_f32_dpp v3, v1, v1 quad_perm:[2,3,0,1] row_mask:0xf bank_mask:0xf
	v_cndmask_b32_e64 v0, v3, v2, s[4:5]
	v_cndmask_b32_e64 v5, v0, v4, s[6:7]
	v_cndmask_b32_e64 v6, v4, v0, s[6:7]
	s_nop 1
	v_add_f32_dpp v4, v6, v5 row_ror:4 row_mask:0xf bank_mask:0xf
	v_cndmask_b32_e64 v13, v4, v12, s[64:65]
	v_cndmask_b32_e64 v14, v12, v4, s[64:65]
	s_nop 1
	v_add_f32_dpp v12, v14, v13 row_ror:8 row_mask:0xf bank_mask:0xf
	s_nop 1
	v_permlane16_swap_b32_e32 v28, v12
	v_add_f32_e32 v28, v28, v12
	s_nop 1
	v_permlane32_swap_b32_e32 v60, v28
	v_add_f32_e32 v60, v60, v28
	ds_write_b32 v235, v60 offset:64
	v_lshlrev_b32_e32 v2, 2, v223
	s_add_u32 s4, s14, s30
	s_addc_u32 s5, s15, s31
	v_lshlrev_b32_e32 v0, 2, v2
	s_waitcnt lgkmcnt(0)
; DI void lbar() { asm volatile("s_waitcnt lgkmcnt(0)" ::: "memory"); __builtin_amdgcn_s_barrier(); asm volatile("" ::: "memory"); }
; DI float wave_sum(float v) { for (int o = 32; o >= 1; o >>= 1) v += __shfl_xor(v, o); return v; }
; DI void attn_sample_item(const Params& p, int item, ldsp lds, int tid_) {
;     ...
;   for (int j = 0; j < 16; ++j) vvA[j] = __builtin_nontemporal_load((const f32x4*)(cv + (size_t)(wid * 32 + j) * 1024 + lane * 4));
;   lbar();
;   if (wid < 4) {
;     float v[4]; float mx = -1e30f;
; #pragma unroll
;     for (int j = 0; j < 4; ++j) { v[j] = SC[wid * 256 + j * 64 + lane]; mx = fmaxf(mx, v[j]); }
;     for (int o = 32; o >= 1; o >>= 1) mx = fmaxf(mx, __shfl_xor(mx, o));
;     float s = 0.f;
; #pragma unroll
;     for (int j = 0; j < 4; ++j) { v[j] = __expf(v[j] - mx); s += v[j]; }
;     s = wave_sum(s); const float inv = 1.f / s;
; #pragma unroll
;     for (int j = 0; j < 4; ++j) SC[wid * 256 + j * 64 + lane] = v[j] * inv;
	v_mov_b32_e32 v1, v145
	v_lshl_add_u64 v[0:1], s[4:5], 0, v[0:1]
	v_lshl_add_u64 v[4:5], v[0:1], 0, v[162:163]
	v_lshl_add_u64 v[6:7], v[0:1], 0, v[166:167]
	global_load_dwordx4 v[100:103], v[4:5], off nt
	global_load_dwordx4 v[92:95], v[6:7], off nt
	v_lshl_add_u64 v[4:5], v[0:1], 0, v[168:169]
	v_lshl_add_u64 v[6:7], v[0:1], 0, v[172:173]
	global_load_dwordx4 v[112:115], v[4:5], off nt
	global_load_dwordx4 v[108:111], v[6:7], off nt
	v_lshl_add_u64 v[4:5], v[0:1], 0, v[176:177]
	v_lshl_add_u64 v[6:7], v[0:1], 0, v[180:181]
	global_load_dwordx4 v[120:123], v[4:5], off nt
	global_load_dwordx4 v[116:119], v[6:7], off nt
	v_lshl_add_u64 v[4:5], v[0:1], 0, v[182:183]
	v_lshl_add_u64 v[6:7], v[0:1], 0, v[186:187]
	global_load_dwordx4 v[124:127], v[4:5], off nt
	global_load_dwordx4 v[104:107], v[6:7], off nt
	v_lshl_add_u64 v[4:5], v[0:1], 0, v[190:191]
	v_lshl_add_u64 v[6:7], v[0:1], 0, v[194:195]
	global_load_dwordx4 v[68:71], v[4:5], off nt
	global_load_dwordx4 v[64:67], v[6:7], off nt
	v_lshl_add_u64 v[4:5], v[0:1], 0, v[198:199]
	v_lshl_add_u64 v[6:7], v[0:1], 0, v[200:201]
	global_load_dwordx4 v[80:83], v[4:5], off nt
	global_load_dwordx4 v[76:79], v[6:7], off nt
	v_lshl_add_u64 v[4:5], v[0:1], 0, v[202:203]
	v_lshl_add_u64 v[6:7], v[0:1], 0, v[204:205]
	global_load_dwordx4 v[88:91], v[4:5], off nt
	global_load_dwordx4 v[84:87], v[6:7], off nt
	v_lshl_add_u64 v[4:5], v[0:1], 0, v[206:207]
	v_lshl_add_u64 v[6:7], v[0:1], 0, v[208:209]
	global_load_dwordx4 v[96:99], v[4:5], off nt
	global_load_dwordx4 v[72:75], v[6:7], off nt
	s_waitcnt lgkmcnt(0)
	s_barrier
	v_cmp_gt_i32_e32 vcc, 4, v210
	s_and_saveexec_b64 s[4:5], vcc
	s_cbranch_execz .LBB0_1603
	v_lshlrev_b32_e32 v3, 10, v210
	v_add3_u32 v6, 16, v3, v2
	ds_read2st64_b32 v[2:3], v6 offset1:1
	ds_read2st64_b32 v[4:5], v6 offset0:2 offset1:3
	s_waitcnt lgkmcnt(1)
	v_max3_f32 v7, v2, s39, v3
	s_waitcnt lgkmcnt(0)
	v_max3_f32 v7, v7, v4, v5
	ds_bpermute_b32 v8, v133, v7
	s_waitcnt lgkmcnt(0)
	v_max_f32_e32 v8, v8, v8
	v_max_f32_e32 v7, v7, v8
	ds_bpermute_b32 v8, v132, v7
	s_waitcnt lgkmcnt(0)
	v_max_f32_e32 v8, v8, v8
	v_max_f32_e32 v7, v7, v8
	ds_bpermute_b32 v8, v131, v7
	s_waitcnt lgkmcnt(0)
	v_max_f32_e32 v8, v8, v8
	v_max_f32_e32 v7, v7, v8
	ds_bpermute_b32 v8, v130, v7
	s_waitcnt lgkmcnt(0)
	v_max_f32_e32 v8, v8, v8
	v_max_f32_e32 v7, v7, v8
	ds_bpermute_b32 v8, v129, v7
	s_waitcnt lgkmcnt(0)
	v_max_f32_e32 v8, v8, v8
	v_max_f32_e32 v7, v7, v8
	ds_bpermute_b32 v8, v128, v7
	s_waitcnt lgkmcnt(0)
	v_max_f32_e32 v8, v8, v8
	v_max_f32_e32 v7, v7, v8
	v_sub_f32_e32 v2, v2, v7
	v_sub_f32_e32 v3, v3, v7
	v_mul_f32_e32 v2, 0x3fb8aa3b, v2
	v_sub_f32_e32 v4, v4, v7
	v_mul_f32_e32 v3, 0x3fb8aa3b, v3
	v_exp_f32_e32 v2, v2
	v_sub_f32_e32 v5, v5, v7
	v_mul_f32_e32 v4, 0x3fb8aa3b, v4
	v_exp_f32_e32 v3, v3
	v_mul_f32_e32 v5, 0x3fb8aa3b, v5
	v_exp_f32_e32 v4, v4
	v_exp_f32_e32 v5, v5
	v_add_f32_e32 v7, 0, v2
	v_add_f32_e32 v7, v3, v7
	v_add_f32_e32 v7, v4, v7
	v_add_f32_e32 v7, v5, v7
	ds_bpermute_b32 v8, v133, v7
	s_waitcnt lgkmcnt(0)
	v_add_f32_e32 v7, v7, v8
	ds_bpermute_b32 v8, v132, v7
	s_waitcnt lgkmcnt(0)
	v_add_f32_e32 v7, v7, v8
	ds_bpermute_b32 v8, v131, v7
	s_waitcnt lgkmcnt(0)
	v_add_f32_e32 v7, v7, v8
	ds_bpermute_b32 v8, v130, v7
	s_waitcnt lgkmcnt(0)
	v_add_f32_e32 v7, v7, v8
	ds_bpermute_b32 v8, v129, v7
	s_waitcnt lgkmcnt(0)
	v_add_f32_e32 v7, v7, v8
	ds_bpermute_b32 v8, v128, v7
	s_waitcnt lgkmcnt(0)
	v_add_f32_e32 v7, v7, v8
	v_div_scale_f32 v8, s[6:7], v7, v7, 1.0
	v_rcp_f32_e32 v9, v8
	v_div_scale_f32 v10, vcc, 1.0, v7, 1.0
	v_fma_f32 v11, -v8, v9, 1.0
	v_fmac_f32_e32 v9, v11, v9
	v_mul_f32_e32 v11, v10, v9
	v_fma_f32 v12, -v8, v11, v10
	v_fmac_f32_e32 v11, v12, v9
	v_fma_f32 v8, -v8, v11, v10
	v_div_fmas_f32 v8, v8, v9, v11
	v_div_fixup_f32 v7, v8, v7, 1.0
	v_mul_f32_e32 v2, v2, v7
	v_mul_f32_e32 v3, v3, v7
	v_mul_f32_e32 v4, v4, v7
	v_mul_f32_e32 v5, v5, v7
	ds_write2st64_b32 v6, v2, v3 offset1:1
	ds_write2st64_b32 v6, v4, v5 offset0:2 offset1:3
	s_branch .LBB0_1603

; DI void attn_sample_item(const Params& p, int item, ldsp lds, int tid_) {
;     ...
;   for (int t = 0; t < 4; ++t) { f32x4 a = {0.f, 0.f, 0.f, 0.f}; const float* pp = (const float*)(p.ws + B_PART) + (size_t)(b * 4 + t) * 1024 + h * 256 + lane * 4;
; #pragma unroll
;     for (int kp = 0; kp < 4; ++kp) a += *(const f32x4*)(pp + (size_t)kp * 512 * 1024);
;     q[t][0] = a[0] * 0.0625f; q[t][1] = a[1] * 0.0625f; q[t][2] = a[2] * 0.0625f; q[t][3] = a[3] * 0.0625f; }
;   const bool b0 = lane & 1, b1 = lane & 2;
;   f32x4 kvA[16], kvB[16];
; #pragma unroll
;   for (int j = 0; j < 16; ++j) kvA[j] = __builtin_nontemporal_load((const f32x4*)(ck + (size_t)(wid * 32 + j) * 1024 + lane * 4));
.LBB0_1676:
	s_ashr_i32 s4, s38, 2
	s_ashr_i32 s5, s4, 31
	s_lshl_b64 s[4:5], s[4:5], 18
	s_and_b32 s24, s0, 0x300
	v_mov_b32_e32 v222, v212
	s_or_b32 s4, s4, s24
	s_and_b32 s26, s38, -4
	s_lshl_b32 s6, s24, 2
	s_add_u32 s6, s36, s6
	v_and_b32_e32 v223, 63, v222
	s_addc_u32 s7, s37, 0
	v_lshlrev_b32_e32 v144, 4, v223
	s_ashr_i32 s27, s26, 31
	v_lshl_add_u64 v[48:49], s[6:7], 0, v[144:145]
	s_lshl_b64 s[6:7], s[26:27], 12
	v_lshl_add_u64 v[8:9], v[48:49], 0, s[6:7]
	v_add_co_u32_e32 v10, vcc, s3, v8
	s_or_b32 s6, s26, 1
	s_nop 0
	v_addc_co_u32_e32 v11, vcc, 0, v9, vcc
	global_load_dwordx4 v[0:3], v[8:9], off
	global_load_dwordx4 v[4:7], v[10:11], off
	v_add_co_u32_e32 v10, vcc, s33, v8
	s_ashr_i32 s7, s6, 31
	s_nop 0
	v_addc_co_u32_e32 v11, vcc, 0, v9, vcc
	v_add_co_u32_e32 v12, vcc, s34, v8
	s_lshl_b64 s[6:7], s[6:7], 12
	s_nop 0
	v_addc_co_u32_e32 v13, vcc, 0, v9, vcc
	v_lshl_add_u64 v[24:25], v[48:49], 0, s[6:7]
	v_add_co_u32_e32 v20, vcc, s3, v24
	s_or_b32 s6, s26, 2
	s_nop 0
	v_addc_co_u32_e32 v21, vcc, 0, v25, vcc
	v_add_co_u32_e32 v26, vcc, s33, v24
	s_ashr_i32 s7, s6, 31
	s_nop 0
	v_addc_co_u32_e32 v27, vcc, 0, v25, vcc
	v_add_co_u32_e32 v28, vcc, s34, v24
	s_lshl_b64 s[6:7], s[6:7], 12
	s_nop 0
	v_addc_co_u32_e32 v29, vcc, 0, v25, vcc
	v_lshl_add_u64 v[44:45], v[48:49], 0, s[6:7]
	global_load_dwordx4 v[8:11], v[10:11], off
	s_nop 0
	global_load_dwordx4 v[12:15], v[12:13], off
	s_nop 0
	global_load_dwordx4 v[16:19], v[24:25], off
	s_nop 0
	global_load_dwordx4 v[20:23], v[20:21], off
	v_add_co_u32_e32 v36, vcc, s3, v44
	global_load_dwordx4 v[24:27], v[26:27], off
	s_nop 0
	global_load_dwordx4 v[28:31], v[28:29], off
	v_addc_co_u32_e32 v37, vcc, 0, v45, vcc
	v_add_co_u32_e32 v40, vcc, s33, v44
	global_load_dwordx4 v[32:35], v[44:45], off
	s_nop 0
	global_load_dwordx4 v[36:39], v[36:37], off
	v_addc_co_u32_e32 v41, vcc, 0, v45, vcc
	v_add_co_u32_e32 v44, vcc, s34, v44
	global_load_dwordx4 v[40:43], v[40:41], off
	s_nop 0
	v_addc_co_u32_e32 v45, vcc, 0, v45, vcc
	global_load_dwordx4 v[44:47], v[44:45], off
	s_or_b32 s6, s38, 3
	s_ashr_i32 s7, s6, 31
	s_lshl_b64 s[6:7], s[6:7], 12
	s_lshl_b64 s[28:29], s[4:5], 2
	s_add_u32 s4, s12, s28
	s_addc_u32 s5, s13, s29
	s_waitcnt vmcnt(11)
	v_pk_add_f32 v[2:3], v[2:3], 0 op_sel_hi:[1,0]
	v_pk_add_f32 v[0:1], v[0:1], 0 op_sel_hi:[1,0]
	s_waitcnt vmcnt(10)
	v_pk_add_f32 v[2:3], v[2:3], v[6:7]
	v_pk_add_f32 v[0:1], v[0:1], v[4:5]
	s_waitcnt vmcnt(9)
	v_pk_add_f32 v[2:3], v[2:3], v[10:11]
	s_waitcnt vmcnt(7)
	v_pk_add_f32 v[4:5], v[18:19], 0 op_sel_hi:[1,0]
	v_pk_add_f32 v[6:7], v[16:17], 0 op_sel_hi:[1,0]
	v_pk_add_f32 v[0:1], v[0:1], v[8:9]
	s_waitcnt vmcnt(6)
	v_pk_add_f32 v[4:5], v[4:5], v[22:23]
	v_pk_add_f32 v[6:7], v[6:7], v[20:21]
	v_pk_add_f32 v[2:3], v[2:3], v[14:15]
	v_pk_add_f32 v[0:1], v[0:1], v[12:13]
	s_waitcnt vmcnt(5)
	v_pk_add_f32 v[4:5], v[4:5], v[26:27]
	v_pk_add_f32 v[6:7], v[6:7], v[24:25]
	v_mul_f32_e32 v228, 0x3d800000, v0
	v_mul_f32_e32 v231, 0x3d800000, v1
	v_mul_f32_e32 v229, 0x3d800000, v2
	v_mul_f32_e32 v225, 0x3d800000, v3
	s_waitcnt vmcnt(4)
	v_pk_add_f32 v[0:1], v[4:5], v[30:31]
	v_pk_add_f32 v[2:3], v[6:7], v[28:29]
	v_mul_f32_e32 v227, 0x3d800000, v0
	v_mul_f32_e32 v226, 0x3d800000, v2
	v_mul_f32_e32 v230, 0x3d800000, v3
	v_mul_f32_e32 v224, 0x3d800000, v1
	s_waitcnt vmcnt(3)
	v_pk_add_f32 v[0:1], v[34:35], 0 op_sel_hi:[1,0]
	v_pk_add_f32 v[2:3], v[32:33], 0 op_sel_hi:[1,0]
	s_waitcnt vmcnt(2)
	v_pk_add_f32 v[0:1], v[0:1], v[38:39]
	v_pk_add_f32 v[2:3], v[2:3], v[36:37]
	s_waitcnt vmcnt(1)
	v_pk_add_f32 v[0:1], v[0:1], v[42:43]
	v_pk_add_f32 v[2:3], v[2:3], v[40:41]
	s_waitcnt vmcnt(0)
	v_pk_add_f32 v[210:211], v[0:1], v[46:47]
	v_pk_add_f32 v[0:1], v[2:3], v[44:45]
	v_mul_f32_e32 v233, 0x3d800000, v210
	v_mul_f32_e32 v232, 0x3d800000, v0
	v_mul_f32_e32 v234, 0x3d800000, v1
	v_lshl_add_u64 v[0:1], v[48:49], 0, s[6:7]
	v_add_co_u32_e32 v2, vcc, s3, v0
	v_ashrrev_i32_e32 v210, 6, v222
	s_nop 0
	v_addc_co_u32_e32 v3, vcc, 0, v1, vcc
	global_load_dwordx4 v[128:131], v[0:1], off
	global_load_dwordx4 v[132:135], v[2:3], off
	v_add_co_u32_e32 v2, vcc, s33, v0
	v_mul_f32_e32 v211, 0x3d800000, v211
	s_nop 0
	v_addc_co_u32_e32 v3, vcc, 0, v1, vcc
	v_add_co_u32_e32 v0, vcc, s34, v0
	v_cmp_lt_i32_e64 s[6:7], v218, v216
	s_nop 0
	v_addc_co_u32_e32 v1, vcc, 0, v1, vcc
	global_load_dwordx4 v[136:139], v[2:3], off
	global_load_dwordx4 v[140:143], v[0:1], off
	v_lshlrev_b32_e32 v0, 5, v210
	v_ashrrev_i32_e32 v1, 31, v0
	v_or_b32_e32 v6, 1, v0
	v_lshl_add_u64 v[2:3], s[4:5], 0, v[144:145]
	v_lshlrev_b64 v[158:159], 12, v[0:1]
	v_ashrrev_i32_e32 v7, 31, v6
	v_lshl_add_u64 v[4:5], v[2:3], 0, v[158:159]
	v_lshlrev_b64 v[162:163], 12, v[6:7]
	v_lshl_add_u64 v[6:7], v[2:3], 0, v[162:163]
	global_load_dwordx4 v[124:127], v[4:5], off nt
	global_load_dwordx4 v[120:123], v[6:7], off nt
	v_or_b32_e32 v4, 2, v0
	v_ashrrev_i32_e32 v5, 31, v4
	v_or_b32_e32 v6, 3, v0
	v_lshlrev_b64 v[164:165], 12, v[4:5]
	v_ashrrev_i32_e32 v7, 31, v6
	v_lshl_add_u64 v[4:5], v[2:3], 0, v[164:165]
	v_lshlrev_b64 v[168:169], 12, v[6:7]
	v_lshl_add_u64 v[6:7], v[2:3], 0, v[168:169]
	global_load_dwordx4 v[116:119], v[4:5], off nt
	global_load_dwordx4 v[112:115], v[6:7], off nt
	v_or_b32_e32 v4, 4, v0
	v_ashrrev_i32_e32 v5, 31, v4
	v_or_b32_e32 v6, 5, v0
	v_lshlrev_b64 v[172:173], 12, v[4:5]
	v_ashrrev_i32_e32 v7, 31, v6
	v_lshl_add_u64 v[4:5], v[2:3], 0, v[172:173]
	v_lshlrev_b64 v[176:177], 12, v[6:7]
	v_lshl_add_u64 v[6:7], v[2:3], 0, v[176:177]
	global_load_dwordx4 v[108:111], v[4:5], off nt
	global_load_dwordx4 v[104:107], v[6:7], off nt
	v_or_b32_e32 v4, 6, v0
	v_ashrrev_i32_e32 v5, 31, v4
	v_or_b32_e32 v6, 7, v0
; DI void attn_sample_item(const Params& p, int item, ldsp lds, int tid_) {
;     ...
;   for (int t = 0; t < 4; ++t) { f32x4 a = {0.f, 0.f, 0.f, 0.f}; const float* pp = (const float*)(p.ws + B_PART) + (size_t)(b * 4 + t) * 1024 + h * 256 + lane * 4;
; #pragma unroll
;     for (int kp = 0; kp < 4; ++kp) a += *(const f32x4*)(pp + (size_t)kp * 512 * 1024);
;     q[t][0] = a[0] * 0.0625f; q[t][1] = a[1] * 0.0625f; q[t][2] = a[2] * 0.0625f; q[t][3] = a[3] * 0.0625f; }
;     ...
;   for (int j = 0; j < 16; ++j) kvA[j] = __builtin_nontemporal_load((const f32x4*)(ck + (size_t)(wid * 32 + j) * 1024 + lane * 4));
; #pragma unroll
;   for (int j = 0; j < 16; ++j) kvB[j] = __builtin_nontemporal_load((const f32x4*)(ck + (size_t)(wid * 32 + 16 + j) * 1024 + lane * 4));
	v_lshlrev_b64 v[180:181], 12, v[4:5]
	v_ashrrev_i32_e32 v7, 31, v6
	v_lshl_add_u64 v[4:5], v[2:3], 0, v[180:181]
	v_lshlrev_b64 v[184:185], 12, v[6:7]
	v_lshl_add_u64 v[6:7], v[2:3], 0, v[184:185]
	global_load_dwordx4 v[100:103], v[4:5], off nt
	global_load_dwordx4 v[96:99], v[6:7], off nt
	v_or_b32_e32 v4, 8, v0
	v_ashrrev_i32_e32 v5, 31, v4
	v_or_b32_e32 v6, 9, v0
	v_lshlrev_b64 v[188:189], 12, v[4:5]
	v_ashrrev_i32_e32 v7, 31, v6
	v_lshl_add_u64 v[4:5], v[2:3], 0, v[188:189]
	v_lshlrev_b64 v[192:193], 12, v[6:7]
	v_lshl_add_u64 v[6:7], v[2:3], 0, v[192:193]
	global_load_dwordx4 v[92:95], v[4:5], off nt
	global_load_dwordx4 v[88:91], v[6:7], off nt
	v_or_b32_e32 v4, 10, v0
	v_ashrrev_i32_e32 v5, 31, v4
	v_or_b32_e32 v6, 11, v0
	v_lshlrev_b64 v[196:197], 12, v[4:5]
	v_ashrrev_i32_e32 v7, 31, v6
	v_lshl_add_u64 v[4:5], v[2:3], 0, v[196:197]
	v_lshlrev_b64 v[200:201], 12, v[6:7]
	v_lshl_add_u64 v[6:7], v[2:3], 0, v[200:201]
	global_load_dwordx4 v[84:87], v[4:5], off nt
	global_load_dwordx4 v[80:83], v[6:7], off nt
	v_or_b32_e32 v4, 12, v0
	v_ashrrev_i32_e32 v5, 31, v4
	v_or_b32_e32 v6, 13, v0
	v_lshlrev_b64 v[202:203], 12, v[4:5]
	v_ashrrev_i32_e32 v7, 31, v6
	v_lshl_add_u64 v[4:5], v[2:3], 0, v[202:203]
	v_lshlrev_b64 v[204:205], 12, v[6:7]
	v_lshl_add_u64 v[6:7], v[2:3], 0, v[204:205]
	global_load_dwordx4 v[76:79], v[4:5], off nt
	global_load_dwordx4 v[72:75], v[6:7], off nt
	v_or_b32_e32 v4, 14, v0
	v_ashrrev_i32_e32 v5, 31, v4
	v_or_b32_e32 v6, 15, v0
	v_lshlrev_b64 v[206:207], 12, v[4:5]
	v_ashrrev_i32_e32 v7, 31, v6
	v_lshl_add_u64 v[4:5], v[2:3], 0, v[206:207]
	v_lshlrev_b64 v[208:209], 12, v[6:7]
	v_lshl_add_u64 v[6:7], v[2:3], 0, v[208:209]
	global_load_dwordx4 v[68:71], v[4:5], off nt
	global_load_dwordx4 v[64:67], v[6:7], off nt
	v_or_b32_e32 v4, 16, v0
	v_ashrrev_i32_e32 v5, 31, v4
	v_or_b32_e32 v6, 17, v0
	v_lshlrev_b64 v[146:147], 12, v[4:5]
	v_ashrrev_i32_e32 v7, 31, v6
	v_lshl_add_u64 v[4:5], v[2:3], 0, v[146:147]
	v_lshlrev_b64 v[148:149], 12, v[6:7]
	v_lshl_add_u64 v[6:7], v[2:3], 0, v[148:149]
	global_load_dwordx4 v[60:63], v[4:5], off nt
	global_load_dwordx4 v[56:59], v[6:7], off nt
	v_or_b32_e32 v4, 18, v0
	v_ashrrev_i32_e32 v5, 31, v4
	v_or_b32_e32 v6, 19, v0
	v_lshlrev_b64 v[150:151], 12, v[4:5]
	v_ashrrev_i32_e32 v7, 31, v6
	v_lshl_add_u64 v[4:5], v[2:3], 0, v[150:151]
	v_lshlrev_b64 v[152:153], 12, v[6:7]
	v_lshl_add_u64 v[6:7], v[2:3], 0, v[152:153]
	global_load_dwordx4 v[52:55], v[4:5], off nt
	global_load_dwordx4 v[48:51], v[6:7], off nt
	v_or_b32_e32 v4, 20, v0
	v_ashrrev_i32_e32 v5, 31, v4
	v_or_b32_e32 v6, 21, v0
	v_lshlrev_b64 v[154:155], 12, v[4:5]
	v_ashrrev_i32_e32 v7, 31, v6
	v_lshl_add_u64 v[4:5], v[2:3], 0, v[154:155]
	v_lshlrev_b64 v[156:157], 12, v[6:7]
	v_lshl_add_u64 v[6:7], v[2:3], 0, v[156:157]
	global_load_dwordx4 v[44:47], v[4:5], off nt
	global_load_dwordx4 v[40:43], v[6:7], off nt
	v_or_b32_e32 v4, 22, v0
	v_ashrrev_i32_e32 v5, 31, v4
	v_or_b32_e32 v6, 23, v0
	v_lshlrev_b64 v[160:161], 12, v[4:5]
	v_ashrrev_i32_e32 v7, 31, v6
	v_lshl_add_u64 v[4:5], v[2:3], 0, v[160:161]
	v_lshlrev_b64 v[166:167], 12, v[6:7]
	v_lshl_add_u64 v[6:7], v[2:3], 0, v[166:167]
	global_load_dwordx4 v[36:39], v[4:5], off nt
	global_load_dwordx4 v[32:35], v[6:7], off nt
	v_or_b32_e32 v4, 24, v0
	v_ashrrev_i32_e32 v5, 31, v4
	v_or_b32_e32 v6, 25, v0
	v_lshlrev_b64 v[170:171], 12, v[4:5]
	v_ashrrev_i32_e32 v7, 31, v6
	v_lshl_add_u64 v[4:5], v[2:3], 0, v[170:171]
	v_lshlrev_b64 v[174:175], 12, v[6:7]
	v_lshl_add_u64 v[6:7], v[2:3], 0, v[174:175]
	global_load_dwordx4 v[28:31], v[4:5], off nt
	global_load_dwordx4 v[24:27], v[6:7], off nt
	v_or_b32_e32 v4, 26, v0
	v_ashrrev_i32_e32 v5, 31, v4
	v_or_b32_e32 v6, 27, v0
	v_lshlrev_b64 v[178:179], 12, v[4:5]
	v_ashrrev_i32_e32 v7, 31, v6
	v_lshl_add_u64 v[4:5], v[2:3], 0, v[178:179]
	v_lshlrev_b64 v[182:183], 12, v[6:7]
	v_lshl_add_u64 v[6:7], v[2:3], 0, v[182:183]
	global_load_dwordx4 v[20:23], v[4:5], off nt
	global_load_dwordx4 v[16:19], v[6:7], off nt
	v_or_b32_e32 v4, 28, v0
	v_ashrrev_i32_e32 v5, 31, v4
	v_or_b32_e32 v6, 29, v0
	v_lshlrev_b64 v[186:187], 12, v[4:5]
	v_ashrrev_i32_e32 v7, 31, v6
	v_lshl_add_u64 v[4:5], v[2:3], 0, v[186:187]
	v_lshlrev_b64 v[190:191], 12, v[6:7]
	v_lshl_add_u64 v[6:7], v[2:3], 0, v[190:191]
	global_load_dwordx4 v[12:15], v[4:5], off nt
	global_load_dwordx4 v[8:11], v[6:7], off nt
	v_or_b32_e32 v4, 30, v0
	v_or_b32_e32 v0, 31, v0
	v_ashrrev_i32_e32 v5, 31, v4
	v_ashrrev_i32_e32 v1, 31, v0
	v_lshlrev_b64 v[194:195], 12, v[4:5]
	v_lshlrev_b64 v[198:199], 12, v[0:1]
	v_lshl_add_u64 v[4:5], v[2:3], 0, v[194:195]
	v_lshl_add_u64 v[0:1], v[2:3], 0, v[198:199]
	global_load_dwordx4 v[4:7], v[4:5], off nt
	s_nop 0
	global_load_dwordx4 v[0:3], v[0:1], off nt
	s_waitcnt vmcnt(35)
	v_pk_add_f32 v[128:129], v[128:129], 0 op_sel_hi:[1,0]
	v_pk_add_f32 v[130:131], v[130:131], 0 op_sel_hi:[1,0]
	s_waitcnt vmcnt(34)
	v_pk_add_f32 v[128:129], v[128:129], v[132:133]
	v_pk_add_f32 v[130:131], v[130:131], v[134:135]
	s_waitcnt vmcnt(33)
	v_pk_add_f32 v[128:129], v[128:129], v[136:137]
	v_pk_add_f32 v[130:131], v[130:131], v[138:139]
	s_waitcnt vmcnt(32)
; DI void attn_sample_item(const Params& p, int item, ldsp lds, int tid_) {
;     ...
;   const bool b0 = lane & 1, b1 = lane & 2;
	v_pk_add_f32 v[128:129], v[128:129], v[140:141]
	v_pk_add_f32 v[130:131], v[130:131], v[142:143]
	v_mul_f32_e32 v138, 0x3d800000, v129
	v_mul_f32_e32 v135, 0x3d800000, v128
	v_mul_f32_e32 v134, 0x3d800000, v131
	v_mul_f32_e32 v137, 0x3d800000, v130
	v_lshlrev_b32_e32 v128, 2, v215
	v_lshlrev_b32_e32 v129, 2, v217
	v_lshlrev_b32_e32 v130, 2, v218
	v_lshlrev_b32_e32 v131, 2, v219
	v_lshlrev_b32_e32 v132, 2, v220
	v_lshlrev_b32_e32 v133, 2, v221
	v_lshl_add_u32 v136, v210, 7, 16
	v_and_b32_e32 v139, 3, v223
	v_bfrev_b32_e32 v139, v139
	v_lshrrev_b32_e32 v139, 20, v139
	v_and_b32_e32 v235, -4, v223
	v_add3_u32 v235, v136, v139, v235
	v_mov_b32_e32 v236, v228
	v_mov_b32_e32 v237, v226
	v_mov_b32_e32 v238, v231
	v_mov_b32_e32 v239, v230
	v_mov_b32_e32 v240, v229
	v_mov_b32_e32 v241, v227
	v_mov_b32_e32 v242, v225
	v_mov_b32_e32 v243, v224
	v_mov_b32_e32 v244, v232
	v_mov_b32_e32 v245, v135
	v_mov_b32_e32 v246, v234
	v_mov_b32_e32 v247, v138
	v_mov_b32_e32 v248, v233
	v_mov_b32_e32 v249, v137
	v_mov_b32_e32 v250, v211
	v_mov_b32_e32 v251, v134
	s_mov_b32 vcc_lo, 0x55555555
	s_mov_b32 vcc_hi, 0x55555555
	s_mov_b32 s4, 0x33333333
	s_mov_b32 s5, 0x33333333
	s_mov_b32 s6, 0x0f0f0f0f
	s_mov_b32 s7, 0x0f0f0f0f
	s_mov_b32 s64, 0x00ff00ff
	s_mov_b32 s65, 0x00ff00ff
	s_waitcnt vmcnt(31)
	v_pk_mul_f32 v[252:253], v[236:237], v[124:125] op_sel_hi:[1,0]
	v_pk_mul_f32 v[254:255], v[244:245], v[124:125] op_sel_hi:[1,0]
	v_pk_fma_f32 v[252:253], v[238:239], v[124:125], v[252:253] op_sel:[0,1,0]
	v_pk_fma_f32 v[254:255], v[246:247], v[124:125], v[254:255] op_sel:[0,1,0]
	v_pk_fma_f32 v[252:253], v[240:241], v[126:127], v[252:253] op_sel_hi:[1,0,1]
	v_pk_fma_f32 v[254:255], v[248:249], v[126:127], v[254:255] op_sel_hi:[1,0,1]
	v_pk_fma_f32 v[252:253], v[242:243], v[126:127], v[252:253] op_sel:[0,1,0]
	v_pk_fma_f32 v[254:255], v[250:251], v[126:127], v[254:255] op_sel:[0,1,0]
	s_waitcnt vmcnt(30)
	v_pk_mul_f32 v[140:141], v[236:237], v[120:121] op_sel_hi:[1,0]
	v_pk_mul_f32 v[142:143], v[244:245], v[120:121] op_sel_hi:[1,0]
	v_pk_fma_f32 v[140:141], v[238:239], v[120:121], v[140:141] op_sel:[0,1,0]
	v_pk_fma_f32 v[142:143], v[246:247], v[120:121], v[142:143] op_sel:[0,1,0]
	v_pk_fma_f32 v[140:141], v[240:241], v[122:123], v[140:141] op_sel_hi:[1,0,1]
	v_pk_fma_f32 v[142:143], v[248:249], v[122:123], v[142:143] op_sel_hi:[1,0,1]
	v_pk_fma_f32 v[140:141], v[242:243], v[122:123], v[140:141] op_sel:[0,1,0]
	v_pk_fma_f32 v[142:143], v[250:251], v[122:123], v[142:143] op_sel:[0,1,0]
	v_add_f32_dpp v124, v252, v252 quad_perm:[1,0,3,2] row_mask:0xf bank_mask:0xf
	v_add_f32_dpp v125, v253, v253 quad_perm:[1,0,3,2] row_mask:0xf bank_mask:0xf
	v_add_f32_dpp v126, v254, v254 quad_perm:[1,0,3,2] row_mask:0xf bank_mask:0xf
	v_add_f32_dpp v127, v255, v255 quad_perm:[1,0,3,2] row_mask:0xf bank_mask:0xf
	v_cndmask_b32_e32 v124, v126, v124, vcc
	v_cndmask_b32_e32 v125, v127, v125, vcc
	s_waitcnt vmcnt(29)
	v_pk_mul_f32 v[252:253], v[236:237], v[116:117] op_sel_hi:[1,0]
	v_pk_mul_f32 v[254:255], v[244:245], v[116:117] op_sel_hi:[1,0]
	v_pk_fma_f32 v[252:253], v[238:239], v[116:117], v[252:253] op_sel:[0,1,0]
	v_pk_fma_f32 v[254:255], v[246:247], v[116:117], v[254:255] op_sel:[0,1,0]
	v_pk_fma_f32 v[252:253], v[240:241], v[118:119], v[252:253] op_sel_hi:[1,0,1]
	v_pk_fma_f32 v[254:255], v[248:249], v[118:119], v[254:255] op_sel_hi:[1,0,1]
	v_pk_fma_f32 v[252:253], v[242:243], v[118:119], v[252:253] op_sel:[0,1,0]
	v_pk_fma_f32 v[254:255], v[250:251], v[118:119], v[254:255] op_sel:[0,1,0]
	v_add_f32_dpp v120, v140, v140 quad_perm:[1,0,3,2] row_mask:0xf bank_mask:0xf
	v_add_f32_dpp v121, v141, v141 quad_perm:[1,0,3,2] row_mask:0xf bank_mask:0xf
	v_add_f32_dpp v122, v142, v142 quad_perm:[1,0,3,2] row_mask:0xf bank_mask:0xf
	v_add_f32_dpp v123, v143, v143 quad_perm:[1,0,3,2] row_mask:0xf bank_mask:0xf
	v_cndmask_b32_e32 v120, v122, v120, vcc
	v_cndmask_b32_e32 v121, v123, v121, vcc
	v_add_f32_dpp v126, v124, v124 quad_perm:[2,3,0,1] row_mask:0xf bank_mask:0xf
	v_add_f32_dpp v127, v125, v125 quad_perm:[2,3,0,1] row_mask:0xf bank_mask:0xf
	v_cndmask_b32_e64 v124, v127, v126, s[4:5]
	s_waitcnt vmcnt(28)
	v_pk_mul_f32 v[140:141], v[236:237], v[112:113] op_sel_hi:[1,0]
	v_pk_mul_f32 v[142:143], v[244:245], v[112:113] op_sel_hi:[1,0]
	v_pk_fma_f32 v[140:141], v[238:239], v[112:113], v[140:141] op_sel:[0,1,0]
	v_pk_fma_f32 v[142:143], v[246:247], v[112:113], v[142:143] op_sel:[0,1,0]
	v_pk_fma_f32 v[140:141], v[240:241], v[114:115], v[140:141] op_sel_hi:[1,0,1]
	v_pk_fma_f32 v[142:143], v[248:249], v[114:115], v[142:143] op_sel_hi:[1,0,1]
	v_pk_fma_f32 v[140:141], v[242:243], v[114:115], v[140:141] op_sel:[0,1,0]
	v_pk_fma_f32 v[142:143], v[250:251], v[114:115], v[142:143] op_sel:[0,1,0]
	v_add_f32_dpp v116, v252, v252 quad_perm:[1,0,3,2] row_mask:0xf bank_mask:0xf
	v_add_f32_dpp v117, v253, v253 quad_perm:[1,0,3,2] row_mask:0xf bank_mask:0xf
	v_add_f32_dpp v118, v254, v254 quad_perm:[1,0,3,2] row_mask:0xf bank_mask:0xf
	v_add_f32_dpp v119, v255, v255 quad_perm:[1,0,3,2] row_mask:0xf bank_mask:0xf
	v_cndmask_b32_e32 v116, v118, v116, vcc
	v_cndmask_b32_e32 v117, v119, v117, vcc
	v_add_f32_dpp v122, v120, v120 quad_perm:[2,3,0,1] row_mask:0xf bank_mask:0xf
	v_add_f32_dpp v123, v121, v121 quad_perm:[2,3,0,1] row_mask:0xf bank_mask:0xf
	v_cndmask_b32_e64 v120, v123, v122, s[4:5]
	v_cndmask_b32_e64 v125, v120, v124, s[6:7]
	v_cndmask_b32_e64 v126, v124, v120, s[6:7]
	s_waitcnt vmcnt(27)
; DI void attn_sample_item(const Params& p, int item, ldsp lds, int tid_) {
;     ...
;   SC_SCORE(kvA, 0)
;   SC_SCORE(kvB, 1)
	v_pk_mul_f32 v[252:253], v[236:237], v[108:109] op_sel_hi:[1,0]
	v_pk_mul_f32 v[254:255], v[244:245], v[108:109] op_sel_hi:[1,0]
	v_pk_fma_f32 v[252:253], v[238:239], v[108:109], v[252:253] op_sel:[0,1,0]
	v_pk_fma_f32 v[254:255], v[246:247], v[108:109], v[254:255] op_sel:[0,1,0]
	v_pk_fma_f32 v[252:253], v[240:241], v[110:111], v[252:253] op_sel_hi:[1,0,1]
	v_pk_fma_f32 v[254:255], v[248:249], v[110:111], v[254:255] op_sel_hi:[1,0,1]
	v_pk_fma_f32 v[252:253], v[242:243], v[110:111], v[252:253] op_sel:[0,1,0]
	v_pk_fma_f32 v[254:255], v[250:251], v[110:111], v[254:255] op_sel:[0,1,0]
	v_add_f32_dpp v124, v126, v125 row_ror:4 row_mask:0xf bank_mask:0xf
	v_add_f32_dpp v112, v140, v140 quad_perm:[1,0,3,2] row_mask:0xf bank_mask:0xf
	v_add_f32_dpp v113, v141, v141 quad_perm:[1,0,3,2] row_mask:0xf bank_mask:0xf
	v_add_f32_dpp v114, v142, v142 quad_perm:[1,0,3,2] row_mask:0xf bank_mask:0xf
	v_add_f32_dpp v115, v143, v143 quad_perm:[1,0,3,2] row_mask:0xf bank_mask:0xf
	v_cndmask_b32_e32 v112, v114, v112, vcc
	v_cndmask_b32_e32 v113, v115, v113, vcc
	v_add_f32_dpp v118, v116, v116 quad_perm:[2,3,0,1] row_mask:0xf bank_mask:0xf
	v_add_f32_dpp v119, v117, v117 quad_perm:[2,3,0,1] row_mask:0xf bank_mask:0xf
	v_cndmask_b32_e64 v116, v119, v118, s[4:5]
	s_waitcnt vmcnt(26)
	v_pk_mul_f32 v[140:141], v[236:237], v[104:105] op_sel_hi:[1,0]
	v_pk_mul_f32 v[142:143], v[244:245], v[104:105] op_sel_hi:[1,0]
	v_pk_fma_f32 v[140:141], v[238:239], v[104:105], v[140:141] op_sel:[0,1,0]
	v_pk_fma_f32 v[142:143], v[246:247], v[104:105], v[142:143] op_sel:[0,1,0]
	v_pk_fma_f32 v[140:141], v[240:241], v[106:107], v[140:141] op_sel_hi:[1,0,1]
	v_pk_fma_f32 v[142:143], v[248:249], v[106:107], v[142:143] op_sel_hi:[1,0,1]
	v_pk_fma_f32 v[140:141], v[242:243], v[106:107], v[140:141] op_sel:[0,1,0]
	v_pk_fma_f32 v[142:143], v[250:251], v[106:107], v[142:143] op_sel:[0,1,0]
	v_add_f32_dpp v108, v252, v252 quad_perm:[1,0,3,2] row_mask:0xf bank_mask:0xf
	v_add_f32_dpp v109, v253, v253 quad_perm:[1,0,3,2] row_mask:0xf bank_mask:0xf
	v_add_f32_dpp v110, v254, v254 quad_perm:[1,0,3,2] row_mask:0xf bank_mask:0xf
	v_add_f32_dpp v111, v255, v255 quad_perm:[1,0,3,2] row_mask:0xf bank_mask:0xf
	v_cndmask_b32_e32 v108, v110, v108, vcc
	v_cndmask_b32_e32 v109, v111, v109, vcc
	v_add_f32_dpp v114, v112, v112 quad_perm:[2,3,0,1] row_mask:0xf bank_mask:0xf
	v_add_f32_dpp v115, v113, v113 quad_perm:[2,3,0,1] row_mask:0xf bank_mask:0xf
	v_cndmask_b32_e64 v112, v115, v114, s[4:5]
	v_cndmask_b32_e64 v117, v112, v116, s[6:7]
	v_cndmask_b32_e64 v118, v116, v112, s[6:7]
	s_waitcnt vmcnt(25)
	v_pk_mul_f32 v[252:253], v[236:237], v[100:101] op_sel_hi:[1,0]
	v_pk_mul_f32 v[254:255], v[244:245], v[100:101] op_sel_hi:[1,0]
	v_pk_fma_f32 v[252:253], v[238:239], v[100:101], v[252:253] op_sel:[0,1,0]
	v_pk_fma_f32 v[254:255], v[246:247], v[100:101], v[254:255] op_sel:[0,1,0]
	v_pk_fma_f32 v[252:253], v[240:241], v[102:103], v[252:253] op_sel_hi:[1,0,1]
	v_pk_fma_f32 v[254:255], v[248:249], v[102:103], v[254:255] op_sel_hi:[1,0,1]
	v_pk_fma_f32 v[252:253], v[242:243], v[102:103], v[252:253] op_sel:[0,1,0]
	v_pk_fma_f32 v[254:255], v[250:251], v[102:103], v[254:255] op_sel:[0,1,0]
	v_add_f32_dpp v116, v118, v117 row_ror:4 row_mask:0xf bank_mask:0xf
	v_cndmask_b32_e64 v125, v116, v124, s[64:65]
	v_cndmask_b32_e64 v126, v124, v116, s[64:65]
	v_add_f32_dpp v104, v140, v140 quad_perm:[1,0,3,2] row_mask:0xf bank_mask:0xf
	v_add_f32_dpp v105, v141, v141 quad_perm:[1,0,3,2] row_mask:0xf bank_mask:0xf
	v_add_f32_dpp v106, v142, v142 quad_perm:[1,0,3,2] row_mask:0xf bank_mask:0xf
	v_add_f32_dpp v107, v143, v143 quad_perm:[1,0,3,2] row_mask:0xf bank_mask:0xf
	v_cndmask_b32_e32 v104, v106, v104, vcc
	v_cndmask_b32_e32 v105, v107, v105, vcc
	v_add_f32_dpp v110, v108, v108 quad_perm:[2,3,0,1] row_mask:0xf bank_mask:0xf
	v_add_f32_dpp v111, v109, v109 quad_perm:[2,3,0,1] row_mask:0xf bank_mask:0xf
	v_cndmask_b32_e64 v108, v111, v110, s[4:5]
	s_waitcnt vmcnt(24)
	v_pk_mul_f32 v[140:141], v[236:237], v[96:97] op_sel_hi:[1,0]
	v_pk_mul_f32 v[142:143], v[244:245], v[96:97] op_sel_hi:[1,0]
	v_pk_fma_f32 v[140:141], v[238:239], v[96:97], v[140:141] op_sel:[0,1,0]
	v_pk_fma_f32 v[142:143], v[246:247], v[96:97], v[142:143] op_sel:[0,1,0]
	v_pk_fma_f32 v[140:141], v[240:241], v[98:99], v[140:141] op_sel_hi:[1,0,1]
	v_pk_fma_f32 v[142:143], v[248:249], v[98:99], v[142:143] op_sel_hi:[1,0,1]
	v_pk_fma_f32 v[140:141], v[242:243], v[98:99], v[140:141] op_sel:[0,1,0]
	v_pk_fma_f32 v[142:143], v[250:251], v[98:99], v[142:143] op_sel:[0,1,0]
	v_add_f32_dpp v124, v126, v125 row_ror:8 row_mask:0xf bank_mask:0xf
	v_add_f32_dpp v100, v252, v252 quad_perm:[1,0,3,2] row_mask:0xf bank_mask:0xf
	v_add_f32_dpp v101, v253, v253 quad_perm:[1,0,3,2] row_mask:0xf bank_mask:0xf
	v_add_f32_dpp v102, v254, v254 quad_perm:[1,0,3,2] row_mask:0xf bank_mask:0xf
	v_add_f32_dpp v103, v255, v255 quad_perm:[1,0,3,2] row_mask:0xf bank_mask:0xf
	v_cndmask_b32_e32 v100, v102, v100, vcc
	v_cndmask_b32_e32 v101, v103, v101, vcc
	v_add_f32_dpp v106, v104, v104 quad_perm:[2,3,0,1] row_mask:0xf bank_mask:0xf
	v_add_f32_dpp v107, v105, v105 quad_perm:[2,3,0,1] row_mask:0xf bank_mask:0xf
	v_cndmask_b32_e64 v104, v107, v106, s[4:5]
	v_cndmask_b32_e64 v109, v104, v108, s[6:7]
	v_cndmask_b32_e64 v110, v108, v104, s[6:7]
	s_waitcnt vmcnt(23)
; DI void attn_sample_item(const Params& p, int item, ldsp lds, int tid_) {
;     ...
;   SC_SCORE(kvA, 0)
;   SC_SCORE(kvB, 1)
	v_pk_mul_f32 v[252:253], v[236:237], v[92:93] op_sel_hi:[1,0]
	v_pk_mul_f32 v[254:255], v[244:245], v[92:93] op_sel_hi:[1,0]
	v_pk_fma_f32 v[252:253], v[238:239], v[92:93], v[252:253] op_sel:[0,1,0]
	v_pk_fma_f32 v[254:255], v[246:247], v[92:93], v[254:255] op_sel:[0,1,0]
	v_pk_fma_f32 v[252:253], v[240:241], v[94:95], v[252:253] op_sel_hi:[1,0,1]
	v_pk_fma_f32 v[254:255], v[248:249], v[94:95], v[254:255] op_sel_hi:[1,0,1]
	v_pk_fma_f32 v[252:253], v[242:243], v[94:95], v[252:253] op_sel:[0,1,0]
	v_pk_fma_f32 v[254:255], v[250:251], v[94:95], v[254:255] op_sel:[0,1,0]
	v_add_f32_dpp v108, v110, v109 row_ror:4 row_mask:0xf bank_mask:0xf
	v_add_f32_dpp v96, v140, v140 quad_perm:[1,0,3,2] row_mask:0xf bank_mask:0xf
	v_add_f32_dpp v97, v141, v141 quad_perm:[1,0,3,2] row_mask:0xf bank_mask:0xf
	v_add_f32_dpp v98, v142, v142 quad_perm:[1,0,3,2] row_mask:0xf bank_mask:0xf
	v_add_f32_dpp v99, v143, v143 quad_perm:[1,0,3,2] row_mask:0xf bank_mask:0xf
	v_cndmask_b32_e32 v96, v98, v96, vcc
	v_cndmask_b32_e32 v97, v99, v97, vcc
	v_add_f32_dpp v102, v100, v100 quad_perm:[2,3,0,1] row_mask:0xf bank_mask:0xf
	v_add_f32_dpp v103, v101, v101 quad_perm:[2,3,0,1] row_mask:0xf bank_mask:0xf
	v_cndmask_b32_e64 v100, v103, v102, s[4:5]
	s_waitcnt vmcnt(22)
	v_pk_mul_f32 v[140:141], v[236:237], v[88:89] op_sel_hi:[1,0]
	v_pk_mul_f32 v[142:143], v[244:245], v[88:89] op_sel_hi:[1,0]
	v_pk_fma_f32 v[140:141], v[238:239], v[88:89], v[140:141] op_sel:[0,1,0]
	v_pk_fma_f32 v[142:143], v[246:247], v[88:89], v[142:143] op_sel:[0,1,0]
	v_pk_fma_f32 v[140:141], v[240:241], v[90:91], v[140:141] op_sel_hi:[1,0,1]
	v_pk_fma_f32 v[142:143], v[248:249], v[90:91], v[142:143] op_sel_hi:[1,0,1]
	v_pk_fma_f32 v[140:141], v[242:243], v[90:91], v[140:141] op_sel:[0,1,0]
	v_pk_fma_f32 v[142:143], v[250:251], v[90:91], v[142:143] op_sel:[0,1,0]
	v_add_f32_dpp v92, v252, v252 quad_perm:[1,0,3,2] row_mask:0xf bank_mask:0xf
	v_add_f32_dpp v93, v253, v253 quad_perm:[1,0,3,2] row_mask:0xf bank_mask:0xf
	v_add_f32_dpp v94, v254, v254 quad_perm:[1,0,3,2] row_mask:0xf bank_mask:0xf
	v_add_f32_dpp v95, v255, v255 quad_perm:[1,0,3,2] row_mask:0xf bank_mask:0xf
	v_cndmask_b32_e32 v92, v94, v92, vcc
	v_cndmask_b32_e32 v93, v95, v93, vcc
	v_add_f32_dpp v98, v96, v96 quad_perm:[2,3,0,1] row_mask:0xf bank_mask:0xf
	v_add_f32_dpp v99, v97, v97 quad_perm:[2,3,0,1] row_mask:0xf bank_mask:0xf
	v_cndmask_b32_e64 v96, v99, v98, s[4:5]
	v_cndmask_b32_e64 v101, v96, v100, s[6:7]
	v_cndmask_b32_e64 v102, v100, v96, s[6:7]
	s_waitcnt vmcnt(21)
	v_pk_mul_f32 v[252:253], v[236:237], v[84:85] op_sel_hi:[1,0]
	v_pk_mul_f32 v[254:255], v[244:245], v[84:85] op_sel_hi:[1,0]
	v_pk_fma_f32 v[252:253], v[238:239], v[84:85], v[252:253] op_sel:[0,1,0]
	v_pk_fma_f32 v[254:255], v[246:247], v[84:85], v[254:255] op_sel:[0,1,0]
	v_pk_fma_f32 v[252:253], v[240:241], v[86:87], v[252:253] op_sel_hi:[1,0,1]
	v_pk_fma_f32 v[254:255], v[248:249], v[86:87], v[254:255] op_sel_hi:[1,0,1]
	v_pk_fma_f32 v[252:253], v[242:243], v[86:87], v[252:253] op_sel:[0,1,0]
	v_pk_fma_f32 v[254:255], v[250:251], v[86:87], v[254:255] op_sel:[0,1,0]
	v_add_f32_dpp v100, v102, v101 row_ror:4 row_mask:0xf bank_mask:0xf
	v_cndmask_b32_e64 v109, v100, v108, s[64:65]
	v_cndmask_b32_e64 v110, v108, v100, s[64:65]
	v_add_f32_dpp v88, v140, v140 quad_perm:[1,0,3,2] row_mask:0xf bank_mask:0xf
	v_add_f32_dpp v89, v141, v141 quad_perm:[1,0,3,2] row_mask:0xf bank_mask:0xf
	v_add_f32_dpp v90, v142, v142 quad_perm:[1,0,3,2] row_mask:0xf bank_mask:0xf
	v_add_f32_dpp v91, v143, v143 quad_perm:[1,0,3,2] row_mask:0xf bank_mask:0xf
	v_cndmask_b32_e32 v88, v90, v88, vcc
	v_cndmask_b32_e32 v89, v91, v89, vcc
	v_add_f32_dpp v94, v92, v92 quad_perm:[2,3,0,1] row_mask:0xf bank_mask:0xf
	v_add_f32_dpp v95, v93, v93 quad_perm:[2,3,0,1] row_mask:0xf bank_mask:0xf
	v_cndmask_b32_e64 v92, v95, v94, s[4:5]
	s_waitcnt vmcnt(20)
	v_pk_mul_f32 v[140:141], v[236:237], v[80:81] op_sel_hi:[1,0]
	v_pk_mul_f32 v[142:143], v[244:245], v[80:81] op_sel_hi:[1,0]
	v_pk_fma_f32 v[140:141], v[238:239], v[80:81], v[140:141] op_sel:[0,1,0]
	v_pk_fma_f32 v[142:143], v[246:247], v[80:81], v[142:143] op_sel:[0,1,0]
	v_pk_fma_f32 v[140:141], v[240:241], v[82:83], v[140:141] op_sel_hi:[1,0,1]
	v_pk_fma_f32 v[142:143], v[248:249], v[82:83], v[142:143] op_sel_hi:[1,0,1]
	v_pk_fma_f32 v[140:141], v[242:243], v[82:83], v[140:141] op_sel:[0,1,0]
	v_pk_fma_f32 v[142:143], v[250:251], v[82:83], v[142:143] op_sel:[0,1,0]
	v_add_f32_dpp v108, v110, v109 row_ror:8 row_mask:0xf bank_mask:0xf
	v_add_f32_dpp v84, v252, v252 quad_perm:[1,0,3,2] row_mask:0xf bank_mask:0xf
	v_add_f32_dpp v85, v253, v253 quad_perm:[1,0,3,2] row_mask:0xf bank_mask:0xf
	v_add_f32_dpp v86, v254, v254 quad_perm:[1,0,3,2] row_mask:0xf bank_mask:0xf
	v_add_f32_dpp v87, v255, v255 quad_perm:[1,0,3,2] row_mask:0xf bank_mask:0xf
	v_cndmask_b32_e32 v84, v86, v84, vcc
	v_cndmask_b32_e32 v85, v87, v85, vcc
	v_add_f32_dpp v90, v88, v88 quad_perm:[2,3,0,1] row_mask:0xf bank_mask:0xf
	v_add_f32_dpp v91, v89, v89 quad_perm:[2,3,0,1] row_mask:0xf bank_mask:0xf
	v_cndmask_b32_e64 v88, v91, v90, s[4:5]
	v_cndmask_b32_e64 v93, v88, v92, s[6:7]
	v_cndmask_b32_e64 v94, v92, v88, s[6:7]
	s_waitcnt vmcnt(19)
; DI void attn_sample_item(const Params& p, int item, ldsp lds, int tid_) {
;     ...
;   SC_SCORE(kvA, 0)
;   SC_SCORE(kvB, 1)
	v_pk_mul_f32 v[252:253], v[236:237], v[76:77] op_sel_hi:[1,0]
	v_pk_mul_f32 v[254:255], v[244:245], v[76:77] op_sel_hi:[1,0]
	v_pk_fma_f32 v[252:253], v[238:239], v[76:77], v[252:253] op_sel:[0,1,0]
	v_pk_fma_f32 v[254:255], v[246:247], v[76:77], v[254:255] op_sel:[0,1,0]
	v_pk_fma_f32 v[252:253], v[240:241], v[78:79], v[252:253] op_sel_hi:[1,0,1]
	v_pk_fma_f32 v[254:255], v[248:249], v[78:79], v[254:255] op_sel_hi:[1,0,1]
	v_pk_fma_f32 v[252:253], v[242:243], v[78:79], v[252:253] op_sel:[0,1,0]
	v_pk_fma_f32 v[254:255], v[250:251], v[78:79], v[254:255] op_sel:[0,1,0]
	v_permlane16_swap_b32_e32 v124, v108
	v_add_f32_e32 v124, v124, v108
	v_add_f32_dpp v92, v94, v93 row_ror:4 row_mask:0xf bank_mask:0xf
	v_add_f32_dpp v80, v140, v140 quad_perm:[1,0,3,2] row_mask:0xf bank_mask:0xf
	v_add_f32_dpp v81, v141, v141 quad_perm:[1,0,3,2] row_mask:0xf bank_mask:0xf
	v_add_f32_dpp v82, v142, v142 quad_perm:[1,0,3,2] row_mask:0xf bank_mask:0xf
	v_add_f32_dpp v83, v143, v143 quad_perm:[1,0,3,2] row_mask:0xf bank_mask:0xf
	v_cndmask_b32_e32 v80, v82, v80, vcc
	v_cndmask_b32_e32 v81, v83, v81, vcc
	v_add_f32_dpp v86, v84, v84 quad_perm:[2,3,0,1] row_mask:0xf bank_mask:0xf
	v_add_f32_dpp v87, v85, v85 quad_perm:[2,3,0,1] row_mask:0xf bank_mask:0xf
	v_cndmask_b32_e64 v84, v87, v86, s[4:5]
	s_waitcnt vmcnt(18)
	v_pk_mul_f32 v[140:141], v[236:237], v[72:73] op_sel_hi:[1,0]
	v_pk_mul_f32 v[142:143], v[244:245], v[72:73] op_sel_hi:[1,0]
	v_pk_fma_f32 v[140:141], v[238:239], v[72:73], v[140:141] op_sel:[0,1,0]
	v_pk_fma_f32 v[142:143], v[246:247], v[72:73], v[142:143] op_sel:[0,1,0]
	v_pk_fma_f32 v[140:141], v[240:241], v[74:75], v[140:141] op_sel_hi:[1,0,1]
	v_pk_fma_f32 v[142:143], v[248:249], v[74:75], v[142:143] op_sel_hi:[1,0,1]
	v_pk_fma_f32 v[140:141], v[242:243], v[74:75], v[140:141] op_sel:[0,1,0]
	v_pk_fma_f32 v[142:143], v[250:251], v[74:75], v[142:143] op_sel:[0,1,0]
	v_add_f32_dpp v76, v252, v252 quad_perm:[1,0,3,2] row_mask:0xf bank_mask:0xf
	v_add_f32_dpp v77, v253, v253 quad_perm:[1,0,3,2] row_mask:0xf bank_mask:0xf
	v_add_f32_dpp v78, v254, v254 quad_perm:[1,0,3,2] row_mask:0xf bank_mask:0xf
	v_add_f32_dpp v79, v255, v255 quad_perm:[1,0,3,2] row_mask:0xf bank_mask:0xf
	v_cndmask_b32_e32 v76, v78, v76, vcc
	v_cndmask_b32_e32 v77, v79, v77, vcc
	v_add_f32_dpp v82, v80, v80 quad_perm:[2,3,0,1] row_mask:0xf bank_mask:0xf
	v_add_f32_dpp v83, v81, v81 quad_perm:[2,3,0,1] row_mask:0xf bank_mask:0xf
	v_cndmask_b32_e64 v80, v83, v82, s[4:5]
	v_cndmask_b32_e64 v85, v80, v84, s[6:7]
	v_cndmask_b32_e64 v86, v84, v80, s[6:7]
	s_waitcnt vmcnt(17)
	v_pk_mul_f32 v[252:253], v[236:237], v[68:69] op_sel_hi:[1,0]
	v_pk_mul_f32 v[254:255], v[244:245], v[68:69] op_sel_hi:[1,0]
	v_pk_fma_f32 v[252:253], v[238:239], v[68:69], v[252:253] op_sel:[0,1,0]
	v_pk_fma_f32 v[254:255], v[246:247], v[68:69], v[254:255] op_sel:[0,1,0]
	v_pk_fma_f32 v[252:253], v[240:241], v[70:71], v[252:253] op_sel_hi:[1,0,1]
	v_pk_fma_f32 v[254:255], v[248:249], v[70:71], v[254:255] op_sel_hi:[1,0,1]
	v_pk_fma_f32 v[252:253], v[242:243], v[70:71], v[252:253] op_sel:[0,1,0]
	v_pk_fma_f32 v[254:255], v[250:251], v[70:71], v[254:255] op_sel:[0,1,0]
	v_add_f32_dpp v84, v86, v85 row_ror:4 row_mask:0xf bank_mask:0xf
	v_cndmask_b32_e64 v93, v84, v92, s[64:65]
	v_cndmask_b32_e64 v94, v92, v84, s[64:65]
	v_add_f32_dpp v72, v140, v140 quad_perm:[1,0,3,2] row_mask:0xf bank_mask:0xf
	v_add_f32_dpp v73, v141, v141 quad_perm:[1,0,3,2] row_mask:0xf bank_mask:0xf
	v_add_f32_dpp v74, v142, v142 quad_perm:[1,0,3,2] row_mask:0xf bank_mask:0xf
	v_add_f32_dpp v75, v143, v143 quad_perm:[1,0,3,2] row_mask:0xf bank_mask:0xf
	v_cndmask_b32_e32 v72, v74, v72, vcc
	v_cndmask_b32_e32 v73, v75, v73, vcc
	v_add_f32_dpp v78, v76, v76 quad_perm:[2,3,0,1] row_mask:0xf bank_mask:0xf
	v_add_f32_dpp v79, v77, v77 quad_perm:[2,3,0,1] row_mask:0xf bank_mask:0xf
	v_cndmask_b32_e64 v76, v79, v78, s[4:5]
	s_waitcnt vmcnt(16)
	v_pk_mul_f32 v[140:141], v[236:237], v[64:65] op_sel_hi:[1,0]
	v_pk_mul_f32 v[142:143], v[244:245], v[64:65] op_sel_hi:[1,0]
	v_pk_fma_f32 v[140:141], v[238:239], v[64:65], v[140:141] op_sel:[0,1,0]
	v_pk_fma_f32 v[142:143], v[246:247], v[64:65], v[142:143] op_sel:[0,1,0]
	v_pk_fma_f32 v[140:141], v[240:241], v[66:67], v[140:141] op_sel_hi:[1,0,1]
	v_pk_fma_f32 v[142:143], v[248:249], v[66:67], v[142:143] op_sel_hi:[1,0,1]
	v_pk_fma_f32 v[140:141], v[242:243], v[66:67], v[140:141] op_sel:[0,1,0]
	v_pk_fma_f32 v[142:143], v[250:251], v[66:67], v[142:143] op_sel:[0,1,0]
	v_add_f32_dpp v92, v94, v93 row_ror:8 row_mask:0xf bank_mask:0xf
	v_add_f32_dpp v68, v252, v252 quad_perm:[1,0,3,2] row_mask:0xf bank_mask:0xf
	v_add_f32_dpp v69, v253, v253 quad_perm:[1,0,3,2] row_mask:0xf bank_mask:0xf
	v_add_f32_dpp v70, v254, v254 quad_perm:[1,0,3,2] row_mask:0xf bank_mask:0xf
	v_add_f32_dpp v71, v255, v255 quad_perm:[1,0,3,2] row_mask:0xf bank_mask:0xf
	v_cndmask_b32_e32 v68, v70, v68, vcc
	v_cndmask_b32_e32 v69, v71, v69, vcc
	v_add_f32_dpp v74, v72, v72 quad_perm:[2,3,0,1] row_mask:0xf bank_mask:0xf
	v_add_f32_dpp v75, v73, v73 quad_perm:[2,3,0,1] row_mask:0xf bank_mask:0xf
	v_cndmask_b32_e64 v72, v75, v74, s[4:5]
	v_cndmask_b32_e64 v77, v72, v76, s[6:7]
	v_cndmask_b32_e64 v78, v76, v72, s[6:7]
	s_waitcnt vmcnt(15)
; DI void attn_sample_item(const Params& p, int item, ldsp lds, int tid_) {
;     ...
;   SC_SCORE(kvA, 0)
;   SC_SCORE(kvB, 1)
	v_pk_mul_f32 v[252:253], v[236:237], v[60:61] op_sel_hi:[1,0]
	v_pk_mul_f32 v[254:255], v[244:245], v[60:61] op_sel_hi:[1,0]
	v_pk_fma_f32 v[252:253], v[238:239], v[60:61], v[252:253] op_sel:[0,1,0]
	v_pk_fma_f32 v[254:255], v[246:247], v[60:61], v[254:255] op_sel:[0,1,0]
	v_pk_fma_f32 v[252:253], v[240:241], v[62:63], v[252:253] op_sel_hi:[1,0,1]
	v_pk_fma_f32 v[254:255], v[248:249], v[62:63], v[254:255] op_sel_hi:[1,0,1]
	v_pk_fma_f32 v[252:253], v[242:243], v[62:63], v[252:253] op_sel:[0,1,0]
	v_pk_fma_f32 v[254:255], v[250:251], v[62:63], v[254:255] op_sel:[0,1,0]
	v_add_f32_dpp v76, v78, v77 row_ror:4 row_mask:0xf bank_mask:0xf
	v_add_f32_dpp v64, v140, v140 quad_perm:[1,0,3,2] row_mask:0xf bank_mask:0xf
	v_add_f32_dpp v65, v141, v141 quad_perm:[1,0,3,2] row_mask:0xf bank_mask:0xf
	v_add_f32_dpp v66, v142, v142 quad_perm:[1,0,3,2] row_mask:0xf bank_mask:0xf
	v_add_f32_dpp v67, v143, v143 quad_perm:[1,0,3,2] row_mask:0xf bank_mask:0xf
	v_cndmask_b32_e32 v64, v66, v64, vcc
	v_cndmask_b32_e32 v65, v67, v65, vcc
	v_add_f32_dpp v70, v68, v68 quad_perm:[2,3,0,1] row_mask:0xf bank_mask:0xf
	v_add_f32_dpp v71, v69, v69 quad_perm:[2,3,0,1] row_mask:0xf bank_mask:0xf
	v_cndmask_b32_e64 v68, v71, v70, s[4:5]
	s_waitcnt vmcnt(14)
	v_pk_mul_f32 v[140:141], v[236:237], v[56:57] op_sel_hi:[1,0]
	v_pk_mul_f32 v[142:143], v[244:245], v[56:57] op_sel_hi:[1,0]
	v_pk_fma_f32 v[140:141], v[238:239], v[56:57], v[140:141] op_sel:[0,1,0]
	v_pk_fma_f32 v[142:143], v[246:247], v[56:57], v[142:143] op_sel:[0,1,0]
	v_pk_fma_f32 v[140:141], v[240:241], v[58:59], v[140:141] op_sel_hi:[1,0,1]
	v_pk_fma_f32 v[142:143], v[248:249], v[58:59], v[142:143] op_sel_hi:[1,0,1]
	v_pk_fma_f32 v[140:141], v[242:243], v[58:59], v[140:141] op_sel:[0,1,0]
	v_pk_fma_f32 v[142:143], v[250:251], v[58:59], v[142:143] op_sel:[0,1,0]
	v_add_f32_dpp v60, v252, v252 quad_perm:[1,0,3,2] row_mask:0xf bank_mask:0xf
	v_add_f32_dpp v61, v253, v253 quad_perm:[1,0,3,2] row_mask:0xf bank_mask:0xf
	v_add_f32_dpp v62, v254, v254 quad_perm:[1,0,3,2] row_mask:0xf bank_mask:0xf
	v_add_f32_dpp v63, v255, v255 quad_perm:[1,0,3,2] row_mask:0xf bank_mask:0xf
	v_cndmask_b32_e32 v60, v62, v60, vcc
	v_cndmask_b32_e32 v61, v63, v61, vcc
	v_add_f32_dpp v66, v64, v64 quad_perm:[2,3,0,1] row_mask:0xf bank_mask:0xf
	v_add_f32_dpp v67, v65, v65 quad_perm:[2,3,0,1] row_mask:0xf bank_mask:0xf
	v_cndmask_b32_e64 v64, v67, v66, s[4:5]
	v_cndmask_b32_e64 v69, v64, v68, s[6:7]
	v_cndmask_b32_e64 v70, v68, v64, s[6:7]
	s_waitcnt vmcnt(13)
	v_pk_mul_f32 v[252:253], v[236:237], v[52:53] op_sel_hi:[1,0]
	v_pk_mul_f32 v[254:255], v[244:245], v[52:53] op_sel_hi:[1,0]
	v_pk_fma_f32 v[252:253], v[238:239], v[52:53], v[252:253] op_sel:[0,1,0]
	v_pk_fma_f32 v[254:255], v[246:247], v[52:53], v[254:255] op_sel:[0,1,0]
	v_pk_fma_f32 v[252:253], v[240:241], v[54:55], v[252:253] op_sel_hi:[1,0,1]
	v_pk_fma_f32 v[254:255], v[248:249], v[54:55], v[254:255] op_sel_hi:[1,0,1]
	v_pk_fma_f32 v[252:253], v[242:243], v[54:55], v[252:253] op_sel:[0,1,0]
	v_pk_fma_f32 v[254:255], v[250:251], v[54:55], v[254:255] op_sel:[0,1,0]
	v_add_f32_dpp v68, v70, v69 row_ror:4 row_mask:0xf bank_mask:0xf
	v_cndmask_b32_e64 v77, v68, v76, s[64:65]
	v_cndmask_b32_e64 v78, v76, v68, s[64:65]
	v_add_f32_dpp v56, v140, v140 quad_perm:[1,0,3,2] row_mask:0xf bank_mask:0xf
	v_add_f32_dpp v57, v141, v141 quad_perm:[1,0,3,2] row_mask:0xf bank_mask:0xf
	v_add_f32_dpp v58, v142, v142 quad_perm:[1,0,3,2] row_mask:0xf bank_mask:0xf
	v_add_f32_dpp v59, v143, v143 quad_perm:[1,0,3,2] row_mask:0xf bank_mask:0xf
	v_cndmask_b32_e32 v56, v58, v56, vcc
	v_cndmask_b32_e32 v57, v59, v57, vcc
	v_add_f32_dpp v62, v60, v60 quad_perm:[2,3,0,1] row_mask:0xf bank_mask:0xf
	v_add_f32_dpp v63, v61, v61 quad_perm:[2,3,0,1] row_mask:0xf bank_mask:0xf
	v_cndmask_b32_e64 v60, v63, v62, s[4:5]
	s_waitcnt vmcnt(12)
	v_pk_mul_f32 v[140:141], v[236:237], v[48:49] op_sel_hi:[1,0]
	v_pk_mul_f32 v[142:143], v[244:245], v[48:49] op_sel_hi:[1,0]
	v_pk_fma_f32 v[140:141], v[238:239], v[48:49], v[140:141] op_sel:[0,1,0]
	v_pk_fma_f32 v[142:143], v[246:247], v[48:49], v[142:143] op_sel:[0,1,0]
	v_pk_fma_f32 v[140:141], v[240:241], v[50:51], v[140:141] op_sel_hi:[1,0,1]
	v_pk_fma_f32 v[142:143], v[248:249], v[50:51], v[142:143] op_sel_hi:[1,0,1]
	v_pk_fma_f32 v[140:141], v[242:243], v[50:51], v[140:141] op_sel:[0,1,0]
	v_pk_fma_f32 v[142:143], v[250:251], v[50:51], v[142:143] op_sel:[0,1,0]
	v_add_f32_dpp v76, v78, v77 row_ror:8 row_mask:0xf bank_mask:0xf
	v_add_f32_dpp v52, v252, v252 quad_perm:[1,0,3,2] row_mask:0xf bank_mask:0xf
	v_add_f32_dpp v53, v253, v253 quad_perm:[1,0,3,2] row_mask:0xf bank_mask:0xf
	v_add_f32_dpp v54, v254, v254 quad_perm:[1,0,3,2] row_mask:0xf bank_mask:0xf
	v_add_f32_dpp v55, v255, v255 quad_perm:[1,0,3,2] row_mask:0xf bank_mask:0xf
	v_cndmask_b32_e32 v52, v54, v52, vcc
	v_cndmask_b32_e32 v53, v55, v53, vcc
	v_add_f32_dpp v58, v56, v56 quad_perm:[2,3,0,1] row_mask:0xf bank_mask:0xf
	v_add_f32_dpp v59, v57, v57 quad_perm:[2,3,0,1] row_mask:0xf bank_mask:0xf
	v_cndmask_b32_e64 v56, v59, v58, s[4:5]
	v_cndmask_b32_e64 v61, v56, v60, s[6:7]
	v_cndmask_b32_e64 v62, v60, v56, s[6:7]
	s_waitcnt vmcnt(11)
; DI void attn_sample_item(const Params& p, int item, ldsp lds, int tid_) {
;     ...
;   SC_SCORE(kvA, 0)
;   SC_SCORE(kvB, 1)
	v_pk_mul_f32 v[252:253], v[236:237], v[44:45] op_sel_hi:[1,0]
	v_pk_mul_f32 v[254:255], v[244:245], v[44:45] op_sel_hi:[1,0]
	v_pk_fma_f32 v[252:253], v[238:239], v[44:45], v[252:253] op_sel:[0,1,0]
	v_pk_fma_f32 v[254:255], v[246:247], v[44:45], v[254:255] op_sel:[0,1,0]
	v_pk_fma_f32 v[252:253], v[240:241], v[46:47], v[252:253] op_sel_hi:[1,0,1]
	v_pk_fma_f32 v[254:255], v[248:249], v[46:47], v[254:255] op_sel_hi:[1,0,1]
	v_pk_fma_f32 v[252:253], v[242:243], v[46:47], v[252:253] op_sel:[0,1,0]
	v_pk_fma_f32 v[254:255], v[250:251], v[46:47], v[254:255] op_sel:[0,1,0]
	v_permlane16_swap_b32_e32 v92, v76
	v_add_f32_e32 v92, v92, v76
	v_add_f32_dpp v60, v62, v61 row_ror:4 row_mask:0xf bank_mask:0xf
	v_add_f32_dpp v48, v140, v140 quad_perm:[1,0,3,2] row_mask:0xf bank_mask:0xf
	v_add_f32_dpp v49, v141, v141 quad_perm:[1,0,3,2] row_mask:0xf bank_mask:0xf
	v_add_f32_dpp v50, v142, v142 quad_perm:[1,0,3,2] row_mask:0xf bank_mask:0xf
	v_add_f32_dpp v51, v143, v143 quad_perm:[1,0,3,2] row_mask:0xf bank_mask:0xf
	v_cndmask_b32_e32 v48, v50, v48, vcc
	v_cndmask_b32_e32 v49, v51, v49, vcc
	v_add_f32_dpp v54, v52, v52 quad_perm:[2,3,0,1] row_mask:0xf bank_mask:0xf
	v_add_f32_dpp v55, v53, v53 quad_perm:[2,3,0,1] row_mask:0xf bank_mask:0xf
	v_cndmask_b32_e64 v52, v55, v54, s[4:5]
	s_waitcnt vmcnt(10)
	v_pk_mul_f32 v[140:141], v[236:237], v[40:41] op_sel_hi:[1,0]
	v_pk_mul_f32 v[142:143], v[244:245], v[40:41] op_sel_hi:[1,0]
	v_pk_fma_f32 v[140:141], v[238:239], v[40:41], v[140:141] op_sel:[0,1,0]
	v_pk_fma_f32 v[142:143], v[246:247], v[40:41], v[142:143] op_sel:[0,1,0]
	v_pk_fma_f32 v[140:141], v[240:241], v[42:43], v[140:141] op_sel_hi:[1,0,1]
	v_pk_fma_f32 v[142:143], v[248:249], v[42:43], v[142:143] op_sel_hi:[1,0,1]
	v_pk_fma_f32 v[140:141], v[242:243], v[42:43], v[140:141] op_sel:[0,1,0]
	v_pk_fma_f32 v[142:143], v[250:251], v[42:43], v[142:143] op_sel:[0,1,0]
	v_permlane32_swap_b32_e32 v124, v92
	v_add_f32_e32 v124, v124, v92
	ds_write_b32 v235, v124
	v_add_f32_dpp v44, v252, v252 quad_perm:[1,0,3,2] row_mask:0xf bank_mask:0xf
	v_add_f32_dpp v45, v253, v253 quad_perm:[1,0,3,2] row_mask:0xf bank_mask:0xf
	v_add_f32_dpp v46, v254, v254 quad_perm:[1,0,3,2] row_mask:0xf bank_mask:0xf
	v_add_f32_dpp v47, v255, v255 quad_perm:[1,0,3,2] row_mask:0xf bank_mask:0xf
	v_cndmask_b32_e32 v44, v46, v44, vcc
	v_cndmask_b32_e32 v45, v47, v45, vcc
	v_add_f32_dpp v50, v48, v48 quad_perm:[2,3,0,1] row_mask:0xf bank_mask:0xf
	v_add_f32_dpp v51, v49, v49 quad_perm:[2,3,0,1] row_mask:0xf bank_mask:0xf
	v_cndmask_b32_e64 v48, v51, v50, s[4:5]
	v_cndmask_b32_e64 v53, v48, v52, s[6:7]
	v_cndmask_b32_e64 v54, v52, v48, s[6:7]
	s_waitcnt vmcnt(9)
	v_pk_mul_f32 v[252:253], v[236:237], v[36:37] op_sel_hi:[1,0]
	v_pk_mul_f32 v[254:255], v[244:245], v[36:37] op_sel_hi:[1,0]
	v_pk_fma_f32 v[252:253], v[238:239], v[36:37], v[252:253] op_sel:[0,1,0]
	v_pk_fma_f32 v[254:255], v[246:247], v[36:37], v[254:255] op_sel:[0,1,0]
	v_pk_fma_f32 v[252:253], v[240:241], v[38:39], v[252:253] op_sel_hi:[1,0,1]
	v_pk_fma_f32 v[254:255], v[248:249], v[38:39], v[254:255] op_sel_hi:[1,0,1]
	v_pk_fma_f32 v[252:253], v[242:243], v[38:39], v[252:253] op_sel:[0,1,0]
	v_pk_fma_f32 v[254:255], v[250:251], v[38:39], v[254:255] op_sel:[0,1,0]
	v_add_f32_dpp v52, v54, v53 row_ror:4 row_mask:0xf bank_mask:0xf
	v_cndmask_b32_e64 v61, v52, v60, s[64:65]
	v_cndmask_b32_e64 v62, v60, v52, s[64:65]
	v_add_f32_dpp v40, v140, v140 quad_perm:[1,0,3,2] row_mask:0xf bank_mask:0xf
	v_add_f32_dpp v41, v141, v141 quad_perm:[1,0,3,2] row_mask:0xf bank_mask:0xf
	v_add_f32_dpp v42, v142, v142 quad_perm:[1,0,3,2] row_mask:0xf bank_mask:0xf
	v_add_f32_dpp v43, v143, v143 quad_perm:[1,0,3,2] row_mask:0xf bank_mask:0xf
	v_cndmask_b32_e32 v40, v42, v40, vcc
	v_cndmask_b32_e32 v41, v43, v41, vcc
	v_add_f32_dpp v46, v44, v44 quad_perm:[2,3,0,1] row_mask:0xf bank_mask:0xf
	v_add_f32_dpp v47, v45, v45 quad_perm:[2,3,0,1] row_mask:0xf bank_mask:0xf
	v_cndmask_b32_e64 v44, v47, v46, s[4:5]
	s_waitcnt vmcnt(8)
	v_pk_mul_f32 v[140:141], v[236:237], v[32:33] op_sel_hi:[1,0]
	v_pk_mul_f32 v[142:143], v[244:245], v[32:33] op_sel_hi:[1,0]
	v_pk_fma_f32 v[140:141], v[238:239], v[32:33], v[140:141] op_sel:[0,1,0]
	v_pk_fma_f32 v[142:143], v[246:247], v[32:33], v[142:143] op_sel:[0,1,0]
	v_pk_fma_f32 v[140:141], v[240:241], v[34:35], v[140:141] op_sel_hi:[1,0,1]
	v_pk_fma_f32 v[142:143], v[248:249], v[34:35], v[142:143] op_sel_hi:[1,0,1]
	v_pk_fma_f32 v[140:141], v[242:243], v[34:35], v[140:141] op_sel:[0,1,0]
	v_pk_fma_f32 v[142:143], v[250:251], v[34:35], v[142:143] op_sel:[0,1,0]
	v_add_f32_dpp v60, v62, v61 row_ror:8 row_mask:0xf bank_mask:0xf
	v_add_f32_dpp v36, v252, v252 quad_perm:[1,0,3,2] row_mask:0xf bank_mask:0xf
	v_add_f32_dpp v37, v253, v253 quad_perm:[1,0,3,2] row_mask:0xf bank_mask:0xf
	v_add_f32_dpp v38, v254, v254 quad_perm:[1,0,3,2] row_mask:0xf bank_mask:0xf
	v_add_f32_dpp v39, v255, v255 quad_perm:[1,0,3,2] row_mask:0xf bank_mask:0xf
	v_cndmask_b32_e32 v36, v38, v36, vcc
	v_cndmask_b32_e32 v37, v39, v37, vcc
	v_add_f32_dpp v42, v40, v40 quad_perm:[2,3,0,1] row_mask:0xf bank_mask:0xf
	v_add_f32_dpp v43, v41, v41 quad_perm:[2,3,0,1] row_mask:0xf bank_mask:0xf
	v_cndmask_b32_e64 v40, v43, v42, s[4:5]
	v_cndmask_b32_e64 v45, v40, v44, s[6:7]
	v_cndmask_b32_e64 v46, v44, v40, s[6:7]
	s_waitcnt vmcnt(7)
; DI void attn_sample_item(const Params& p, int item, ldsp lds, int tid_) {
;     ...
;   SC_SCORE(kvA, 0)
;   SC_SCORE(kvB, 1)
	v_pk_mul_f32 v[252:253], v[236:237], v[28:29] op_sel_hi:[1,0]
	v_pk_mul_f32 v[254:255], v[244:245], v[28:29] op_sel_hi:[1,0]
	v_pk_fma_f32 v[252:253], v[238:239], v[28:29], v[252:253] op_sel:[0,1,0]
	v_pk_fma_f32 v[254:255], v[246:247], v[28:29], v[254:255] op_sel:[0,1,0]
	v_pk_fma_f32 v[252:253], v[240:241], v[30:31], v[252:253] op_sel_hi:[1,0,1]
	v_pk_fma_f32 v[254:255], v[248:249], v[30:31], v[254:255] op_sel_hi:[1,0,1]
	v_pk_fma_f32 v[252:253], v[242:243], v[30:31], v[252:253] op_sel:[0,1,0]
	v_pk_fma_f32 v[254:255], v[250:251], v[30:31], v[254:255] op_sel:[0,1,0]
	v_add_f32_dpp v44, v46, v45 row_ror:4 row_mask:0xf bank_mask:0xf
	v_add_f32_dpp v32, v140, v140 quad_perm:[1,0,3,2] row_mask:0xf bank_mask:0xf
	v_add_f32_dpp v33, v141, v141 quad_perm:[1,0,3,2] row_mask:0xf bank_mask:0xf
	v_add_f32_dpp v34, v142, v142 quad_perm:[1,0,3,2] row_mask:0xf bank_mask:0xf
	v_add_f32_dpp v35, v143, v143 quad_perm:[1,0,3,2] row_mask:0xf bank_mask:0xf
	v_cndmask_b32_e32 v32, v34, v32, vcc
	v_cndmask_b32_e32 v33, v35, v33, vcc
	v_add_f32_dpp v38, v36, v36 quad_perm:[2,3,0,1] row_mask:0xf bank_mask:0xf
	v_add_f32_dpp v39, v37, v37 quad_perm:[2,3,0,1] row_mask:0xf bank_mask:0xf
	v_cndmask_b32_e64 v36, v39, v38, s[4:5]
	s_waitcnt vmcnt(6)
	v_pk_mul_f32 v[140:141], v[236:237], v[24:25] op_sel_hi:[1,0]
	v_pk_mul_f32 v[142:143], v[244:245], v[24:25] op_sel_hi:[1,0]
	v_pk_fma_f32 v[140:141], v[238:239], v[24:25], v[140:141] op_sel:[0,1,0]
	v_pk_fma_f32 v[142:143], v[246:247], v[24:25], v[142:143] op_sel:[0,1,0]
	v_pk_fma_f32 v[140:141], v[240:241], v[26:27], v[140:141] op_sel_hi:[1,0,1]
	v_pk_fma_f32 v[142:143], v[248:249], v[26:27], v[142:143] op_sel_hi:[1,0,1]
	v_pk_fma_f32 v[140:141], v[242:243], v[26:27], v[140:141] op_sel:[0,1,0]
	v_pk_fma_f32 v[142:143], v[250:251], v[26:27], v[142:143] op_sel:[0,1,0]
	v_add_f32_dpp v28, v252, v252 quad_perm:[1,0,3,2] row_mask:0xf bank_mask:0xf
	v_add_f32_dpp v29, v253, v253 quad_perm:[1,0,3,2] row_mask:0xf bank_mask:0xf
	v_add_f32_dpp v30, v254, v254 quad_perm:[1,0,3,2] row_mask:0xf bank_mask:0xf
	v_add_f32_dpp v31, v255, v255 quad_perm:[1,0,3,2] row_mask:0xf bank_mask:0xf
	v_cndmask_b32_e32 v28, v30, v28, vcc
	v_cndmask_b32_e32 v29, v31, v29, vcc
	v_add_f32_dpp v34, v32, v32 quad_perm:[2,3,0,1] row_mask:0xf bank_mask:0xf
	v_add_f32_dpp v35, v33, v33 quad_perm:[2,3,0,1] row_mask:0xf bank_mask:0xf
	v_cndmask_b32_e64 v32, v35, v34, s[4:5]
	v_cndmask_b32_e64 v37, v32, v36, s[6:7]
	v_cndmask_b32_e64 v38, v36, v32, s[6:7]
	s_waitcnt vmcnt(5)
	v_pk_mul_f32 v[252:253], v[236:237], v[20:21] op_sel_hi:[1,0]
	v_pk_mul_f32 v[254:255], v[244:245], v[20:21] op_sel_hi:[1,0]
	v_pk_fma_f32 v[252:253], v[238:239], v[20:21], v[252:253] op_sel:[0,1,0]
	v_pk_fma_f32 v[254:255], v[246:247], v[20:21], v[254:255] op_sel:[0,1,0]
	v_pk_fma_f32 v[252:253], v[240:241], v[22:23], v[252:253] op_sel_hi:[1,0,1]
	v_pk_fma_f32 v[254:255], v[248:249], v[22:23], v[254:255] op_sel_hi:[1,0,1]
	v_pk_fma_f32 v[252:253], v[242:243], v[22:23], v[252:253] op_sel:[0,1,0]
	v_pk_fma_f32 v[254:255], v[250:251], v[22:23], v[254:255] op_sel:[0,1,0]
	v_add_f32_dpp v36, v38, v37 row_ror:4 row_mask:0xf bank_mask:0xf
	v_cndmask_b32_e64 v45, v36, v44, s[64:65]
	v_cndmask_b32_e64 v46, v44, v36, s[64:65]
	v_add_f32_dpp v24, v140, v140 quad_perm:[1,0,3,2] row_mask:0xf bank_mask:0xf
	v_add_f32_dpp v25, v141, v141 quad_perm:[1,0,3,2] row_mask:0xf bank_mask:0xf
	v_add_f32_dpp v26, v142, v142 quad_perm:[1,0,3,2] row_mask:0xf bank_mask:0xf
	v_add_f32_dpp v27, v143, v143 quad_perm:[1,0,3,2] row_mask:0xf bank_mask:0xf
	v_cndmask_b32_e32 v24, v26, v24, vcc
	v_cndmask_b32_e32 v25, v27, v25, vcc
	v_add_f32_dpp v30, v28, v28 quad_perm:[2,3,0,1] row_mask:0xf bank_mask:0xf
	v_add_f32_dpp v31, v29, v29 quad_perm:[2,3,0,1] row_mask:0xf bank_mask:0xf
	v_cndmask_b32_e64 v28, v31, v30, s[4:5]
	s_waitcnt vmcnt(4)
	v_pk_mul_f32 v[140:141], v[236:237], v[16:17] op_sel_hi:[1,0]
	v_pk_mul_f32 v[142:143], v[244:245], v[16:17] op_sel_hi:[1,0]
	v_pk_fma_f32 v[140:141], v[238:239], v[16:17], v[140:141] op_sel:[0,1,0]
	v_pk_fma_f32 v[142:143], v[246:247], v[16:17], v[142:143] op_sel:[0,1,0]
	v_pk_fma_f32 v[140:141], v[240:241], v[18:19], v[140:141] op_sel_hi:[1,0,1]
	v_pk_fma_f32 v[142:143], v[248:249], v[18:19], v[142:143] op_sel_hi:[1,0,1]
	v_pk_fma_f32 v[140:141], v[242:243], v[18:19], v[140:141] op_sel:[0,1,0]
	v_pk_fma_f32 v[142:143], v[250:251], v[18:19], v[142:143] op_sel:[0,1,0]
	v_add_f32_dpp v44, v46, v45 row_ror:8 row_mask:0xf bank_mask:0xf
	v_add_f32_dpp v20, v252, v252 quad_perm:[1,0,3,2] row_mask:0xf bank_mask:0xf
	v_add_f32_dpp v21, v253, v253 quad_perm:[1,0,3,2] row_mask:0xf bank_mask:0xf
	v_add_f32_dpp v22, v254, v254 quad_perm:[1,0,3,2] row_mask:0xf bank_mask:0xf
	v_add_f32_dpp v23, v255, v255 quad_perm:[1,0,3,2] row_mask:0xf bank_mask:0xf
	v_cndmask_b32_e32 v20, v22, v20, vcc
	v_cndmask_b32_e32 v21, v23, v21, vcc
	v_add_f32_dpp v26, v24, v24 quad_perm:[2,3,0,1] row_mask:0xf bank_mask:0xf
	v_add_f32_dpp v27, v25, v25 quad_perm:[2,3,0,1] row_mask:0xf bank_mask:0xf
	v_cndmask_b32_e64 v24, v27, v26, s[4:5]
	v_cndmask_b32_e64 v29, v24, v28, s[6:7]
	v_cndmask_b32_e64 v30, v28, v24, s[6:7]
	s_waitcnt vmcnt(3)
; DI void attn_sample_item(const Params& p, int item, ldsp lds, int tid_) {
;     ...
;   SC_SCORE(kvA, 0)
;   SC_SCORE(kvB, 1)
	v_pk_mul_f32 v[252:253], v[236:237], v[12:13] op_sel_hi:[1,0]
	v_pk_mul_f32 v[254:255], v[244:245], v[12:13] op_sel_hi:[1,0]
	v_pk_fma_f32 v[252:253], v[238:239], v[12:13], v[252:253] op_sel:[0,1,0]
	v_pk_fma_f32 v[254:255], v[246:247], v[12:13], v[254:255] op_sel:[0,1,0]
	v_pk_fma_f32 v[252:253], v[240:241], v[14:15], v[252:253] op_sel_hi:[1,0,1]
	v_pk_fma_f32 v[254:255], v[248:249], v[14:15], v[254:255] op_sel_hi:[1,0,1]
	v_pk_fma_f32 v[252:253], v[242:243], v[14:15], v[252:253] op_sel:[0,1,0]
	v_pk_fma_f32 v[254:255], v[250:251], v[14:15], v[254:255] op_sel:[0,1,0]
	v_permlane16_swap_b32_e32 v60, v44
	v_add_f32_e32 v60, v60, v44
	v_add_f32_dpp v28, v30, v29 row_ror:4 row_mask:0xf bank_mask:0xf
	v_add_f32_dpp v16, v140, v140 quad_perm:[1,0,3,2] row_mask:0xf bank_mask:0xf
	v_add_f32_dpp v17, v141, v141 quad_perm:[1,0,3,2] row_mask:0xf bank_mask:0xf
	v_add_f32_dpp v18, v142, v142 quad_perm:[1,0,3,2] row_mask:0xf bank_mask:0xf
	v_add_f32_dpp v19, v143, v143 quad_perm:[1,0,3,2] row_mask:0xf bank_mask:0xf
	v_cndmask_b32_e32 v16, v18, v16, vcc
	v_cndmask_b32_e32 v17, v19, v17, vcc
	v_add_f32_dpp v22, v20, v20 quad_perm:[2,3,0,1] row_mask:0xf bank_mask:0xf
	v_add_f32_dpp v23, v21, v21 quad_perm:[2,3,0,1] row_mask:0xf bank_mask:0xf
	v_cndmask_b32_e64 v20, v23, v22, s[4:5]
	s_waitcnt vmcnt(2)
	v_pk_mul_f32 v[140:141], v[236:237], v[8:9] op_sel_hi:[1,0]
	v_pk_mul_f32 v[142:143], v[244:245], v[8:9] op_sel_hi:[1,0]
	v_pk_fma_f32 v[140:141], v[238:239], v[8:9], v[140:141] op_sel:[0,1,0]
	v_pk_fma_f32 v[142:143], v[246:247], v[8:9], v[142:143] op_sel:[0,1,0]
	v_pk_fma_f32 v[140:141], v[240:241], v[10:11], v[140:141] op_sel_hi:[1,0,1]
	v_pk_fma_f32 v[142:143], v[248:249], v[10:11], v[142:143] op_sel_hi:[1,0,1]
	v_pk_fma_f32 v[140:141], v[242:243], v[10:11], v[140:141] op_sel:[0,1,0]
	v_pk_fma_f32 v[142:143], v[250:251], v[10:11], v[142:143] op_sel:[0,1,0]
	v_add_f32_dpp v12, v252, v252 quad_perm:[1,0,3,2] row_mask:0xf bank_mask:0xf
	v_add_f32_dpp v13, v253, v253 quad_perm:[1,0,3,2] row_mask:0xf bank_mask:0xf
	v_add_f32_dpp v14, v254, v254 quad_perm:[1,0,3,2] row_mask:0xf bank_mask:0xf
	v_add_f32_dpp v15, v255, v255 quad_perm:[1,0,3,2] row_mask:0xf bank_mask:0xf
	v_cndmask_b32_e32 v12, v14, v12, vcc
	v_cndmask_b32_e32 v13, v15, v13, vcc
	v_add_f32_dpp v18, v16, v16 quad_perm:[2,3,0,1] row_mask:0xf bank_mask:0xf
	v_add_f32_dpp v19, v17, v17 quad_perm:[2,3,0,1] row_mask:0xf bank_mask:0xf
	v_cndmask_b32_e64 v16, v19, v18, s[4:5]
	v_cndmask_b32_e64 v21, v16, v20, s[6:7]
	v_cndmask_b32_e64 v22, v20, v16, s[6:7]
	s_waitcnt vmcnt(1)
	v_pk_mul_f32 v[252:253], v[236:237], v[4:5] op_sel_hi:[1,0]
	v_pk_mul_f32 v[254:255], v[244:245], v[4:5] op_sel_hi:[1,0]
	v_pk_fma_f32 v[252:253], v[238:239], v[4:5], v[252:253] op_sel:[0,1,0]
	v_pk_fma_f32 v[254:255], v[246:247], v[4:5], v[254:255] op_sel:[0,1,0]
	v_pk_fma_f32 v[252:253], v[240:241], v[6:7], v[252:253] op_sel_hi:[1,0,1]
	v_pk_fma_f32 v[254:255], v[248:249], v[6:7], v[254:255] op_sel_hi:[1,0,1]
	v_pk_fma_f32 v[252:253], v[242:243], v[6:7], v[252:253] op_sel:[0,1,0]
	v_pk_fma_f32 v[254:255], v[250:251], v[6:7], v[254:255] op_sel:[0,1,0]
	v_add_f32_dpp v20, v22, v21 row_ror:4 row_mask:0xf bank_mask:0xf
	v_cndmask_b32_e64 v29, v20, v28, s[64:65]
	v_cndmask_b32_e64 v30, v28, v20, s[64:65]
	v_add_f32_dpp v8, v140, v140 quad_perm:[1,0,3,2] row_mask:0xf bank_mask:0xf
	v_add_f32_dpp v9, v141, v141 quad_perm:[1,0,3,2] row_mask:0xf bank_mask:0xf
	v_add_f32_dpp v10, v142, v142 quad_perm:[1,0,3,2] row_mask:0xf bank_mask:0xf
	v_add_f32_dpp v11, v143, v143 quad_perm:[1,0,3,2] row_mask:0xf bank_mask:0xf
	v_cndmask_b32_e32 v8, v10, v8, vcc
	v_cndmask_b32_e32 v9, v11, v9, vcc
	v_add_f32_dpp v14, v12, v12 quad_perm:[2,3,0,1] row_mask:0xf bank_mask:0xf
	v_add_f32_dpp v15, v13, v13 quad_perm:[2,3,0,1] row_mask:0xf bank_mask:0xf
	v_cndmask_b32_e64 v12, v15, v14, s[4:5]
	s_waitcnt vmcnt(0)
	v_pk_mul_f32 v[140:141], v[236:237], v[0:1] op_sel_hi:[1,0]
	v_pk_mul_f32 v[142:143], v[244:245], v[0:1] op_sel_hi:[1,0]
	v_pk_fma_f32 v[140:141], v[238:239], v[0:1], v[140:141] op_sel:[0,1,0]
	v_pk_fma_f32 v[142:143], v[246:247], v[0:1], v[142:143] op_sel:[0,1,0]
	v_pk_fma_f32 v[140:141], v[240:241], v[2:3], v[140:141] op_sel_hi:[1,0,1]
	v_pk_fma_f32 v[142:143], v[248:249], v[2:3], v[142:143] op_sel_hi:[1,0,1]
	v_pk_fma_f32 v[140:141], v[242:243], v[2:3], v[140:141] op_sel:[0,1,0]
	v_pk_fma_f32 v[142:143], v[250:251], v[2:3], v[142:143] op_sel:[0,1,0]
	v_add_f32_dpp v28, v30, v29 row_ror:8 row_mask:0xf bank_mask:0xf
	v_add_f32_dpp v4, v252, v252 quad_perm:[1,0,3,2] row_mask:0xf bank_mask:0xf
	v_add_f32_dpp v5, v253, v253 quad_perm:[1,0,3,2] row_mask:0xf bank_mask:0xf
	v_add_f32_dpp v6, v254, v254 quad_perm:[1,0,3,2] row_mask:0xf bank_mask:0xf
	v_add_f32_dpp v7, v255, v255 quad_perm:[1,0,3,2] row_mask:0xf bank_mask:0xf
	v_cndmask_b32_e32 v4, v6, v4, vcc
	v_cndmask_b32_e32 v5, v7, v5, vcc
	v_add_f32_dpp v10, v8, v8 quad_perm:[2,3,0,1] row_mask:0xf bank_mask:0xf
	v_add_f32_dpp v11, v9, v9 quad_perm:[2,3,0,1] row_mask:0xf bank_mask:0xf
	v_cndmask_b32_e64 v8, v11, v10, s[4:5]
	v_cndmask_b32_e64 v13, v8, v12, s[6:7]
	v_cndmask_b32_e64 v14, v12, v8, s[6:7]
	s_nop 1
	v_add_f32_dpp v12, v14, v13 row_ror:4 row_mask:0xf bank_mask:0xf
	v_add_f32_dpp v0, v140, v140 quad_perm:[1,0,3,2] row_mask:0xf bank_mask:0xf
	v_add_f32_dpp v1, v141, v141 quad_perm:[1,0,3,2] row_mask:0xf bank_mask:0xf
	v_add_f32_dpp v2, v142, v142 quad_perm:[1,0,3,2] row_mask:0xf bank_mask:0xf
	v_add_f32_dpp v3, v143, v143 quad_perm:[1,0,3,2] row_mask:0xf bank_mask:0xf
	v_cndmask_b32_e32 v0, v2, v0, vcc
	v_cndmask_b32_e32 v1, v3, v1, vcc
	v_add_f32_dpp v6, v4, v4 quad_perm:[2,3,0,1] row_mask:0xf bank_mask:0xf
	v_add_f32_dpp v7, v5, v5 quad_perm:[2,3,0,1] row_mask:0xf bank_mask:0xf
	v_cndmask_b32_e64 v4, v7, v6, s[4:5]
	v_add_f32_dpp v2, v0, v0 quad_perm:[2,3,0,1] row_mask:0xf bank_mask:0xf
	v_add_f32_dpp v3, v1, v1 quad_perm:[2,3,0,1] row_mask:0xf bank_mask:0xf
	v_cndmask_b32_e64 v0, v3, v2, s[4:5]
	v_cndmask_b32_e64 v5, v0, v4, s[6:7]
	v_cndmask_b32_e64 v6, v4, v0, s[6:7]
	s_nop 1
	v_add_f32_dpp v4, v6, v5 row_ror:4 row_mask:0xf bank_mask:0xf
	v_cndmask_b32_e64 v13, v4, v12, s[64:65]
	v_cndmask_b32_e64 v14, v12, v4, s[64:65]
	s_nop 1
	v_add_f32_dpp v12, v14, v13 row_ror:8 row_mask:0xf bank_mask:0xf
	s_nop 1
	v_permlane16_swap_b32_e32 v28, v12
	v_add_f32_e32 v28, v28, v12
	s_nop 1
	v_permlane32_swap_b32_e32 v60, v28
	v_add_f32_e32 v60, v60, v28
	ds_write_b32 v235, v60 offset:64
	v_lshlrev_b32_e32 v2, 2, v223
	s_add_u32 s4, s14, s28
	s_addc_u32 s5, s15, s29
	v_lshlrev_b32_e32 v0, 2, v2
	s_waitcnt lgkmcnt(0)
; DI void lbar() { asm volatile("s_waitcnt lgkmcnt(0)" ::: "memory"); __builtin_amdgcn_s_barrier(); asm volatile("" ::: "memory"); }
; DI float wave_sum(float v) { for (int o = 32; o >= 1; o >>= 1) v += __shfl_xor(v, o); return v; }
; DI void attn_sample_item(const Params& p, int item, ldsp lds, int tid_) {
;     ...
;   for (int j = 0; j < 16; ++j) vvA[j] = __builtin_nontemporal_load((const f32x4*)(cv + (size_t)(wid * 32 + j) * 1024 + lane * 4));
;   lbar();
;   if (wid < 4) {
;     float v[4]; float mx = -1e30f;
; #pragma unroll
;     for (int j = 0; j < 4; ++j) { v[j] = SC[wid * 256 + j * 64 + lane]; mx = fmaxf(mx, v[j]); }
;     for (int o = 32; o >= 1; o >>= 1) mx = fmaxf(mx, __shfl_xor(mx, o));
;     float s = 0.f;
; #pragma unroll
;     for (int j = 0; j < 4; ++j) { v[j] = __expf(v[j] - mx); s += v[j]; }
;     s = wave_sum(s); const float inv = 1.f / s;
; #pragma unroll
;     for (int j = 0; j < 4; ++j) SC[wid * 256 + j * 64 + lane] = v[j] * inv;
;   }
	v_mov_b32_e32 v1, v145
	v_lshl_add_u64 v[0:1], s[4:5], 0, v[0:1]
	v_lshl_add_u64 v[4:5], v[0:1], 0, v[158:159]
	v_lshl_add_u64 v[6:7], v[0:1], 0, v[162:163]
	global_load_dwordx4 v[100:103], v[4:5], off nt
	global_load_dwordx4 v[92:95], v[6:7], off nt
	v_lshl_add_u64 v[4:5], v[0:1], 0, v[164:165]
	v_lshl_add_u64 v[6:7], v[0:1], 0, v[168:169]
	global_load_dwordx4 v[112:115], v[4:5], off nt
	global_load_dwordx4 v[108:111], v[6:7], off nt
	v_lshl_add_u64 v[4:5], v[0:1], 0, v[172:173]
	v_lshl_add_u64 v[6:7], v[0:1], 0, v[176:177]
	global_load_dwordx4 v[120:123], v[4:5], off nt
	global_load_dwordx4 v[116:119], v[6:7], off nt
	v_lshl_add_u64 v[4:5], v[0:1], 0, v[180:181]
	v_lshl_add_u64 v[6:7], v[0:1], 0, v[184:185]
	global_load_dwordx4 v[124:127], v[4:5], off nt
	global_load_dwordx4 v[104:107], v[6:7], off nt
	v_lshl_add_u64 v[4:5], v[0:1], 0, v[188:189]
	v_lshl_add_u64 v[6:7], v[0:1], 0, v[192:193]
	global_load_dwordx4 v[68:71], v[4:5], off nt
	global_load_dwordx4 v[64:67], v[6:7], off nt
	v_lshl_add_u64 v[4:5], v[0:1], 0, v[196:197]
	v_lshl_add_u64 v[6:7], v[0:1], 0, v[200:201]
	global_load_dwordx4 v[80:83], v[4:5], off nt
	global_load_dwordx4 v[76:79], v[6:7], off nt
	v_lshl_add_u64 v[4:5], v[0:1], 0, v[202:203]
	v_lshl_add_u64 v[6:7], v[0:1], 0, v[204:205]
	global_load_dwordx4 v[88:91], v[4:5], off nt
	global_load_dwordx4 v[84:87], v[6:7], off nt
	v_lshl_add_u64 v[4:5], v[0:1], 0, v[206:207]
	v_lshl_add_u64 v[6:7], v[0:1], 0, v[208:209]
	global_load_dwordx4 v[96:99], v[4:5], off nt
	global_load_dwordx4 v[72:75], v[6:7], off nt
	s_waitcnt lgkmcnt(0)
	s_barrier
	v_cmp_gt_i32_e32 vcc, 4, v210
	s_and_saveexec_b64 s[4:5], vcc
	s_cbranch_execz .LBB0_1675
	v_lshlrev_b32_e32 v3, 10, v210
	v_add3_u32 v6, 16, v3, v2
	ds_read2st64_b32 v[2:3], v6 offset1:1
	ds_read2st64_b32 v[4:5], v6 offset0:2 offset1:3
	s_waitcnt lgkmcnt(1)
	v_max3_f32 v7, v2, s35, v3
	s_waitcnt lgkmcnt(0)
	v_max3_f32 v7, v7, v4, v5
	ds_bpermute_b32 v8, v133, v7
	s_waitcnt lgkmcnt(0)
	v_max_f32_e32 v8, v8, v8
	v_max_f32_e32 v7, v7, v8
	ds_bpermute_b32 v8, v132, v7
	s_waitcnt lgkmcnt(0)
	v_max_f32_e32 v8, v8, v8
	v_max_f32_e32 v7, v7, v8
	ds_bpermute_b32 v8, v131, v7
	s_waitcnt lgkmcnt(0)
	v_max_f32_e32 v8, v8, v8
	v_max_f32_e32 v7, v7, v8
	ds_bpermute_b32 v8, v130, v7
	s_waitcnt lgkmcnt(0)
	v_max_f32_e32 v8, v8, v8
	v_max_f32_e32 v7, v7, v8
	ds_bpermute_b32 v8, v129, v7
	s_waitcnt lgkmcnt(0)
	v_max_f32_e32 v8, v8, v8
	v_max_f32_e32 v7, v7, v8
	ds_bpermute_b32 v8, v128, v7
	s_waitcnt lgkmcnt(0)
	v_max_f32_e32 v8, v8, v8
	v_max_f32_e32 v7, v7, v8
	v_sub_f32_e32 v2, v2, v7
	v_sub_f32_e32 v3, v3, v7
	v_mul_f32_e32 v2, 0x3fb8aa3b, v2
	v_sub_f32_e32 v4, v4, v7
	v_mul_f32_e32 v3, 0x3fb8aa3b, v3
	v_exp_f32_e32 v2, v2
	v_sub_f32_e32 v5, v5, v7
	v_mul_f32_e32 v4, 0x3fb8aa3b, v4
	v_exp_f32_e32 v3, v3
	v_mul_f32_e32 v5, 0x3fb8aa3b, v5
	v_exp_f32_e32 v4, v4
	v_exp_f32_e32 v5, v5
	v_add_f32_e32 v7, 0, v2
	v_add_f32_e32 v7, v3, v7
	v_add_f32_e32 v7, v4, v7
	v_add_f32_e32 v7, v5, v7
	ds_bpermute_b32 v8, v133, v7
	s_waitcnt lgkmcnt(0)
	v_add_f32_e32 v7, v7, v8
	ds_bpermute_b32 v8, v132, v7
	s_waitcnt lgkmcnt(0)
	v_add_f32_e32 v7, v7, v8
	ds_bpermute_b32 v8, v131, v7
	s_waitcnt lgkmcnt(0)
	v_add_f32_e32 v7, v7, v8
	ds_bpermute_b32 v8, v130, v7
	s_waitcnt lgkmcnt(0)
	v_add_f32_e32 v7, v7, v8
	ds_bpermute_b32 v8, v129, v7
	s_waitcnt lgkmcnt(0)
	v_add_f32_e32 v7, v7, v8
	ds_bpermute_b32 v8, v128, v7
	s_waitcnt lgkmcnt(0)
	v_add_f32_e32 v7, v7, v8
	v_div_scale_f32 v8, s[6:7], v7, v7, 1.0
	v_rcp_f32_e32 v9, v8
	v_div_scale_f32 v10, vcc, 1.0, v7, 1.0
	v_fma_f32 v11, -v8, v9, 1.0
	v_fmac_f32_e32 v9, v11, v9
	v_mul_f32_e32 v11, v10, v9
	v_fma_f32 v12, -v8, v11, v10
	v_fmac_f32_e32 v11, v12, v9
	v_fma_f32 v8, -v8, v11, v10
	v_div_fmas_f32 v8, v8, v9, v11
	v_div_fixup_f32 v7, v8, v7, 1.0
	v_mul_f32_e32 v2, v2, v7
	v_mul_f32_e32 v3, v3, v7
	v_mul_f32_e32 v4, v4, v7
	v_mul_f32_e32 v5, v5, v7
	ds_write2st64_b32 v6, v2, v3 offset1:1
	ds_write2st64_b32 v6, v4, v5 offset0:2 offset1:3
	s_branch .LBB0_1675
